# complete 4/4 LDS-DMA split in every load segment of the 8 K-loops (last pair of the second 6-load segment issued at the next iteration head / loop exit) on top of v075
# speedup vs baseline: 1.0042x; 1.0042x over previous
; #define PG8_LAS __attribute__((address_space(3)))
;     __device__ __forceinline__ bool next(int i, Unit& u) const { if (!StaticOrder::next(i, u)) return false; u.pm = 0; u.pn = 0; u.a = A; u.b = Bt; return true; }
; #define PG8_STAGE(bufoff, gbase, voff) do { _Pragma("unroll") for (int _i = 0; _i < 2; ++_i) \
;         __builtin_amdgcn_global_load_lds((const unsigned*)((const char*)(gbase) + (voff)[_i]), (PG8_LAS unsigned*)(lds + (bufoff) + ldsw + _i * 8192), 16, 0, 0); } while (0)
; #define PG8_LDA(dst, b, h) do { _Pragma("unroll") for (int m = 0; m < 4; ++m) _Pragma("unroll") for (int k = 0; k < 2; ++k) dst[m][k] = *(const PG8_LAS bf16x8*)(lds + PG8_SA(b, h) + aoff + m * 2048 + k * 1024); } while (0)
; template <class Epi, class Sched, bool ALIGN_EPI = false, bool SP2 = false>
; __device__ __forceinline__ void gemm_phase(PG8_LAS unsigned char* lds, const Gemm g, const Sched& S, const Epi& E, int tid_in) {
;     ...
;     for (;;) {
;         const bool has_next = S.next(ui + 1, nxt);
;         const char* nA = has_next ? nxt.a : cA; const char* nB = has_next ? nxt.b : cB;
;         const int nt = cur.nk;
;         if constexpr (rowsc_of<Epi>::v) __builtin_amdgcn_global_load_lds((const unsigned*)(E.SSQ + cur.pm * BM + lane * 4), (PG8_LAS unsigned*)(lds + RS_LDS_OFF + wid * 1024), 16, 0, 0);
;         for (int t = 0; t < nt; t += 2) {
;             const bool last = (t == nt - 2);
;             const char* a1 = cA + (size_t)(t + 1) * kstep;
;             const char* a2 = last ? nA : cA + (size_t)(t + 2) * kstep; const char* b2 = last ? nB : cB + (size_t)(t + 2) * kstep;
;             const char* a3 = a2 + kstep; const char* b3 = b2 + kstep;
;             if (last && has_next) S.a_ready(nxt);
;             if constexpr (SP2) {
;             PG8_LDB(B0, 0, 0); PG8_LDB(B1, 0, 1); PG8_SCHED; PG8_LDA(At, 0, 0); PG8_STAGE(PG8_SA(1, 1), a1 + hstepA, voffA);
;             PG8_WAIT_V(8); PG8_WAIT_L(0); PG8_BAR; PG8_MMA(0, 0, At, B0); PG8_MMA(0, 1, At, B1); PG8_BAR; PG8_SCHED;
;     ...
;         if (!(nxt.tag & 0x100)) {
; #pragma unroll
;         for (int a = 0; a < 2; ++a)
; #pragma unroll
;             for (int b = 0; b < 2; ++b)
; #pragma unroll
;                 for (int m = 0; m < 4; ++m)
; #pragma unroll
;                     for (int n = 0; n < 2; ++n) acc[a][b][m][n] = (f32x4){0.f, 0.f, 0.f, 0.f};
;         }
;         cur = nxt; cA = nA; cB = nB; ++ui;
.LBB0_281:
	s_lshl_b32 s22, s28, 8
	s_ashr_i32 s23, s22, 31
	s_mov_b32 m0, s41
	v_lshl_add_u64 v[2:3], s[22:23], 2, v[136:137]
	global_load_lds_dwordx4 v[2:3], off
	s_add_u32 s24, s24, 0x80080
	s_addc_u32 s25, s25, 0
	s_add_u32 s15, s26, 0x100
	v_mov_b32_e32 v2, 0
	s_addc_u32 s17, s27, 0
	s_mov_b32 s23, -2
	v_mov_b32_e32 v3, v2
	v_mov_b32_e32 v4, v2
	v_mov_b32_e32 v5, v2
	v_mov_b32_e32 v10, v2
	v_mov_b32_e32 v11, v2
	v_mov_b32_e32 v12, v2
	v_mov_b32_e32 v13, v2
	v_mov_b32_e32 v18, v2
	v_mov_b32_e32 v19, v2
	v_mov_b32_e32 v20, v2
	v_mov_b32_e32 v21, v2
	v_mov_b32_e32 v26, v2
	v_mov_b32_e32 v27, v2
	v_mov_b32_e32 v28, v2
	v_mov_b32_e32 v29, v2
	v_mov_b32_e32 v34, v2
	v_mov_b32_e32 v35, v2
	v_mov_b32_e32 v36, v2
	v_mov_b32_e32 v37, v2
	v_mov_b32_e32 v42, v2
	v_mov_b32_e32 v43, v2
	v_mov_b32_e32 v44, v2
	v_mov_b32_e32 v45, v2
	v_mov_b32_e32 v50, v2
	v_mov_b32_e32 v51, v2
	v_mov_b32_e32 v52, v2
	v_mov_b32_e32 v53, v2
	v_mov_b32_e32 v58, v2
	v_mov_b32_e32 v59, v2
	v_mov_b32_e32 v60, v2
	v_mov_b32_e32 v61, v2
	v_mov_b32_e32 v6, v2
	v_mov_b32_e32 v7, v2
	v_mov_b32_e32 v8, v2
	v_mov_b32_e32 v9, v2
	v_mov_b32_e32 v14, v2
	v_mov_b32_e32 v15, v2
	v_mov_b32_e32 v16, v2
	v_mov_b32_e32 v17, v2
	v_mov_b32_e32 v22, v2
	v_mov_b32_e32 v23, v2
	v_mov_b32_e32 v24, v2
	v_mov_b32_e32 v25, v2
	v_mov_b32_e32 v30, v2
	v_mov_b32_e32 v31, v2
	v_mov_b32_e32 v32, v2
	v_mov_b32_e32 v33, v2
	v_mov_b32_e32 v38, v2
	v_mov_b32_e32 v39, v2
	v_mov_b32_e32 v40, v2
	v_mov_b32_e32 v41, v2
	v_mov_b32_e32 v46, v2
	v_mov_b32_e32 v47, v2
	v_mov_b32_e32 v48, v2
	v_mov_b32_e32 v49, v2
	v_mov_b32_e32 v54, v2
	v_mov_b32_e32 v55, v2
	v_mov_b32_e32 v56, v2
	v_mov_b32_e32 v57, v2
	v_mov_b32_e32 v62, v2
	v_mov_b32_e32 v63, v2
	v_mov_b32_e32 v64, v2
	v_mov_b32_e32 v65, v2
	v_mov_b32_e32 v66, v2
	v_mov_b32_e32 v67, v2
	v_mov_b32_e32 v68, v2
	v_mov_b32_e32 v69, v2
	v_mov_b32_e32 v74, v2
	v_mov_b32_e32 v75, v2
	v_mov_b32_e32 v76, v2
	v_mov_b32_e32 v77, v2
	v_mov_b32_e32 v82, v2
	v_mov_b32_e32 v83, v2
	v_mov_b32_e32 v84, v2
	v_mov_b32_e32 v85, v2
	v_mov_b32_e32 v90, v2
	v_mov_b32_e32 v91, v2
	v_mov_b32_e32 v92, v2
	v_mov_b32_e32 v93, v2
	v_mov_b32_e32 v98, v2
	v_mov_b32_e32 v99, v2
	v_mov_b32_e32 v100, v2
	v_mov_b32_e32 v101, v2
	v_mov_b32_e32 v106, v2
	v_mov_b32_e32 v107, v2
	v_mov_b32_e32 v108, v2
	v_mov_b32_e32 v109, v2
	v_mov_b32_e32 v114, v2
	v_mov_b32_e32 v115, v2
	v_mov_b32_e32 v116, v2
	v_mov_b32_e32 v117, v2
	v_mov_b32_e32 v122, v2
	v_mov_b32_e32 v123, v2
	v_mov_b32_e32 v124, v2
	v_mov_b32_e32 v125, v2
	v_mov_b32_e32 v70, v2
	v_mov_b32_e32 v71, v2
	v_mov_b32_e32 v72, v2
	v_mov_b32_e32 v73, v2
	v_mov_b32_e32 v78, v2
	v_mov_b32_e32 v79, v2
	v_mov_b32_e32 v80, v2
	v_mov_b32_e32 v81, v2
	v_mov_b32_e32 v86, v2
	v_mov_b32_e32 v87, v2
	v_mov_b32_e32 v88, v2
	v_mov_b32_e32 v89, v2
	v_mov_b32_e32 v94, v2
	v_mov_b32_e32 v95, v2
	v_mov_b32_e32 v96, v2
	v_mov_b32_e32 v97, v2
	v_mov_b32_e32 v102, v2
	v_mov_b32_e32 v103, v2
	v_mov_b32_e32 v104, v2
	v_mov_b32_e32 v105, v2
	v_mov_b32_e32 v110, v2
	v_mov_b32_e32 v111, v2
	v_mov_b32_e32 v112, v2
	v_mov_b32_e32 v113, v2
	v_mov_b32_e32 v118, v2
	v_mov_b32_e32 v119, v2
	v_mov_b32_e32 v120, v2
	v_mov_b32_e32 v121, v2
	v_mov_b32_e32 v126, v2
	v_mov_b32_e32 v127, v2
	v_mov_b32_e32 v128, v2
	v_mov_b32_e32 v129, v2
	s_branch .LBB0_282
.Lbal_top_282:
	s_mov_b32 m0, s39
	s_nop 0
	global_load_lds_dwordx4 v[226:227], off
	s_mov_b32 m0, s40
	s_nop 0
	global_load_lds_dwordx4 v[228:229], off
.LBB0_282:
	s_add_u32 s26, s24, 0xfff80080
	s_addc_u32 s27, s25, -1
	s_add_i32 s45, 0, 0x10000
	s_cmp_eq_u32 s23, 28
	s_cselect_b32 s29, s19, s27
	s_cselect_b32 s28, s18, s26
	s_cselect_b32 s27, s21, s17
	s_cselect_b32 s26, s20, s15
	s_add_i32 s48, 0, 0x14000
	v_add_u32_e32 v158, s45, v152
	v_add_u32_e32 v186, s48, v152
	ds_read_b128 v[142:145], v158
	ds_read_b128 v[146:149], v158 offset:1024
	ds_read_b128 v[154:157], v158 offset:2048
	ds_read_b128 v[158:161], v158 offset:3072
	ds_read_b128 v[162:165], v186
	ds_read_b128 v[166:169], v186 offset:1024
	ds_read_b128 v[182:185], v186 offset:2048
	ds_read_b128 v[186:189], v186 offset:3072
	v_lshl_add_u64 v[222:223], s[24:25], 0, v[138:139]
	s_add_i32 m0, s33, 0xc000
	ds_read_b128 v[190:193], v153
	ds_read_b128 v[194:197], v153 offset:1024
	ds_read_b128 v[198:201], v153 offset:2048
	ds_read_b128 v[202:205], v153 offset:3072
	ds_read_b128 v[206:209], v153 offset:4096
	ds_read_b128 v[210:213], v153 offset:5120
	ds_read_b128 v[214:217], v153 offset:6144
	ds_read_b128 v[218:221], v153 offset:7168
	global_load_lds_dwordx4 v[222:223], off
	v_lshl_add_u64 v[222:223], s[24:25], 0, v[140:141]
	s_add_i32 m0, s33, 0xe000
	s_nop 0
	global_load_lds_dwordx4 v[222:223], off
	s_waitcnt vmcnt(8)
	s_waitcnt lgkmcnt(0)
	s_barrier
; #define PG8_STAGE(bufoff, gbase, voff) do { _Pragma("unroll") for (int _i = 0; _i < 2; ++_i) \
;         __builtin_amdgcn_global_load_lds((const unsigned*)((const char*)(gbase) + (voff)[_i]), (PG8_LAS unsigned*)(lds + (bufoff) + ldsw + _i * 8192), 16, 0, 0); } while (0)
; #define PG8_LDA(dst, b, h) do { _Pragma("unroll") for (int m = 0; m < 4; ++m) _Pragma("unroll") for (int k = 0; k < 2; ++k) dst[m][k] = *(const PG8_LAS bf16x8*)(lds + PG8_SA(b, h) + aoff + m * 2048 + k * 1024); } while (0)
; #define PG8_MMA(ai, bj, At, Bt) do { __builtin_amdgcn_s_setprio(1); _Pragma("unroll") for (int m = 0; m < 4; ++m) _Pragma("unroll") for (int n = 0; n < 2; ++n) _Pragma("unroll") for (int k = 0; k < 2; ++k) \
;         acc[ai][bj][m][n] = __builtin_amdgcn_mfma_f32_16x16x32_bf16(Bt[n][k], At[m][k], acc[ai][bj][m][n], 0, 0, 0); __builtin_amdgcn_s_setprio(0); } while (0)
; #define PG8_WAIT_V(n) asm volatile("s_waitcnt vmcnt(" #n ")" ::: "memory")
; #define PG8_WAIT_L(n) asm volatile("s_waitcnt lgkmcnt(" #n ")" ::: "memory")
; #define PG8_BAR __builtin_amdgcn_s_barrier()
; #define PG8_SCHED __builtin_amdgcn_sched_barrier(0)
; template <class Epi, class Sched, bool ALIGN_EPI = false, bool SP2 = false>
; __device__ __forceinline__ void gemm_phase(PG8_LAS unsigned char* lds, const Gemm g, const Sched& S, const Epi& E, int tid_in) {
;     ...
;             PG8_WAIT_V(8); PG8_WAIT_L(0); PG8_BAR; PG8_MMA(0, 0, At, B0); PG8_MMA(0, 1, At, B1); PG8_BAR; PG8_SCHED;
;             PG8_LDA(At, 0, 1); PG8_STAGE(PG8_SB(0, 0), b2, voffB); PG8_STAGE(PG8_SB(0, 1), b2 + hstep, voffB); PG8_STAGE(PG8_SA(0, 0), a2, voffA);
;             PG8_WAIT_V(8); PG8_WAIT_L(0); PG8_BAR; PG8_MMA(1, 0, At, B0); PG8_MMA(1, 1, At, B1); PG8_BAR; PG8_SCHED;
	s_setprio 1
	s_waitcnt lgkmcnt(0)
	v_mfma_f32_16x16x32_bf16 v[126:129], v[142:145], v[190:193], v[126:129]
	v_mfma_f32_16x16x32_bf16 v[118:121], v[154:157], v[190:193], v[118:121]
	v_mfma_f32_16x16x32_bf16 v[110:113], v[142:145], v[198:201], v[110:113]
	v_mfma_f32_16x16x32_bf16 v[102:105], v[154:157], v[198:201], v[102:105]
	v_mfma_f32_16x16x32_bf16 v[94:97], v[142:145], v[206:209], v[94:97]
	v_mfma_f32_16x16x32_bf16 v[86:89], v[154:157], v[206:209], v[86:89]
	v_mfma_f32_16x16x32_bf16 v[78:81], v[142:145], v[214:217], v[78:81]
	v_mfma_f32_16x16x32_bf16 v[70:73], v[154:157], v[214:217], v[70:73]
	v_mfma_f32_16x16x32_bf16 v[126:129], v[146:149], v[194:197], v[126:129]
	v_mfma_f32_16x16x32_bf16 v[118:121], v[158:161], v[194:197], v[118:121]
	v_mfma_f32_16x16x32_bf16 v[110:113], v[146:149], v[202:205], v[110:113]
	v_mfma_f32_16x16x32_bf16 v[102:105], v[158:161], v[202:205], v[102:105]
	v_mfma_f32_16x16x32_bf16 v[94:97], v[146:149], v[210:213], v[94:97]
	v_mfma_f32_16x16x32_bf16 v[86:89], v[158:161], v[210:213], v[86:89]
	v_mfma_f32_16x16x32_bf16 v[78:81], v[146:149], v[218:221], v[78:81]
	v_mfma_f32_16x16x32_bf16 v[70:73], v[158:161], v[218:221], v[70:73]
	s_setprio 0
	s_setprio 1
	v_mfma_f32_16x16x32_bf16 v[122:125], v[162:165], v[190:193], v[122:125]
	v_mfma_f32_16x16x32_bf16 v[114:117], v[182:185], v[190:193], v[114:117]
	v_mfma_f32_16x16x32_bf16 v[106:109], v[162:165], v[198:201], v[106:109]
	v_mfma_f32_16x16x32_bf16 v[98:101], v[182:185], v[198:201], v[98:101]
	v_mfma_f32_16x16x32_bf16 v[90:93], v[162:165], v[206:209], v[90:93]
	v_mfma_f32_16x16x32_bf16 v[82:85], v[182:185], v[206:209], v[82:85]
	v_mfma_f32_16x16x32_bf16 v[74:77], v[162:165], v[214:217], v[74:77]
	v_mfma_f32_16x16x32_bf16 v[66:69], v[182:185], v[214:217], v[66:69]
	v_mfma_f32_16x16x32_bf16 v[122:125], v[166:169], v[194:197], v[122:125]
	v_mfma_f32_16x16x32_bf16 v[114:117], v[186:189], v[194:197], v[114:117]
	v_mfma_f32_16x16x32_bf16 v[106:109], v[166:169], v[202:205], v[106:109]
	v_mfma_f32_16x16x32_bf16 v[98:101], v[186:189], v[202:205], v[98:101]
	v_mfma_f32_16x16x32_bf16 v[90:93], v[166:169], v[210:213], v[90:93]
	v_mfma_f32_16x16x32_bf16 v[82:85], v[186:189], v[210:213], v[82:85]
	v_mfma_f32_16x16x32_bf16 v[74:77], v[166:169], v[218:221], v[74:77]
	v_mfma_f32_16x16x32_bf16 v[66:69], v[186:189], v[218:221], v[66:69]
	s_setprio 0
	s_barrier
	s_add_i32 s45, s45, s31
	v_lshl_add_u64 v[222:223], s[26:27], 0, v[0:1]
	s_mov_b32 m0, s45
	ds_read_b128 v[190:193], v153 offset:16384
	ds_read_b128 v[194:197], v153 offset:17408
	ds_read_b128 v[198:201], v153 offset:18432
	ds_read_b128 v[202:205], v153 offset:19456
	ds_read_b128 v[206:209], v153 offset:20480
	ds_read_b128 v[210:213], v153 offset:21504
	ds_read_b128 v[214:217], v153 offset:22528
	ds_read_b128 v[218:221], v153 offset:23552
	global_load_lds_dwordx4 v[222:223], off
	s_add_i32 m0, s45, 0x2000
	s_add_u32 s46, s26, 0x80000
	v_lshl_add_u64 v[224:225], s[26:27], 0, v[130:131]
	s_addc_u32 s47, s27, 0
	s_add_i32 s45, s48, s31
	global_load_lds_dwordx4 v[224:225], off
	v_lshl_add_u64 v[226:227], s[46:47], 0, v[0:1]
	s_mov_b32 m0, s45
	v_lshl_add_u64 v[228:229], s[28:29], 0, v[132:133]
	global_load_lds_dwordx4 v[226:227], off
	v_lshl_add_u64 v[226:227], s[46:47], 0, v[130:131]
	s_add_i32 m0, s45, 0x2000
	s_nop 0
	global_load_lds_dwordx4 v[226:227], off
	s_waitcnt vmcnt(6)
	s_waitcnt lgkmcnt(0)
	s_barrier
	s_setprio 1
	s_waitcnt lgkmcnt(0)
	v_mfma_f32_16x16x32_bf16 v[62:65], v[142:145], v[190:193], v[62:65]
	v_mfma_f32_16x16x32_bf16 v[54:57], v[154:157], v[190:193], v[54:57]
	v_mfma_f32_16x16x32_bf16 v[46:49], v[142:145], v[198:201], v[46:49]
	v_mfma_f32_16x16x32_bf16 v[38:41], v[154:157], v[198:201], v[38:41]
	v_mfma_f32_16x16x32_bf16 v[30:33], v[142:145], v[206:209], v[30:33]
	v_mfma_f32_16x16x32_bf16 v[22:25], v[154:157], v[206:209], v[22:25]
	v_mfma_f32_16x16x32_bf16 v[14:17], v[142:145], v[214:217], v[14:17]
	v_mfma_f32_16x16x32_bf16 v[6:9], v[154:157], v[214:217], v[6:9]
	v_mfma_f32_16x16x32_bf16 v[62:65], v[146:149], v[194:197], v[62:65]
	v_mfma_f32_16x16x32_bf16 v[54:57], v[158:161], v[194:197], v[54:57]
	v_mfma_f32_16x16x32_bf16 v[46:49], v[146:149], v[202:205], v[46:49]
	v_mfma_f32_16x16x32_bf16 v[38:41], v[158:161], v[202:205], v[38:41]
	v_mfma_f32_16x16x32_bf16 v[30:33], v[146:149], v[210:213], v[30:33]
	v_mfma_f32_16x16x32_bf16 v[22:25], v[158:161], v[210:213], v[22:25]
	v_mfma_f32_16x16x32_bf16 v[14:17], v[146:149], v[218:221], v[14:17]
	v_mfma_f32_16x16x32_bf16 v[6:9], v[158:161], v[218:221], v[6:9]
	s_setprio 0
	s_setprio 1
	v_mfma_f32_16x16x32_bf16 v[58:61], v[162:165], v[190:193], v[58:61]
	v_mfma_f32_16x16x32_bf16 v[50:53], v[182:185], v[190:193], v[50:53]
	v_mfma_f32_16x16x32_bf16 v[42:45], v[162:165], v[198:201], v[42:45]
	v_mfma_f32_16x16x32_bf16 v[34:37], v[182:185], v[198:201], v[34:37]
	v_mfma_f32_16x16x32_bf16 v[26:29], v[162:165], v[206:209], v[26:29]
	v_mfma_f32_16x16x32_bf16 v[18:21], v[182:185], v[206:209], v[18:21]
	v_mfma_f32_16x16x32_bf16 v[10:13], v[162:165], v[214:217], v[10:13]
	v_mfma_f32_16x16x32_bf16 v[2:5], v[182:185], v[214:217], v[2:5]
	v_mfma_f32_16x16x32_bf16 v[58:61], v[166:169], v[194:197], v[58:61]
	v_mfma_f32_16x16x32_bf16 v[50:53], v[186:189], v[194:197], v[50:53]
	v_mfma_f32_16x16x32_bf16 v[42:45], v[166:169], v[202:205], v[42:45]
	v_mfma_f32_16x16x32_bf16 v[34:37], v[186:189], v[202:205], v[34:37]
	v_mfma_f32_16x16x32_bf16 v[26:29], v[166:169], v[210:213], v[26:29]
	v_mfma_f32_16x16x32_bf16 v[18:21], v[186:189], v[210:213], v[18:21]
	v_mfma_f32_16x16x32_bf16 v[10:13], v[166:169], v[218:221], v[10:13]
	v_mfma_f32_16x16x32_bf16 v[2:5], v[186:189], v[218:221], v[2:5]
	s_setprio 0
	s_barrier
; #define PG8_STAGE(bufoff, gbase, voff) do { _Pragma("unroll") for (int _i = 0; _i < 2; ++_i) \
;         __builtin_amdgcn_global_load_lds((const unsigned*)((const char*)(gbase) + (voff)[_i]), (PG8_LAS unsigned*)(lds + (bufoff) + ldsw + _i * 8192), 16, 0, 0); } while (0)
; #define PG8_LDA(dst, b, h) do { _Pragma("unroll") for (int m = 0; m < 4; ++m) _Pragma("unroll") for (int k = 0; k < 2; ++k) dst[m][k] = *(const PG8_LAS bf16x8*)(lds + PG8_SA(b, h) + aoff + m * 2048 + k * 1024); } while (0)
; #define PG8_LDB(dst, b, h) do { _Pragma("unroll") for (int n = 0; n < 2; ++n) _Pragma("unroll") for (int k = 0; k < 2; ++k) dst[n][k] = *(const PG8_LAS bf16x8*)(lds + PG8_SB(b, h) + boff + n * 2048 + k * 1024); } while (0)
; #define PG8_MMA(ai, bj, At, Bt) do { __builtin_amdgcn_s_setprio(1); _Pragma("unroll") for (int m = 0; m < 4; ++m) _Pragma("unroll") for (int n = 0; n < 2; ++n) _Pragma("unroll") for (int k = 0; k < 2; ++k) \
;         acc[ai][bj][m][n] = __builtin_amdgcn_mfma_f32_16x16x32_bf16(Bt[n][k], At[m][k], acc[ai][bj][m][n], 0, 0, 0); __builtin_amdgcn_s_setprio(0); } while (0)
; #define PG8_WAIT_V(n) asm volatile("s_waitcnt vmcnt(" #n ")" ::: "memory")
; #define PG8_WAIT_L(n) asm volatile("s_waitcnt lgkmcnt(" #n ")" ::: "memory")
; #define PG8_BAR __builtin_amdgcn_s_barrier()
; #define PG8_SCHED __builtin_amdgcn_sched_barrier(0)
; template <class Epi, class Sched, bool ALIGN_EPI = false, bool SP2 = false>
; __device__ __forceinline__ void gemm_phase(PG8_LAS unsigned char* lds, const Gemm g, const Sched& S, const Epi& E, int tid_in) {
;     ...
;             PG8_LDB(B0, 1, 0); PG8_LDB(B1, 1, 1); PG8_SCHED; PG8_LDA(At, 1, 0); PG8_STAGE(PG8_SA(0, 1), a2 + hstepA, voffA);
;             PG8_WAIT_V(8); PG8_WAIT_L(0); PG8_BAR; PG8_MMA(0, 0, At, B0); PG8_MMA(0, 1, At, B1); PG8_BAR; PG8_SCHED;
	v_lshl_add_u64 v[226:227], s[28:29], 0, v[134:135]
	s_mov_b32 m0, s33
	s_nop 0
	global_load_lds_dwordx4 v[226:227], off
	s_mov_b32 m0, s34
	s_nop 0
	global_load_lds_dwordx4 v[228:229], off
	s_add_i32 s45, 0, 0x18000
	s_add_i32 s46, 0, 0x1c000
	v_add_u32_e32 v158, s45, v152
	v_add_u32_e32 v186, s46, v152
	ds_read_b128 v[142:145], v158
	ds_read_b128 v[146:149], v158 offset:1024
	ds_read_b128 v[154:157], v158 offset:2048
	ds_read_b128 v[158:161], v158 offset:3072
	ds_read_b128 v[162:165], v186
	ds_read_b128 v[166:169], v186 offset:1024
	ds_read_b128 v[182:185], v186 offset:2048
	ds_read_b128 v[186:189], v186 offset:3072
	s_add_u32 s28, s28, 0x80000
	s_addc_u32 s29, s29, 0
	s_mov_b32 m0, s35
	v_lshl_add_u64 v[240:241], s[28:29], 0, v[134:135]
	ds_read_b128 v[190:193], v153 offset:32768
	ds_read_b128 v[194:197], v153 offset:33792
	ds_read_b128 v[198:201], v153 offset:34816
	ds_read_b128 v[202:205], v153 offset:35840
	ds_read_b128 v[206:209], v153 offset:36864
	ds_read_b128 v[210:213], v153 offset:37888
	ds_read_b128 v[214:217], v153 offset:38912
	ds_read_b128 v[218:221], v153 offset:39936
	global_load_lds_dwordx4 v[240:241], off
	v_lshl_add_u64 v[240:241], s[28:29], 0, v[132:133]
	s_mov_b32 m0, s36
	s_nop 0
	global_load_lds_dwordx4 v[240:241], off
	s_waitcnt vmcnt(8)
	s_waitcnt lgkmcnt(0)
	s_barrier
	s_setprio 1
	s_waitcnt lgkmcnt(0)
	v_mfma_f32_16x16x32_bf16 v[126:129], v[142:145], v[190:193], v[126:129]
	v_mfma_f32_16x16x32_bf16 v[118:121], v[154:157], v[190:193], v[118:121]
	v_mfma_f32_16x16x32_bf16 v[110:113], v[142:145], v[198:201], v[110:113]
	v_mfma_f32_16x16x32_bf16 v[102:105], v[154:157], v[198:201], v[102:105]
	v_mfma_f32_16x16x32_bf16 v[94:97], v[142:145], v[206:209], v[94:97]
	v_mfma_f32_16x16x32_bf16 v[86:89], v[154:157], v[206:209], v[86:89]
	v_mfma_f32_16x16x32_bf16 v[78:81], v[142:145], v[214:217], v[78:81]
	v_mfma_f32_16x16x32_bf16 v[70:73], v[154:157], v[214:217], v[70:73]
	v_mfma_f32_16x16x32_bf16 v[126:129], v[146:149], v[194:197], v[126:129]
	v_mfma_f32_16x16x32_bf16 v[118:121], v[158:161], v[194:197], v[118:121]
	v_mfma_f32_16x16x32_bf16 v[110:113], v[146:149], v[202:205], v[110:113]
	v_mfma_f32_16x16x32_bf16 v[102:105], v[158:161], v[202:205], v[102:105]
	v_mfma_f32_16x16x32_bf16 v[94:97], v[146:149], v[210:213], v[94:97]
	v_mfma_f32_16x16x32_bf16 v[86:89], v[158:161], v[210:213], v[86:89]
	v_mfma_f32_16x16x32_bf16 v[78:81], v[146:149], v[218:221], v[78:81]
	v_mfma_f32_16x16x32_bf16 v[70:73], v[158:161], v[218:221], v[70:73]
	s_setprio 0
	s_setprio 1
	v_mfma_f32_16x16x32_bf16 v[122:125], v[162:165], v[190:193], v[122:125]
	v_mfma_f32_16x16x32_bf16 v[114:117], v[182:185], v[190:193], v[114:117]
	v_mfma_f32_16x16x32_bf16 v[106:109], v[162:165], v[198:201], v[106:109]
	v_mfma_f32_16x16x32_bf16 v[98:101], v[182:185], v[198:201], v[98:101]
	v_mfma_f32_16x16x32_bf16 v[90:93], v[162:165], v[206:209], v[90:93]
	v_mfma_f32_16x16x32_bf16 v[82:85], v[182:185], v[206:209], v[82:85]
	v_mfma_f32_16x16x32_bf16 v[74:77], v[162:165], v[214:217], v[74:77]
	v_mfma_f32_16x16x32_bf16 v[66:69], v[182:185], v[214:217], v[66:69]
	v_mfma_f32_16x16x32_bf16 v[122:125], v[166:169], v[194:197], v[122:125]
	v_mfma_f32_16x16x32_bf16 v[114:117], v[186:189], v[194:197], v[114:117]
	v_mfma_f32_16x16x32_bf16 v[106:109], v[166:169], v[202:205], v[106:109]
	v_mfma_f32_16x16x32_bf16 v[98:101], v[186:189], v[202:205], v[98:101]
	v_mfma_f32_16x16x32_bf16 v[90:93], v[166:169], v[210:213], v[90:93]
	v_mfma_f32_16x16x32_bf16 v[82:85], v[186:189], v[210:213], v[82:85]
	v_mfma_f32_16x16x32_bf16 v[74:77], v[166:169], v[218:221], v[74:77]
	v_mfma_f32_16x16x32_bf16 v[66:69], v[186:189], v[218:221], v[66:69]
	s_setprio 0
	s_barrier
; #define PG8_STAGE(bufoff, gbase, voff) do { _Pragma("unroll") for (int _i = 0; _i < 2; ++_i) \
;         __builtin_amdgcn_global_load_lds((const unsigned*)((const char*)(gbase) + (voff)[_i]), (PG8_LAS unsigned*)(lds + (bufoff) + ldsw + _i * 8192), 16, 0, 0); } while (0)
; #define PG8_LDA(dst, b, h) do { _Pragma("unroll") for (int m = 0; m < 4; ++m) _Pragma("unroll") for (int k = 0; k < 2; ++k) dst[m][k] = *(const PG8_LAS bf16x8*)(lds + PG8_SA(b, h) + aoff + m * 2048 + k * 1024); } while (0)
; #define PG8_WAIT_V(n) asm volatile("s_waitcnt vmcnt(" #n ")" ::: "memory")
; #define PG8_WAIT_L(n) asm volatile("s_waitcnt lgkmcnt(" #n ")" ::: "memory")
; #define PG8_BAR __builtin_amdgcn_s_barrier()
; template <class Epi, class Sched, bool ALIGN_EPI = false, bool SP2 = false>
; __device__ __forceinline__ void gemm_phase(PG8_LAS unsigned char* lds, const Gemm g, const Sched& S, const Epi& E, int tid_in) {
;     ...
;         for (int t = 0; t < nt; t += 2) {
;             const bool last = (t == nt - 2);
;             const char* a1 = cA + (size_t)(t + 1) * kstep;
;             const char* a2 = last ? nA : cA + (size_t)(t + 2) * kstep; const char* b2 = last ? nB : cB + (size_t)(t + 2) * kstep;
;             const char* a3 = a2 + kstep; const char* b3 = b2 + kstep;
;             if (last && has_next) S.a_ready(nxt);
;             if constexpr (SP2) {
;             PG8_LDB(B0, 0, 0); PG8_LDB(B1, 0, 1); PG8_SCHED; PG8_LDA(At, 0, 0); PG8_STAGE(PG8_SA(1, 1), a1 + hstepA, voffA);
;             PG8_WAIT_V(8); PG8_WAIT_L(0); PG8_BAR; PG8_MMA(0, 0, At, B0); PG8_MMA(0, 1, At, B1); PG8_BAR; PG8_SCHED;
;             PG8_LDA(At, 0, 1); PG8_STAGE(PG8_SB(0, 0), b2, voffB); PG8_STAGE(PG8_SB(0, 1), b2 + hstep, voffB); PG8_STAGE(PG8_SA(0, 0), a2, voffA);
;             PG8_WAIT_V(8); PG8_WAIT_L(0); PG8_BAR; PG8_MMA(1, 0, At, B0); PG8_MMA(1, 1, At, B1); PG8_BAR; PG8_SCHED;
;             PG8_LDB(B0, 1, 0); PG8_LDB(B1, 1, 1); PG8_SCHED; PG8_LDA(At, 1, 0); PG8_STAGE(PG8_SA(0, 1), a2 + hstepA, voffA);
;             PG8_WAIT_V(8); PG8_WAIT_L(0); PG8_BAR; PG8_MMA(0, 0, At, B0); PG8_MMA(0, 1, At, B1); PG8_BAR; PG8_SCHED;
;             PG8_LDA(At, 1, 1); PG8_STAGE(PG8_SB(1, 0), b3, voffB); PG8_STAGE(PG8_SB(1, 1), b3 + hstep, voffB); PG8_STAGE(PG8_SA(1, 0), a3, voffA);
;             PG8_WAIT_V(8); PG8_WAIT_L(0); PG8_BAR; PG8_MMA(1, 0, At, B0); PG8_MMA(1, 1, At, B1); PG8_BAR; PG8_SCHED;
	s_add_i32 s28, s45, s31
	v_lshl_add_u64 v[222:223], v[222:223], 0, s[90:91]
	s_mov_b32 m0, s28
	ds_read_b128 v[190:193], v153 offset:49152
	ds_read_b128 v[194:197], v153 offset:50176
	ds_read_b128 v[198:201], v153 offset:51200
	ds_read_b128 v[202:205], v153 offset:52224
	ds_read_b128 v[206:209], v153 offset:53248
	ds_read_b128 v[210:213], v153 offset:54272
	ds_read_b128 v[214:217], v153 offset:55296
	ds_read_b128 v[218:221], v153 offset:56320
	global_load_lds_dwordx4 v[222:223], off
	s_add_i32 m0, s28, 0x2000
	s_add_u32 s26, s26, 0x80080
	v_lshl_add_u64 v[222:223], v[224:225], 0, s[90:91]
	s_addc_u32 s27, s27, 0
	s_add_i32 s28, s46, s31
	global_load_lds_dwordx4 v[222:223], off
	v_lshl_add_u64 v[222:223], s[26:27], 0, v[0:1]
	s_mov_b32 m0, s28
	s_nop 0
	global_load_lds_dwordx4 v[222:223], off
	v_lshl_add_u64 v[222:223], s[26:27], 0, v[130:131]
	s_add_i32 m0, s28, 0x2000
	s_nop 0
	global_load_lds_dwordx4 v[222:223], off
	v_lshl_add_u64 v[226:227], v[226:227], 0, s[90:91]
	v_lshl_add_u64 v[228:229], v[228:229], 0, s[90:91]
	s_add_i32 s23, s23, 2
	s_add_u32 s24, s24, 0x100
	s_addc_u32 s25, s25, 0
	s_add_u32 s15, s15, 0x100
	s_addc_u32 s17, s17, 0
	s_cmp_gt_u32 s23, 29
	s_waitcnt vmcnt(6)
	s_waitcnt lgkmcnt(0)
	s_barrier
	s_setprio 1
	s_waitcnt lgkmcnt(0)
	v_mfma_f32_16x16x32_bf16 v[62:65], v[142:145], v[190:193], v[62:65]
	v_mfma_f32_16x16x32_bf16 v[54:57], v[154:157], v[190:193], v[54:57]
	v_mfma_f32_16x16x32_bf16 v[46:49], v[142:145], v[198:201], v[46:49]
	v_mfma_f32_16x16x32_bf16 v[38:41], v[154:157], v[198:201], v[38:41]
	v_mfma_f32_16x16x32_bf16 v[30:33], v[142:145], v[206:209], v[30:33]
	v_mfma_f32_16x16x32_bf16 v[22:25], v[154:157], v[206:209], v[22:25]
	v_mfma_f32_16x16x32_bf16 v[14:17], v[142:145], v[214:217], v[14:17]
	v_mfma_f32_16x16x32_bf16 v[6:9], v[154:157], v[214:217], v[6:9]
	v_mfma_f32_16x16x32_bf16 v[62:65], v[146:149], v[194:197], v[62:65]
	v_mfma_f32_16x16x32_bf16 v[54:57], v[158:161], v[194:197], v[54:57]
	v_mfma_f32_16x16x32_bf16 v[46:49], v[146:149], v[202:205], v[46:49]
	v_mfma_f32_16x16x32_bf16 v[38:41], v[158:161], v[202:205], v[38:41]
	v_mfma_f32_16x16x32_bf16 v[30:33], v[146:149], v[210:213], v[30:33]
	v_mfma_f32_16x16x32_bf16 v[22:25], v[158:161], v[210:213], v[22:25]
	v_mfma_f32_16x16x32_bf16 v[14:17], v[146:149], v[218:221], v[14:17]
	v_mfma_f32_16x16x32_bf16 v[6:9], v[158:161], v[218:221], v[6:9]
	s_setprio 0
	s_setprio 1
	v_mfma_f32_16x16x32_bf16 v[58:61], v[162:165], v[190:193], v[58:61]
	v_mfma_f32_16x16x32_bf16 v[50:53], v[182:185], v[190:193], v[50:53]
	v_mfma_f32_16x16x32_bf16 v[42:45], v[162:165], v[198:201], v[42:45]
	v_mfma_f32_16x16x32_bf16 v[34:37], v[182:185], v[198:201], v[34:37]
	v_mfma_f32_16x16x32_bf16 v[26:29], v[162:165], v[206:209], v[26:29]
	v_mfma_f32_16x16x32_bf16 v[18:21], v[182:185], v[206:209], v[18:21]
	v_mfma_f32_16x16x32_bf16 v[10:13], v[162:165], v[214:217], v[10:13]
	v_mfma_f32_16x16x32_bf16 v[2:5], v[182:185], v[214:217], v[2:5]
	v_mfma_f32_16x16x32_bf16 v[58:61], v[166:169], v[194:197], v[58:61]
	v_mfma_f32_16x16x32_bf16 v[50:53], v[186:189], v[194:197], v[50:53]
	v_mfma_f32_16x16x32_bf16 v[42:45], v[166:169], v[202:205], v[42:45]
	v_mfma_f32_16x16x32_bf16 v[34:37], v[186:189], v[202:205], v[34:37]
	v_mfma_f32_16x16x32_bf16 v[26:29], v[166:169], v[210:213], v[26:29]
	v_mfma_f32_16x16x32_bf16 v[18:21], v[186:189], v[210:213], v[18:21]
	v_mfma_f32_16x16x32_bf16 v[10:13], v[166:169], v[218:221], v[10:13]
	v_mfma_f32_16x16x32_bf16 v[2:5], v[186:189], v[218:221], v[2:5]
	s_setprio 0
	s_barrier
	s_cbranch_scc0 .Lbal_top_282
	s_mov_b32 m0, s39
	s_nop 0
	global_load_lds_dwordx4 v[226:227], off
	s_mov_b32 m0, s40
	s_nop 0
	global_load_lds_dwordx4 v[228:229], off
	s_and_b64 vcc, exec, s[12:13]
	s_cbranch_vccz .LBB0_285
	s_barrier

; #define PG8_LAS __attribute__((address_space(3)))
;     __device__ __forceinline__ bool next(int i, Unit& u) const { if (!StaticOrder::next(i, u)) return false; u.pm = 0; u.pn = 0; u.a = A; u.b = Bt; return true; }
; #define PG8_STAGE(bufoff, gbase, voff) do { _Pragma("unroll") for (int _i = 0; _i < 2; ++_i) \
;         __builtin_amdgcn_global_load_lds((const unsigned*)((const char*)(gbase) + (voff)[_i]), (PG8_LAS unsigned*)(lds + (bufoff) + ldsw + _i * 8192), 16, 0, 0); } while (0)
; #define PG8_LDA(dst, b, h) do { _Pragma("unroll") for (int m = 0; m < 4; ++m) _Pragma("unroll") for (int k = 0; k < 2; ++k) dst[m][k] = *(const PG8_LAS bf16x8*)(lds + PG8_SA(b, h) + aoff + m * 2048 + k * 1024); } while (0)
; #define PG8_WAIT_V(n) asm volatile("s_waitcnt vmcnt(" #n ")" ::: "memory")
; #define PG8_BAR __builtin_amdgcn_s_barrier()
; template <class Epi, class Sched, bool ALIGN_EPI = false, bool SP2 = false>
; __device__ __forceinline__ void gemm_phase(PG8_LAS unsigned char* lds, const Gemm g, const Sched& S, const Epi& E, int tid_in) {
;     ...
;     for (;;) {
;         const bool has_next = S.next(ui + 1, nxt);
;         const char* nA = has_next ? nxt.a : cA; const char* nB = has_next ? nxt.b : cB;
;         const int nt = cur.nk;
;         if constexpr (rowsc_of<Epi>::v) __builtin_amdgcn_global_load_lds((const unsigned*)(E.SSQ + cur.pm * BM + lane * 4), (PG8_LAS unsigned*)(lds + RS_LDS_OFF + wid * 1024), 16, 0, 0);
;         for (int t = 0; t < nt; t += 2) {
;             const bool last = (t == nt - 2);
;             const char* a1 = cA + (size_t)(t + 1) * kstep;
;             const char* a2 = last ? nA : cA + (size_t)(t + 2) * kstep; const char* b2 = last ? nB : cB + (size_t)(t + 2) * kstep;
;             const char* a3 = a2 + kstep; const char* b3 = b2 + kstep;
;             if (last && has_next) S.a_ready(nxt);
;             if constexpr (SP2) {
;             PG8_LDB(B0, 0, 0); PG8_LDB(B1, 0, 1); PG8_SCHED; PG8_LDA(At, 0, 0); PG8_STAGE(PG8_SA(1, 1), a1 + hstepA, voffA);
;             PG8_WAIT_V(8); PG8_WAIT_L(0); PG8_BAR; PG8_MMA(0, 0, At, B0); PG8_MMA(0, 1, At, B1); PG8_BAR; PG8_SCHED;
;             PG8_LDA(At, 0, 1); PG8_STAGE(PG8_SB(0, 0), b2, voffB); PG8_STAGE(PG8_SB(0, 1), b2 + hstep, voffB); PG8_STAGE(PG8_SA(0, 0), a2, voffA);
;             PG8_WAIT_V(8); PG8_WAIT_L(0); PG8_BAR; PG8_MMA(1, 0, At, B0); PG8_MMA(1, 1, At, B1); PG8_BAR; PG8_SCHED;
.LBB0_351:
	s_and_b64 s[4:5], s[24:25], exec
	s_cselect_b32 s46, s21, s9
	s_cselect_b32 s47, s20, s8
	s_cselect_b32 s67, s23, s27
	s_cselect_b32 s68, s22, s26
	s_add_i32 s70, s66, -2
	s_add_u32 s76, s26, 0x100
	s_addc_u32 s79, s27, 0
	s_mov_b32 s28, 0
	s_branch .LBB0_352
.Lbal_top_352:
	s_mov_b32 m0, s43
	s_nop 0
	global_load_lds_dwordx4 v[220:221], off
	s_mov_b32 m0, s44
	s_nop 0
	global_load_lds_dwordx4 v[222:223], off
.LBB0_352:
	s_add_i32 s82, s28, 2
	s_add_u32 s26, s8, 0x100
	s_addc_u32 s27, s9, 0
	s_add_i32 s4, 0, 0x10000
	s_cmp_eq_u32 s70, s28
	s_cselect_b32 s31, s46, s27
	s_cselect_b32 s30, s47, s26
	s_cselect_b32 s29, s67, s79
	s_cselect_b32 s28, s68, s76
	s_add_i32 s5, 0, 0x14000
	v_add_u32_e32 v152, s4, v146
	v_add_u32_e32 v168, s5, v146
	ds_read_b128 v[136:139], v152
	ds_read_b128 v[140:143], v152 offset:1024
	ds_read_b128 v[148:151], v152 offset:2048
	ds_read_b128 v[152:155], v152 offset:3072
	ds_read_b128 v[156:159], v168
	ds_read_b128 v[160:163], v168 offset:1024
	ds_read_b128 v[164:167], v168 offset:2048
	ds_read_b128 v[182:185], v168 offset:3072
	v_lshl_add_u64 v[168:169], s[8:9], 0, v[132:133]
	s_add_i32 m0, s34, 0xc000
	ds_read_b128 v[186:189], v147
	ds_read_b128 v[190:193], v147 offset:1024
	ds_read_b128 v[194:197], v147 offset:2048
	ds_read_b128 v[198:201], v147 offset:3072
	ds_read_b128 v[202:205], v147 offset:4096
	ds_read_b128 v[206:209], v147 offset:5120
	ds_read_b128 v[210:213], v147 offset:6144
	ds_read_b128 v[214:217], v147 offset:7168
	global_load_lds_dwordx4 v[168:169], off
	v_lshl_add_u64 v[168:169], s[8:9], 0, v[134:135]
	s_add_i32 m0, s34, 0xe000
	s_nop 0
	global_load_lds_dwordx4 v[168:169], off
	s_waitcnt vmcnt(8)
	s_waitcnt lgkmcnt(0)
	s_barrier
	s_setprio 1
	s_waitcnt lgkmcnt(0)
	v_mfma_f32_16x16x32_bf16 v[126:129], v[136:139], v[186:189], v[126:129]
	v_mfma_f32_16x16x32_bf16 v[122:125], v[148:151], v[186:189], v[122:125]
	v_mfma_f32_16x16x32_bf16 v[118:121], v[136:139], v[194:197], v[118:121]
	v_mfma_f32_16x16x32_bf16 v[114:117], v[148:151], v[194:197], v[114:117]
	v_mfma_f32_16x16x32_bf16 v[110:113], v[136:139], v[202:205], v[110:113]
	v_mfma_f32_16x16x32_bf16 v[106:109], v[148:151], v[202:205], v[106:109]
	v_mfma_f32_16x16x32_bf16 v[102:105], v[136:139], v[210:213], v[102:105]
	v_mfma_f32_16x16x32_bf16 v[98:101], v[148:151], v[210:213], v[98:101]
	v_mfma_f32_16x16x32_bf16 v[126:129], v[140:143], v[190:193], v[126:129]
	v_mfma_f32_16x16x32_bf16 v[122:125], v[152:155], v[190:193], v[122:125]
	v_mfma_f32_16x16x32_bf16 v[118:121], v[140:143], v[198:201], v[118:121]
	v_mfma_f32_16x16x32_bf16 v[114:117], v[152:155], v[198:201], v[114:117]
	v_mfma_f32_16x16x32_bf16 v[110:113], v[140:143], v[206:209], v[110:113]
	v_mfma_f32_16x16x32_bf16 v[106:109], v[152:155], v[206:209], v[106:109]
	v_mfma_f32_16x16x32_bf16 v[102:105], v[140:143], v[214:217], v[102:105]
	v_mfma_f32_16x16x32_bf16 v[98:101], v[152:155], v[214:217], v[98:101]
	s_setprio 0
	s_setprio 1
	v_mfma_f32_16x16x32_bf16 v[94:97], v[156:159], v[186:189], v[94:97]
	v_mfma_f32_16x16x32_bf16 v[90:93], v[164:167], v[186:189], v[90:93]
	v_mfma_f32_16x16x32_bf16 v[86:89], v[156:159], v[194:197], v[86:89]
	v_mfma_f32_16x16x32_bf16 v[82:85], v[164:167], v[194:197], v[82:85]
	v_mfma_f32_16x16x32_bf16 v[78:81], v[156:159], v[202:205], v[78:81]
	v_mfma_f32_16x16x32_bf16 v[74:77], v[164:167], v[202:205], v[74:77]
	v_mfma_f32_16x16x32_bf16 v[70:73], v[156:159], v[210:213], v[70:73]
	v_mfma_f32_16x16x32_bf16 v[66:69], v[164:167], v[210:213], v[66:69]
	v_mfma_f32_16x16x32_bf16 v[94:97], v[160:163], v[190:193], v[94:97]
	v_mfma_f32_16x16x32_bf16 v[90:93], v[182:185], v[190:193], v[90:93]
	v_mfma_f32_16x16x32_bf16 v[86:89], v[160:163], v[198:201], v[86:89]
	v_mfma_f32_16x16x32_bf16 v[82:85], v[182:185], v[198:201], v[82:85]
	v_mfma_f32_16x16x32_bf16 v[78:81], v[160:163], v[206:209], v[78:81]
	v_mfma_f32_16x16x32_bf16 v[74:77], v[182:185], v[206:209], v[74:77]
	v_mfma_f32_16x16x32_bf16 v[70:73], v[160:163], v[214:217], v[70:73]
	v_mfma_f32_16x16x32_bf16 v[66:69], v[182:185], v[214:217], v[66:69]
	s_setprio 0
	s_barrier
	s_add_i32 s8, s4, s33
	v_lshl_add_u64 v[168:169], s[28:29], 0, v[0:1]
	s_mov_b32 m0, s8
	ds_read_b128 v[186:189], v147 offset:16384
	ds_read_b128 v[190:193], v147 offset:17408
	ds_read_b128 v[194:197], v147 offset:18432
	ds_read_b128 v[198:201], v147 offset:19456
	ds_read_b128 v[202:205], v147 offset:20480
	ds_read_b128 v[206:209], v147 offset:21504
	ds_read_b128 v[210:213], v147 offset:22528
	ds_read_b128 v[214:217], v147 offset:23552
	global_load_lds_dwordx4 v[168:169], off
	s_add_i32 m0, s8, 0x2000
	s_add_u32 s8, s28, 0x160000
	v_lshl_add_u64 v[218:219], s[28:29], 0, v[130:131]
	s_addc_u32 s9, s29, 0
	s_add_i32 s55, s5, s33
	global_load_lds_dwordx4 v[218:219], off
	v_lshl_add_u64 v[220:221], s[8:9], 0, v[0:1]
	s_mov_b32 m0, s55
	v_lshl_add_u64 v[222:223], s[30:31], 0, v[130:131]
	global_load_lds_dwordx4 v[220:221], off
	v_lshl_add_u64 v[220:221], s[8:9], 0, v[130:131]
	s_add_i32 m0, s55, 0x2000
	s_nop 0
	global_load_lds_dwordx4 v[220:221], off
	s_waitcnt vmcnt(6)
	s_waitcnt lgkmcnt(0)
	s_barrier
; #define PG8_STAGE(bufoff, gbase, voff) do { _Pragma("unroll") for (int _i = 0; _i < 2; ++_i) \
;         __builtin_amdgcn_global_load_lds((const unsigned*)((const char*)(gbase) + (voff)[_i]), (PG8_LAS unsigned*)(lds + (bufoff) + ldsw + _i * 8192), 16, 0, 0); } while (0)
; #define PG8_LDA(dst, b, h) do { _Pragma("unroll") for (int m = 0; m < 4; ++m) _Pragma("unroll") for (int k = 0; k < 2; ++k) dst[m][k] = *(const PG8_LAS bf16x8*)(lds + PG8_SA(b, h) + aoff + m * 2048 + k * 1024); } while (0)
; #define PG8_LDB(dst, b, h) do { _Pragma("unroll") for (int n = 0; n < 2; ++n) _Pragma("unroll") for (int k = 0; k < 2; ++k) dst[n][k] = *(const PG8_LAS bf16x8*)(lds + PG8_SB(b, h) + boff + n * 2048 + k * 1024); } while (0)
; #define PG8_MMA(ai, bj, At, Bt) do { __builtin_amdgcn_s_setprio(1); _Pragma("unroll") for (int m = 0; m < 4; ++m) _Pragma("unroll") for (int n = 0; n < 2; ++n) _Pragma("unroll") for (int k = 0; k < 2; ++k) \
;         acc[ai][bj][m][n] = __builtin_amdgcn_mfma_f32_16x16x32_bf16(Bt[n][k], At[m][k], acc[ai][bj][m][n], 0, 0, 0); __builtin_amdgcn_s_setprio(0); } while (0)
; #define PG8_WAIT_V(n) asm volatile("s_waitcnt vmcnt(" #n ")" ::: "memory")
; #define PG8_WAIT_L(n) asm volatile("s_waitcnt lgkmcnt(" #n ")" ::: "memory")
; #define PG8_BAR __builtin_amdgcn_s_barrier()
; #define PG8_SCHED __builtin_amdgcn_sched_barrier(0)
; template <class Epi, class Sched, bool ALIGN_EPI = false, bool SP2 = false>
; __device__ __forceinline__ void gemm_phase(PG8_LAS unsigned char* lds, const Gemm g, const Sched& S, const Epi& E, int tid_in) {
;     ...
;             PG8_WAIT_V(8); PG8_WAIT_L(0); PG8_BAR; PG8_MMA(1, 0, At, B0); PG8_MMA(1, 1, At, B1); PG8_BAR; PG8_SCHED;
;             PG8_LDB(B0, 1, 0); PG8_LDB(B1, 1, 1); PG8_SCHED; PG8_LDA(At, 1, 0); PG8_STAGE(PG8_SA(0, 1), a2 + hstepA, voffA);
;             PG8_WAIT_V(8); PG8_WAIT_L(0); PG8_BAR; PG8_MMA(0, 0, At, B0); PG8_MMA(0, 1, At, B1); PG8_BAR; PG8_SCHED;
	s_setprio 1
	s_waitcnt lgkmcnt(0)
	v_mfma_f32_16x16x32_bf16 v[62:65], v[136:139], v[186:189], v[62:65]
	v_mfma_f32_16x16x32_bf16 v[58:61], v[148:151], v[186:189], v[58:61]
	v_mfma_f32_16x16x32_bf16 v[54:57], v[136:139], v[194:197], v[54:57]
	v_mfma_f32_16x16x32_bf16 v[50:53], v[148:151], v[194:197], v[50:53]
	v_mfma_f32_16x16x32_bf16 v[46:49], v[136:139], v[202:205], v[46:49]
	v_mfma_f32_16x16x32_bf16 v[42:45], v[148:151], v[202:205], v[42:45]
	v_mfma_f32_16x16x32_bf16 v[38:41], v[136:139], v[210:213], v[38:41]
	v_mfma_f32_16x16x32_bf16 v[34:37], v[148:151], v[210:213], v[34:37]
	v_mfma_f32_16x16x32_bf16 v[62:65], v[140:143], v[190:193], v[62:65]
	v_mfma_f32_16x16x32_bf16 v[58:61], v[152:155], v[190:193], v[58:61]
	v_mfma_f32_16x16x32_bf16 v[54:57], v[140:143], v[198:201], v[54:57]
	v_mfma_f32_16x16x32_bf16 v[50:53], v[152:155], v[198:201], v[50:53]
	v_mfma_f32_16x16x32_bf16 v[46:49], v[140:143], v[206:209], v[46:49]
	v_mfma_f32_16x16x32_bf16 v[42:45], v[152:155], v[206:209], v[42:45]
	v_mfma_f32_16x16x32_bf16 v[38:41], v[140:143], v[214:217], v[38:41]
	v_mfma_f32_16x16x32_bf16 v[34:37], v[152:155], v[214:217], v[34:37]
	s_setprio 0
	s_setprio 1
	v_mfma_f32_16x16x32_bf16 v[30:33], v[156:159], v[186:189], v[30:33]
	v_mfma_f32_16x16x32_bf16 v[26:29], v[164:167], v[186:189], v[26:29]
	v_mfma_f32_16x16x32_bf16 v[22:25], v[156:159], v[194:197], v[22:25]
	v_mfma_f32_16x16x32_bf16 v[18:21], v[164:167], v[194:197], v[18:21]
	v_mfma_f32_16x16x32_bf16 v[14:17], v[156:159], v[202:205], v[14:17]
	v_mfma_f32_16x16x32_bf16 v[10:13], v[164:167], v[202:205], v[10:13]
	v_mfma_f32_16x16x32_bf16 v[6:9], v[156:159], v[210:213], v[6:9]
	v_mfma_f32_16x16x32_bf16 v[2:5], v[164:167], v[210:213], v[2:5]
	v_mfma_f32_16x16x32_bf16 v[30:33], v[160:163], v[190:193], v[30:33]
	v_mfma_f32_16x16x32_bf16 v[26:29], v[182:185], v[190:193], v[26:29]
	v_mfma_f32_16x16x32_bf16 v[22:25], v[160:163], v[198:201], v[22:25]
	v_mfma_f32_16x16x32_bf16 v[18:21], v[182:185], v[198:201], v[18:21]
	v_mfma_f32_16x16x32_bf16 v[14:17], v[160:163], v[206:209], v[14:17]
	v_mfma_f32_16x16x32_bf16 v[10:13], v[182:185], v[206:209], v[10:13]
	v_mfma_f32_16x16x32_bf16 v[6:9], v[160:163], v[214:217], v[6:9]
	v_mfma_f32_16x16x32_bf16 v[2:5], v[182:185], v[214:217], v[2:5]
	s_setprio 0
	s_barrier
	v_lshl_add_u64 v[220:221], s[30:31], 0, v[0:1]
	s_mov_b32 m0, s34
	s_nop 0
	global_load_lds_dwordx4 v[220:221], off
	s_mov_b32 m0, s35
	s_nop 0
	global_load_lds_dwordx4 v[222:223], off
	s_add_i32 s63, 0, 0x18000
	s_add_i32 s55, 0, 0x1c000
	v_add_u32_e32 v152, s63, v146
	v_add_u32_e32 v182, s55, v146
	ds_read_b128 v[136:139], v152
	ds_read_b128 v[140:143], v152 offset:1024
	ds_read_b128 v[148:151], v152 offset:2048
	ds_read_b128 v[152:155], v152 offset:3072
	ds_read_b128 v[156:159], v182
	ds_read_b128 v[160:163], v182 offset:1024
	ds_read_b128 v[164:167], v182 offset:2048
	ds_read_b128 v[182:185], v182 offset:3072
	s_add_u32 s8, s30, 0x160000
	s_addc_u32 s9, s31, 0
	s_mov_b32 m0, s36
	v_lshl_add_u64 v[224:225], s[8:9], 0, v[0:1]
	ds_read_b128 v[186:189], v147 offset:32768
	ds_read_b128 v[190:193], v147 offset:33792
	ds_read_b128 v[194:197], v147 offset:34816
	ds_read_b128 v[198:201], v147 offset:35840
	ds_read_b128 v[202:205], v147 offset:36864
	ds_read_b128 v[206:209], v147 offset:37888
	ds_read_b128 v[210:213], v147 offset:38912
	ds_read_b128 v[214:217], v147 offset:39936
	global_load_lds_dwordx4 v[224:225], off
	v_lshl_add_u64 v[224:225], s[8:9], 0, v[130:131]
	s_mov_b32 m0, s37
	s_nop 0
	global_load_lds_dwordx4 v[224:225], off
	s_waitcnt vmcnt(8)
	s_waitcnt lgkmcnt(0)
	s_barrier
	s_setprio 1
	s_waitcnt lgkmcnt(0)
	v_mfma_f32_16x16x32_bf16 v[126:129], v[136:139], v[186:189], v[126:129]
	v_mfma_f32_16x16x32_bf16 v[122:125], v[148:151], v[186:189], v[122:125]
	v_mfma_f32_16x16x32_bf16 v[118:121], v[136:139], v[194:197], v[118:121]
	v_mfma_f32_16x16x32_bf16 v[114:117], v[148:151], v[194:197], v[114:117]
	v_mfma_f32_16x16x32_bf16 v[110:113], v[136:139], v[202:205], v[110:113]
	v_mfma_f32_16x16x32_bf16 v[106:109], v[148:151], v[202:205], v[106:109]
	v_mfma_f32_16x16x32_bf16 v[102:105], v[136:139], v[210:213], v[102:105]
	v_mfma_f32_16x16x32_bf16 v[98:101], v[148:151], v[210:213], v[98:101]
	v_mfma_f32_16x16x32_bf16 v[126:129], v[140:143], v[190:193], v[126:129]
	v_mfma_f32_16x16x32_bf16 v[122:125], v[152:155], v[190:193], v[122:125]
	v_mfma_f32_16x16x32_bf16 v[118:121], v[140:143], v[198:201], v[118:121]
	v_mfma_f32_16x16x32_bf16 v[114:117], v[152:155], v[198:201], v[114:117]
	v_mfma_f32_16x16x32_bf16 v[110:113], v[140:143], v[206:209], v[110:113]
	v_mfma_f32_16x16x32_bf16 v[106:109], v[152:155], v[206:209], v[106:109]
	v_mfma_f32_16x16x32_bf16 v[102:105], v[140:143], v[214:217], v[102:105]
	v_mfma_f32_16x16x32_bf16 v[98:101], v[152:155], v[214:217], v[98:101]
	s_setprio 0
	s_setprio 1
	v_mfma_f32_16x16x32_bf16 v[94:97], v[156:159], v[186:189], v[94:97]
	v_mfma_f32_16x16x32_bf16 v[90:93], v[164:167], v[186:189], v[90:93]
	v_mfma_f32_16x16x32_bf16 v[86:89], v[156:159], v[194:197], v[86:89]
	v_mfma_f32_16x16x32_bf16 v[82:85], v[164:167], v[194:197], v[82:85]
	v_mfma_f32_16x16x32_bf16 v[78:81], v[156:159], v[202:205], v[78:81]
	v_mfma_f32_16x16x32_bf16 v[74:77], v[164:167], v[202:205], v[74:77]
	v_mfma_f32_16x16x32_bf16 v[70:73], v[156:159], v[210:213], v[70:73]
	v_mfma_f32_16x16x32_bf16 v[66:69], v[164:167], v[210:213], v[66:69]
	v_mfma_f32_16x16x32_bf16 v[94:97], v[160:163], v[190:193], v[94:97]
	v_mfma_f32_16x16x32_bf16 v[90:93], v[182:185], v[190:193], v[90:93]
	v_mfma_f32_16x16x32_bf16 v[86:89], v[160:163], v[198:201], v[86:89]
	v_mfma_f32_16x16x32_bf16 v[82:85], v[182:185], v[198:201], v[82:85]
	v_mfma_f32_16x16x32_bf16 v[78:81], v[160:163], v[206:209], v[78:81]
	v_mfma_f32_16x16x32_bf16 v[74:77], v[182:185], v[206:209], v[74:77]
	v_mfma_f32_16x16x32_bf16 v[70:73], v[160:163], v[214:217], v[70:73]
	v_mfma_f32_16x16x32_bf16 v[66:69], v[182:185], v[214:217], v[66:69]
	s_setprio 0
	s_barrier
; #define PG8_STAGE(bufoff, gbase, voff) do { _Pragma("unroll") for (int _i = 0; _i < 2; ++_i) \
;         __builtin_amdgcn_global_load_lds((const unsigned*)((const char*)(gbase) + (voff)[_i]), (PG8_LAS unsigned*)(lds + (bufoff) + ldsw + _i * 8192), 16, 0, 0); } while (0)
; #define PG8_LDA(dst, b, h) do { _Pragma("unroll") for (int m = 0; m < 4; ++m) _Pragma("unroll") for (int k = 0; k < 2; ++k) dst[m][k] = *(const PG8_LAS bf16x8*)(lds + PG8_SA(b, h) + aoff + m * 2048 + k * 1024); } while (0)
; #define PG8_WAIT_V(n) asm volatile("s_waitcnt vmcnt(" #n ")" ::: "memory")
; #define PG8_WAIT_L(n) asm volatile("s_waitcnt lgkmcnt(" #n ")" ::: "memory")
; #define PG8_BAR __builtin_amdgcn_s_barrier()
; template <class Epi, class Sched, bool ALIGN_EPI = false, bool SP2 = false>
; __device__ __forceinline__ void gemm_phase(PG8_LAS unsigned char* lds, const Gemm g, const Sched& S, const Epi& E, int tid_in) {
;     ...
;         for (int t = 0; t < nt; t += 2) {
;             const bool last = (t == nt - 2);
;             const char* a1 = cA + (size_t)(t + 1) * kstep;
;             const char* a2 = last ? nA : cA + (size_t)(t + 2) * kstep; const char* b2 = last ? nB : cB + (size_t)(t + 2) * kstep;
;             const char* a3 = a2 + kstep; const char* b3 = b2 + kstep;
;             if (last && has_next) S.a_ready(nxt);
;             if constexpr (SP2) {
;             PG8_LDB(B0, 0, 0); PG8_LDB(B1, 0, 1); PG8_SCHED; PG8_LDA(At, 0, 0); PG8_STAGE(PG8_SA(1, 1), a1 + hstepA, voffA);
;             PG8_WAIT_V(8); PG8_WAIT_L(0); PG8_BAR; PG8_MMA(0, 0, At, B0); PG8_MMA(0, 1, At, B1); PG8_BAR; PG8_SCHED;
;             PG8_LDA(At, 0, 1); PG8_STAGE(PG8_SB(0, 0), b2, voffB); PG8_STAGE(PG8_SB(0, 1), b2 + hstep, voffB); PG8_STAGE(PG8_SA(0, 0), a2, voffA);
;             PG8_WAIT_V(8); PG8_WAIT_L(0); PG8_BAR; PG8_MMA(1, 0, At, B0); PG8_MMA(1, 1, At, B1); PG8_BAR; PG8_SCHED;
;             PG8_LDB(B0, 1, 0); PG8_LDB(B1, 1, 1); PG8_SCHED; PG8_LDA(At, 1, 0); PG8_STAGE(PG8_SA(0, 1), a2 + hstepA, voffA);
;             PG8_WAIT_V(8); PG8_WAIT_L(0); PG8_BAR; PG8_MMA(0, 0, At, B0); PG8_MMA(0, 1, At, B1); PG8_BAR; PG8_SCHED;
;             PG8_LDA(At, 1, 1); PG8_STAGE(PG8_SB(1, 0), b3, voffB); PG8_STAGE(PG8_SB(1, 1), b3 + hstep, voffB); PG8_STAGE(PG8_SA(1, 0), a3, voffA);
;             PG8_WAIT_V(8); PG8_WAIT_L(0); PG8_BAR; PG8_MMA(1, 0, At, B0); PG8_MMA(1, 1, At, B1); PG8_BAR; PG8_SCHED;
	s_add_i32 s8, s63, s33
	v_lshl_add_u64 v[168:169], v[168:169], 0, s[90:91]
	s_mov_b32 m0, s8
	ds_read_b128 v[186:189], v147 offset:49152
	ds_read_b128 v[190:193], v147 offset:50176
	ds_read_b128 v[194:197], v147 offset:51200
	ds_read_b128 v[198:201], v147 offset:52224
	ds_read_b128 v[202:205], v147 offset:53248
	ds_read_b128 v[206:209], v147 offset:54272
	ds_read_b128 v[210:213], v147 offset:55296
	ds_read_b128 v[214:217], v147 offset:56320
	global_load_lds_dwordx4 v[168:169], off
	s_add_i32 m0, s8, 0x2000
	s_add_u32 s8, s28, 0x160080
	v_lshl_add_u64 v[168:169], v[218:219], 0, s[90:91]
	s_addc_u32 s9, s29, 0
	s_add_i32 s28, s55, s33
	global_load_lds_dwordx4 v[168:169], off
	v_lshl_add_u64 v[168:169], s[8:9], 0, v[0:1]
	s_mov_b32 m0, s28
	s_nop 0
	global_load_lds_dwordx4 v[168:169], off
	v_lshl_add_u64 v[168:169], s[8:9], 0, v[130:131]
	s_add_i32 m0, s28, 0x2000
	s_nop 0
	global_load_lds_dwordx4 v[168:169], off
	v_lshl_add_u64 v[220:221], v[220:221], 0, s[90:91]
	v_lshl_add_u64 v[222:223], v[222:223], 0, s[90:91]
	s_add_u32 s76, s76, 0x100
	s_addc_u32 s79, s79, 0
	s_cmp_ge_u32 s82, s66
	s_mov_b64 s[8:9], s[26:27]
	s_mov_b32 s28, s82
	s_waitcnt vmcnt(6)
	s_waitcnt lgkmcnt(0)
	s_barrier
	s_setprio 1
	s_waitcnt lgkmcnt(0)
	v_mfma_f32_16x16x32_bf16 v[62:65], v[136:139], v[186:189], v[62:65]
	v_mfma_f32_16x16x32_bf16 v[58:61], v[148:151], v[186:189], v[58:61]
	v_mfma_f32_16x16x32_bf16 v[54:57], v[136:139], v[194:197], v[54:57]
	v_mfma_f32_16x16x32_bf16 v[50:53], v[148:151], v[194:197], v[50:53]
	v_mfma_f32_16x16x32_bf16 v[46:49], v[136:139], v[202:205], v[46:49]
	v_mfma_f32_16x16x32_bf16 v[42:45], v[148:151], v[202:205], v[42:45]
	v_mfma_f32_16x16x32_bf16 v[38:41], v[136:139], v[210:213], v[38:41]
	v_mfma_f32_16x16x32_bf16 v[34:37], v[148:151], v[210:213], v[34:37]
	v_mfma_f32_16x16x32_bf16 v[62:65], v[140:143], v[190:193], v[62:65]
	v_mfma_f32_16x16x32_bf16 v[58:61], v[152:155], v[190:193], v[58:61]
	v_mfma_f32_16x16x32_bf16 v[54:57], v[140:143], v[198:201], v[54:57]
	v_mfma_f32_16x16x32_bf16 v[50:53], v[152:155], v[198:201], v[50:53]
	v_mfma_f32_16x16x32_bf16 v[46:49], v[140:143], v[206:209], v[46:49]
	v_mfma_f32_16x16x32_bf16 v[42:45], v[152:155], v[206:209], v[42:45]
	v_mfma_f32_16x16x32_bf16 v[38:41], v[140:143], v[214:217], v[38:41]
	v_mfma_f32_16x16x32_bf16 v[34:37], v[152:155], v[214:217], v[34:37]
	s_setprio 0
	s_setprio 1
	v_mfma_f32_16x16x32_bf16 v[30:33], v[156:159], v[186:189], v[30:33]
	v_mfma_f32_16x16x32_bf16 v[26:29], v[164:167], v[186:189], v[26:29]
	v_mfma_f32_16x16x32_bf16 v[22:25], v[156:159], v[194:197], v[22:25]
	v_mfma_f32_16x16x32_bf16 v[18:21], v[164:167], v[194:197], v[18:21]
	v_mfma_f32_16x16x32_bf16 v[14:17], v[156:159], v[202:205], v[14:17]
	v_mfma_f32_16x16x32_bf16 v[10:13], v[164:167], v[202:205], v[10:13]
	v_mfma_f32_16x16x32_bf16 v[6:9], v[156:159], v[210:213], v[6:9]
	v_mfma_f32_16x16x32_bf16 v[2:5], v[164:167], v[210:213], v[2:5]
	v_mfma_f32_16x16x32_bf16 v[30:33], v[160:163], v[190:193], v[30:33]
	v_mfma_f32_16x16x32_bf16 v[26:29], v[182:185], v[190:193], v[26:29]
	v_mfma_f32_16x16x32_bf16 v[22:25], v[160:163], v[198:201], v[22:25]
	v_mfma_f32_16x16x32_bf16 v[18:21], v[182:185], v[198:201], v[18:21]
	v_mfma_f32_16x16x32_bf16 v[14:17], v[160:163], v[206:209], v[14:17]
	v_mfma_f32_16x16x32_bf16 v[10:13], v[182:185], v[206:209], v[10:13]
	v_mfma_f32_16x16x32_bf16 v[6:9], v[160:163], v[214:217], v[6:9]
	v_mfma_f32_16x16x32_bf16 v[2:5], v[182:185], v[214:217], v[2:5]
	s_setprio 0
	s_barrier
	s_cbranch_scc0 .Lbal_top_352
	s_mov_b32 m0, s43
	s_nop 0
	global_load_lds_dwordx4 v[220:221], off
	s_mov_b32 m0, s44
	s_nop 0
	global_load_lds_dwordx4 v[222:223], off
	s_and_b64 vcc, exec, s[18:19]
	s_cbranch_vccz .LBB0_355
	s_barrier

; #define PG8_LAS __attribute__((address_space(3)))
; #define PG8_STAGE(bufoff, gbase, voff) do { _Pragma("unroll") for (int _i = 0; _i < 2; ++_i) \
;         __builtin_amdgcn_global_load_lds((const unsigned*)((const char*)(gbase) + (voff)[_i]), (PG8_LAS unsigned*)(lds + (bufoff) + ldsw + _i * 8192), 16, 0, 0); } while (0)
; #define PG8_LDA(dst, b, h) do { _Pragma("unroll") for (int m = 0; m < 4; ++m) _Pragma("unroll") for (int k = 0; k < 2; ++k) dst[m][k] = *(const PG8_LAS bf16x8*)(lds + PG8_SA(b, h) + aoff + m * 2048 + k * 1024); } while (0)
; #define PG8_LDB(dst, b, h) do { _Pragma("unroll") for (int n = 0; n < 2; ++n) _Pragma("unroll") for (int k = 0; k < 2; ++k) dst[n][k] = *(const PG8_LAS bf16x8*)(lds + PG8_SB(b, h) + boff + n * 2048 + k * 1024); } while (0)
; #define PG8_WAIT_V(n) asm volatile("s_waitcnt vmcnt(" #n ")" ::: "memory")
; #define PG8_WAIT_L(n) asm volatile("s_waitcnt lgkmcnt(" #n ")" ::: "memory")
; #define PG8_BAR __builtin_amdgcn_s_barrier()
; #define PG8_SCHED __builtin_amdgcn_sched_barrier(0)
; template <class Epi, class Sched, bool ALIGN_EPI = false, bool SP2 = false>
; __device__ __forceinline__ void gemm_phase(PG8_LAS unsigned char* lds, const Gemm g, const Sched& S, const Epi& E, int tid_in) {
;     ...
;         if constexpr (rowsc_of<Epi>::v) __builtin_amdgcn_global_load_lds((const unsigned*)(E.SSQ + cur.pm * BM + lane * 4), (PG8_LAS unsigned*)(lds + RS_LDS_OFF + wid * 1024), 16, 0, 0);
;         for (int t = 0; t < nt; t += 2) {
;             const bool last = (t == nt - 2);
;             const char* a1 = cA + (size_t)(t + 1) * kstep;
;             const char* a2 = last ? nA : cA + (size_t)(t + 2) * kstep; const char* b2 = last ? nB : cB + (size_t)(t + 2) * kstep;
;             const char* a3 = a2 + kstep; const char* b3 = b2 + kstep;
;             if (last && has_next) S.a_ready(nxt);
;             if constexpr (SP2) {
;             PG8_LDB(B0, 0, 0); PG8_LDB(B1, 0, 1); PG8_SCHED; PG8_LDA(At, 0, 0); PG8_STAGE(PG8_SA(1, 1), a1 + hstepA, voffA);
;             PG8_WAIT_V(8); PG8_WAIT_L(0); PG8_BAR; PG8_MMA(0, 0, At, B0); PG8_MMA(0, 1, At, B1); PG8_BAR; PG8_SCHED;
;     ...
;         for (int a = 0; a < 2; ++a)
; #pragma unroll
;             for (int b = 0; b < 2; ++b)
; #pragma unroll
;                 for (int m = 0; m < 4; ++m)
; #pragma unroll
;                     for (int n = 0; n < 2; ++n) acc[a][b][m][n] = (f32x4){0.f, 0.f, 0.f, 0.f};
.LBB0_512:
	s_lshl_b32 s12, s30, 8
	s_ashr_i32 s13, s12, 31
	s_mov_b32 m0, s49
	v_lshl_add_u64 v[2:3], s[12:13], 2, v[136:137]
	global_load_lds_dwordx4 v[2:3], off
	s_add_u32 s14, s14, 0x80080
	s_addc_u32 s15, s15, 0
	s_add_u32 s13, s28, 0x100
	v_mov_b32_e32 v2, 0
	s_addc_u32 s21, s29, 0
	s_mov_b32 s23, -2
	v_mov_b32_e32 v3, v2
	v_mov_b32_e32 v4, v2
	v_mov_b32_e32 v5, v2
	v_mov_b32_e32 v6, v2
	v_mov_b32_e32 v7, v2
	v_mov_b32_e32 v8, v2
	v_mov_b32_e32 v9, v2
	v_mov_b32_e32 v18, v2
	v_mov_b32_e32 v19, v2
	v_mov_b32_e32 v20, v2
	v_mov_b32_e32 v21, v2
	v_mov_b32_e32 v22, v2
	v_mov_b32_e32 v23, v2
	v_mov_b32_e32 v24, v2
	v_mov_b32_e32 v25, v2
	v_mov_b32_e32 v34, v2
	v_mov_b32_e32 v35, v2
	v_mov_b32_e32 v36, v2
	v_mov_b32_e32 v37, v2
	v_mov_b32_e32 v38, v2
	v_mov_b32_e32 v39, v2
	v_mov_b32_e32 v40, v2
	v_mov_b32_e32 v41, v2
	v_mov_b32_e32 v50, v2
	v_mov_b32_e32 v51, v2
	v_mov_b32_e32 v52, v2
	v_mov_b32_e32 v53, v2
	v_mov_b32_e32 v54, v2
	v_mov_b32_e32 v55, v2
	v_mov_b32_e32 v56, v2
	v_mov_b32_e32 v57, v2
	v_mov_b32_e32 v10, v2
	v_mov_b32_e32 v11, v2
	v_mov_b32_e32 v12, v2
	v_mov_b32_e32 v13, v2
	v_mov_b32_e32 v14, v2
	v_mov_b32_e32 v15, v2
	v_mov_b32_e32 v16, v2
	v_mov_b32_e32 v17, v2
	v_mov_b32_e32 v26, v2
	v_mov_b32_e32 v27, v2
	v_mov_b32_e32 v28, v2
	v_mov_b32_e32 v29, v2
	v_mov_b32_e32 v30, v2
	v_mov_b32_e32 v31, v2
	v_mov_b32_e32 v32, v2
	v_mov_b32_e32 v33, v2
	v_mov_b32_e32 v42, v2
	v_mov_b32_e32 v43, v2
	v_mov_b32_e32 v44, v2
	v_mov_b32_e32 v45, v2
	v_mov_b32_e32 v46, v2
	v_mov_b32_e32 v47, v2
	v_mov_b32_e32 v48, v2
	v_mov_b32_e32 v49, v2
	v_mov_b32_e32 v58, v2
	v_mov_b32_e32 v59, v2
	v_mov_b32_e32 v60, v2
	v_mov_b32_e32 v61, v2
	v_mov_b32_e32 v62, v2
	v_mov_b32_e32 v63, v2
	v_mov_b32_e32 v64, v2
	v_mov_b32_e32 v65, v2
	v_mov_b32_e32 v66, v2
	v_mov_b32_e32 v67, v2
	v_mov_b32_e32 v68, v2
	v_mov_b32_e32 v69, v2
	v_mov_b32_e32 v70, v2
	v_mov_b32_e32 v71, v2
	v_mov_b32_e32 v72, v2
	v_mov_b32_e32 v73, v2
	v_mov_b32_e32 v82, v2
	v_mov_b32_e32 v83, v2
	v_mov_b32_e32 v84, v2
	v_mov_b32_e32 v85, v2
	v_mov_b32_e32 v86, v2
	v_mov_b32_e32 v87, v2
	v_mov_b32_e32 v88, v2
	v_mov_b32_e32 v89, v2
	v_mov_b32_e32 v98, v2
	v_mov_b32_e32 v99, v2
	v_mov_b32_e32 v100, v2
	v_mov_b32_e32 v101, v2
	v_mov_b32_e32 v102, v2
	v_mov_b32_e32 v103, v2
	v_mov_b32_e32 v104, v2
	v_mov_b32_e32 v105, v2
	v_mov_b32_e32 v114, v2
	v_mov_b32_e32 v115, v2
	v_mov_b32_e32 v116, v2
	v_mov_b32_e32 v117, v2
	v_mov_b32_e32 v118, v2
	v_mov_b32_e32 v119, v2
	v_mov_b32_e32 v120, v2
	v_mov_b32_e32 v121, v2
	v_mov_b32_e32 v74, v2
	v_mov_b32_e32 v75, v2
	v_mov_b32_e32 v76, v2
	v_mov_b32_e32 v77, v2
	v_mov_b32_e32 v78, v2
	v_mov_b32_e32 v79, v2
	v_mov_b32_e32 v80, v2
	v_mov_b32_e32 v81, v2
	v_mov_b32_e32 v90, v2
	v_mov_b32_e32 v91, v2
	v_mov_b32_e32 v92, v2
	v_mov_b32_e32 v93, v2
	v_mov_b32_e32 v94, v2
	v_mov_b32_e32 v95, v2
	v_mov_b32_e32 v96, v2
	v_mov_b32_e32 v97, v2
	v_mov_b32_e32 v106, v2
	v_mov_b32_e32 v107, v2
	v_mov_b32_e32 v108, v2
	v_mov_b32_e32 v109, v2
	v_mov_b32_e32 v110, v2
	v_mov_b32_e32 v111, v2
	v_mov_b32_e32 v112, v2
	v_mov_b32_e32 v113, v2
	v_mov_b32_e32 v122, v2
	v_mov_b32_e32 v123, v2
	v_mov_b32_e32 v124, v2
	v_mov_b32_e32 v125, v2
	v_mov_b32_e32 v126, v2
	v_mov_b32_e32 v127, v2
	v_mov_b32_e32 v128, v2
	v_mov_b32_e32 v129, v2
	s_branch .LBB0_513
.Lbal_top_513:
	s_mov_b32 m0, s45
	s_nop 0
	global_load_lds_dwordx4 v[228:229], off
	s_mov_b32 m0, s48
	s_nop 0
	global_load_lds_dwordx4 v[240:241], off
.LBB0_513:
	v_add_u32_e32 v150, s4, v157
	ds_read_b128 v[142:145], v150
	ds_read_b128 v[146:149], v150 offset:1024
	ds_read_b128 v[152:155], v150 offset:2048
	ds_read_b128 v[160:163], v150 offset:3072
	v_add_u32_e32 v150, s5, v157
	ds_read_b128 v[164:167], v150
	ds_read_b128 v[182:185], v150 offset:1024
	ds_read_b128 v[186:189], v150 offset:2048
	ds_read_b128 v[190:193], v150 offset:3072
	s_add_u32 s28, s14, 0xfff80080
	s_addc_u32 s29, s15, -1
	s_cmp_eq_u32 s23, 28
	s_cselect_b32 s31, s25, s29
	s_cselect_b32 s30, s24, s28
	s_cselect_b32 s29, s27, s21
	s_cselect_b32 s28, s26, s13
	v_lshl_add_u64 v[168:169], s[14:15], 0, v[138:139]
	s_add_i32 m0, s38, 0xc000
	ds_read_b128 v[194:197], v158
	ds_read_b128 v[198:201], v158 offset:1024
	ds_read_b128 v[202:205], v158 offset:2048
	ds_read_b128 v[206:209], v158 offset:3072
	ds_read_b128 v[210:213], v158 offset:4096
	ds_read_b128 v[214:217], v158 offset:5120
	ds_read_b128 v[218:221], v158 offset:6144
	ds_read_b128 v[222:225], v158 offset:7168
	global_load_lds_dwordx4 v[168:169], off
	v_lshl_add_u64 v[168:169], s[14:15], 0, v[140:141]
	s_add_i32 m0, s38, 0xe000
	s_nop 0
	global_load_lds_dwordx4 v[168:169], off
	s_waitcnt vmcnt(8)
	s_waitcnt lgkmcnt(0)
	s_barrier
; #define PG8_STAGE(bufoff, gbase, voff) do { _Pragma("unroll") for (int _i = 0; _i < 2; ++_i) \
;         __builtin_amdgcn_global_load_lds((const unsigned*)((const char*)(gbase) + (voff)[_i]), (PG8_LAS unsigned*)(lds + (bufoff) + ldsw + _i * 8192), 16, 0, 0); } while (0)
; #define PG8_LDA(dst, b, h) do { _Pragma("unroll") for (int m = 0; m < 4; ++m) _Pragma("unroll") for (int k = 0; k < 2; ++k) dst[m][k] = *(const PG8_LAS bf16x8*)(lds + PG8_SA(b, h) + aoff + m * 2048 + k * 1024); } while (0)
; #define PG8_MMA(ai, bj, At, Bt) do { __builtin_amdgcn_s_setprio(1); _Pragma("unroll") for (int m = 0; m < 4; ++m) _Pragma("unroll") for (int n = 0; n < 2; ++n) _Pragma("unroll") for (int k = 0; k < 2; ++k) \
;         acc[ai][bj][m][n] = __builtin_amdgcn_mfma_f32_16x16x32_bf16(Bt[n][k], At[m][k], acc[ai][bj][m][n], 0, 0, 0); __builtin_amdgcn_s_setprio(0); } while (0)
; #define PG8_WAIT_V(n) asm volatile("s_waitcnt vmcnt(" #n ")" ::: "memory")
; #define PG8_WAIT_L(n) asm volatile("s_waitcnt lgkmcnt(" #n ")" ::: "memory")
; #define PG8_BAR __builtin_amdgcn_s_barrier()
; #define PG8_SCHED __builtin_amdgcn_sched_barrier(0)
; template <class Epi, class Sched, bool ALIGN_EPI = false, bool SP2 = false>
; __device__ __forceinline__ void gemm_phase(PG8_LAS unsigned char* lds, const Gemm g, const Sched& S, const Epi& E, int tid_in) {
;     ...
;             PG8_WAIT_V(8); PG8_WAIT_L(0); PG8_BAR; PG8_MMA(0, 0, At, B0); PG8_MMA(0, 1, At, B1); PG8_BAR; PG8_SCHED;
;             PG8_LDA(At, 0, 1); PG8_STAGE(PG8_SB(0, 0), b2, voffB); PG8_STAGE(PG8_SB(0, 1), b2 + hstep, voffB); PG8_STAGE(PG8_SA(0, 0), a2, voffA);
;             PG8_WAIT_V(8); PG8_WAIT_L(0); PG8_BAR; PG8_MMA(1, 0, At, B0); PG8_MMA(1, 1, At, B1); PG8_BAR; PG8_SCHED;
	s_setprio 1
	s_waitcnt lgkmcnt(0)
	v_mfma_f32_16x16x32_bf16 v[126:129], v[142:145], v[194:197], v[126:129]
	v_mfma_f32_16x16x32_bf16 v[122:125], v[152:155], v[194:197], v[122:125]
	v_mfma_f32_16x16x32_bf16 v[110:113], v[142:145], v[202:205], v[110:113]
	v_mfma_f32_16x16x32_bf16 v[106:109], v[152:155], v[202:205], v[106:109]
	v_mfma_f32_16x16x32_bf16 v[94:97], v[142:145], v[210:213], v[94:97]
	v_mfma_f32_16x16x32_bf16 v[90:93], v[152:155], v[210:213], v[90:93]
	v_mfma_f32_16x16x32_bf16 v[78:81], v[142:145], v[218:221], v[78:81]
	v_mfma_f32_16x16x32_bf16 v[74:77], v[152:155], v[218:221], v[74:77]
	v_mfma_f32_16x16x32_bf16 v[126:129], v[146:149], v[198:201], v[126:129]
	v_mfma_f32_16x16x32_bf16 v[122:125], v[160:163], v[198:201], v[122:125]
	v_mfma_f32_16x16x32_bf16 v[110:113], v[146:149], v[206:209], v[110:113]
	v_mfma_f32_16x16x32_bf16 v[106:109], v[160:163], v[206:209], v[106:109]
	v_mfma_f32_16x16x32_bf16 v[94:97], v[146:149], v[214:217], v[94:97]
	v_mfma_f32_16x16x32_bf16 v[90:93], v[160:163], v[214:217], v[90:93]
	v_mfma_f32_16x16x32_bf16 v[78:81], v[146:149], v[222:225], v[78:81]
	v_mfma_f32_16x16x32_bf16 v[74:77], v[160:163], v[222:225], v[74:77]
	s_setprio 0
	s_setprio 1
	v_mfma_f32_16x16x32_bf16 v[118:121], v[164:167], v[194:197], v[118:121]
	v_mfma_f32_16x16x32_bf16 v[114:117], v[186:189], v[194:197], v[114:117]
	v_mfma_f32_16x16x32_bf16 v[102:105], v[164:167], v[202:205], v[102:105]
	v_mfma_f32_16x16x32_bf16 v[98:101], v[186:189], v[202:205], v[98:101]
	v_mfma_f32_16x16x32_bf16 v[86:89], v[164:167], v[210:213], v[86:89]
	v_mfma_f32_16x16x32_bf16 v[82:85], v[186:189], v[210:213], v[82:85]
	v_mfma_f32_16x16x32_bf16 v[70:73], v[164:167], v[218:221], v[70:73]
	v_mfma_f32_16x16x32_bf16 v[66:69], v[186:189], v[218:221], v[66:69]
	v_mfma_f32_16x16x32_bf16 v[118:121], v[182:185], v[198:201], v[118:121]
	v_mfma_f32_16x16x32_bf16 v[114:117], v[190:193], v[198:201], v[114:117]
	v_mfma_f32_16x16x32_bf16 v[102:105], v[182:185], v[206:209], v[102:105]
	v_mfma_f32_16x16x32_bf16 v[98:101], v[190:193], v[206:209], v[98:101]
	v_mfma_f32_16x16x32_bf16 v[86:89], v[182:185], v[214:217], v[86:89]
	v_mfma_f32_16x16x32_bf16 v[82:85], v[190:193], v[214:217], v[82:85]
	v_mfma_f32_16x16x32_bf16 v[70:73], v[182:185], v[222:225], v[70:73]
	v_mfma_f32_16x16x32_bf16 v[66:69], v[190:193], v[222:225], v[66:69]
	s_setprio 0
	s_barrier
	s_add_i32 s46, s4, s37
	v_lshl_add_u64 v[168:169], s[28:29], 0, v[0:1]
	s_mov_b32 m0, s46
	ds_read_b128 v[194:197], v158 offset:16384
	ds_read_b128 v[198:201], v158 offset:17408
	ds_read_b128 v[202:205], v158 offset:18432
	ds_read_b128 v[206:209], v158 offset:19456
	ds_read_b128 v[210:213], v158 offset:20480
	ds_read_b128 v[214:217], v158 offset:21504
	ds_read_b128 v[218:221], v158 offset:22528
	ds_read_b128 v[222:225], v158 offset:23552
	global_load_lds_dwordx4 v[168:169], off
	s_add_i32 m0, s46, 0x2000
	s_add_u32 s46, s28, 0x80000
	v_lshl_add_u64 v[226:227], s[28:29], 0, v[134:135]
	s_addc_u32 s47, s29, 0
	s_add_i32 s64, s5, s37
	global_load_lds_dwordx4 v[226:227], off
	v_lshl_add_u64 v[228:229], s[46:47], 0, v[0:1]
	s_mov_b32 m0, s64
	v_lshl_add_u64 v[240:241], s[30:31], 0, v[132:133]
	global_load_lds_dwordx4 v[228:229], off
	v_lshl_add_u64 v[228:229], s[46:47], 0, v[134:135]
	s_add_i32 m0, s64, 0x2000
	s_nop 0
	global_load_lds_dwordx4 v[228:229], off
	s_waitcnt vmcnt(6)
	s_waitcnt lgkmcnt(0)
	s_barrier
	s_setprio 1
	s_waitcnt lgkmcnt(0)
	v_mfma_f32_16x16x32_bf16 v[62:65], v[142:145], v[194:197], v[62:65]
	v_mfma_f32_16x16x32_bf16 v[58:61], v[152:155], v[194:197], v[58:61]
	v_mfma_f32_16x16x32_bf16 v[46:49], v[142:145], v[202:205], v[46:49]
	v_mfma_f32_16x16x32_bf16 v[42:45], v[152:155], v[202:205], v[42:45]
	v_mfma_f32_16x16x32_bf16 v[30:33], v[142:145], v[210:213], v[30:33]
	v_mfma_f32_16x16x32_bf16 v[26:29], v[152:155], v[210:213], v[26:29]
	v_mfma_f32_16x16x32_bf16 v[14:17], v[142:145], v[218:221], v[14:17]
	v_mfma_f32_16x16x32_bf16 v[10:13], v[152:155], v[218:221], v[10:13]
	v_mfma_f32_16x16x32_bf16 v[62:65], v[146:149], v[198:201], v[62:65]
	v_mfma_f32_16x16x32_bf16 v[58:61], v[160:163], v[198:201], v[58:61]
	v_mfma_f32_16x16x32_bf16 v[46:49], v[146:149], v[206:209], v[46:49]
	v_mfma_f32_16x16x32_bf16 v[42:45], v[160:163], v[206:209], v[42:45]
	v_mfma_f32_16x16x32_bf16 v[30:33], v[146:149], v[214:217], v[30:33]
	v_mfma_f32_16x16x32_bf16 v[26:29], v[160:163], v[214:217], v[26:29]
	v_mfma_f32_16x16x32_bf16 v[14:17], v[146:149], v[222:225], v[14:17]
	v_mfma_f32_16x16x32_bf16 v[10:13], v[160:163], v[222:225], v[10:13]
	s_setprio 0
	s_setprio 1
	v_mfma_f32_16x16x32_bf16 v[54:57], v[164:167], v[194:197], v[54:57]
	v_mfma_f32_16x16x32_bf16 v[50:53], v[186:189], v[194:197], v[50:53]
	v_mfma_f32_16x16x32_bf16 v[38:41], v[164:167], v[202:205], v[38:41]
	v_mfma_f32_16x16x32_bf16 v[34:37], v[186:189], v[202:205], v[34:37]
	v_mfma_f32_16x16x32_bf16 v[22:25], v[164:167], v[210:213], v[22:25]
	v_mfma_f32_16x16x32_bf16 v[18:21], v[186:189], v[210:213], v[18:21]
	v_mfma_f32_16x16x32_bf16 v[6:9], v[164:167], v[218:221], v[6:9]
	v_mfma_f32_16x16x32_bf16 v[2:5], v[186:189], v[218:221], v[2:5]
	v_mfma_f32_16x16x32_bf16 v[54:57], v[182:185], v[198:201], v[54:57]
	v_mfma_f32_16x16x32_bf16 v[50:53], v[190:193], v[198:201], v[50:53]
	v_mfma_f32_16x16x32_bf16 v[38:41], v[182:185], v[206:209], v[38:41]
	v_mfma_f32_16x16x32_bf16 v[34:37], v[190:193], v[206:209], v[34:37]
	v_mfma_f32_16x16x32_bf16 v[22:25], v[182:185], v[214:217], v[22:25]
	v_mfma_f32_16x16x32_bf16 v[18:21], v[190:193], v[214:217], v[18:21]
	v_mfma_f32_16x16x32_bf16 v[6:9], v[182:185], v[222:225], v[6:9]
	v_mfma_f32_16x16x32_bf16 v[2:5], v[190:193], v[222:225], v[2:5]
	s_setprio 0
	s_barrier
; #define PG8_STAGE(bufoff, gbase, voff) do { _Pragma("unroll") for (int _i = 0; _i < 2; ++_i) \
;         __builtin_amdgcn_global_load_lds((const unsigned*)((const char*)(gbase) + (voff)[_i]), (PG8_LAS unsigned*)(lds + (bufoff) + ldsw + _i * 8192), 16, 0, 0); } while (0)
; #define PG8_LDA(dst, b, h) do { _Pragma("unroll") for (int m = 0; m < 4; ++m) _Pragma("unroll") for (int k = 0; k < 2; ++k) dst[m][k] = *(const PG8_LAS bf16x8*)(lds + PG8_SA(b, h) + aoff + m * 2048 + k * 1024); } while (0)
; #define PG8_LDB(dst, b, h) do { _Pragma("unroll") for (int n = 0; n < 2; ++n) _Pragma("unroll") for (int k = 0; k < 2; ++k) dst[n][k] = *(const PG8_LAS bf16x8*)(lds + PG8_SB(b, h) + boff + n * 2048 + k * 1024); } while (0)
; #define PG8_MMA(ai, bj, At, Bt) do { __builtin_amdgcn_s_setprio(1); _Pragma("unroll") for (int m = 0; m < 4; ++m) _Pragma("unroll") for (int n = 0; n < 2; ++n) _Pragma("unroll") for (int k = 0; k < 2; ++k) \
;         acc[ai][bj][m][n] = __builtin_amdgcn_mfma_f32_16x16x32_bf16(Bt[n][k], At[m][k], acc[ai][bj][m][n], 0, 0, 0); __builtin_amdgcn_s_setprio(0); } while (0)
; #define PG8_WAIT_V(n) asm volatile("s_waitcnt vmcnt(" #n ")" ::: "memory")
; #define PG8_WAIT_L(n) asm volatile("s_waitcnt lgkmcnt(" #n ")" ::: "memory")
; #define PG8_BAR __builtin_amdgcn_s_barrier()
; #define PG8_SCHED __builtin_amdgcn_sched_barrier(0)
; template <class Epi, class Sched, bool ALIGN_EPI = false, bool SP2 = false>
; __device__ __forceinline__ void gemm_phase(PG8_LAS unsigned char* lds, const Gemm g, const Sched& S, const Epi& E, int tid_in) {
;     ...
;             PG8_LDB(B0, 1, 0); PG8_LDB(B1, 1, 1); PG8_SCHED; PG8_LDA(At, 1, 0); PG8_STAGE(PG8_SA(0, 1), a2 + hstepA, voffA);
;             PG8_WAIT_V(8); PG8_WAIT_L(0); PG8_BAR; PG8_MMA(0, 0, At, B0); PG8_MMA(0, 1, At, B1); PG8_BAR; PG8_SCHED;
	v_lshl_add_u64 v[228:229], s[30:31], 0, v[130:131]
	s_mov_b32 m0, s38
	s_nop 0
	global_load_lds_dwordx4 v[228:229], off
	s_mov_b32 m0, s39
	s_nop 0
	global_load_lds_dwordx4 v[240:241], off
	v_add_u32_e32 v150, s63, v157
	ds_read_b128 v[142:145], v150
	ds_read_b128 v[146:149], v150 offset:1024
	ds_read_b128 v[152:155], v150 offset:2048
	ds_read_b128 v[160:163], v150 offset:3072
	v_add_u32_e32 v150, s55, v157
	ds_read_b128 v[164:167], v150
	ds_read_b128 v[182:185], v150 offset:1024
	ds_read_b128 v[186:189], v150 offset:2048
	ds_read_b128 v[190:193], v150 offset:3072
	s_add_u32 s30, s30, 0x80000
	s_addc_u32 s31, s31, 0
	s_mov_b32 m0, s40
	v_lshl_add_u64 v[242:243], s[30:31], 0, v[130:131]
	ds_read_b128 v[194:197], v158 offset:32768
	ds_read_b128 v[198:201], v158 offset:33792
	ds_read_b128 v[202:205], v158 offset:34816
	ds_read_b128 v[206:209], v158 offset:35840
	ds_read_b128 v[210:213], v158 offset:36864
	ds_read_b128 v[214:217], v158 offset:37888
	ds_read_b128 v[218:221], v158 offset:38912
	ds_read_b128 v[222:225], v158 offset:39936
	global_load_lds_dwordx4 v[242:243], off
	v_lshl_add_u64 v[242:243], s[30:31], 0, v[132:133]
	s_mov_b32 m0, s41
	s_nop 0
	global_load_lds_dwordx4 v[242:243], off
	s_waitcnt vmcnt(8)
	s_waitcnt lgkmcnt(0)
	s_barrier
	s_setprio 1
	s_waitcnt lgkmcnt(0)
	v_mfma_f32_16x16x32_bf16 v[126:129], v[142:145], v[194:197], v[126:129]
	v_mfma_f32_16x16x32_bf16 v[122:125], v[152:155], v[194:197], v[122:125]
	v_mfma_f32_16x16x32_bf16 v[110:113], v[142:145], v[202:205], v[110:113]
	v_mfma_f32_16x16x32_bf16 v[106:109], v[152:155], v[202:205], v[106:109]
	v_mfma_f32_16x16x32_bf16 v[94:97], v[142:145], v[210:213], v[94:97]
	v_mfma_f32_16x16x32_bf16 v[90:93], v[152:155], v[210:213], v[90:93]
	v_mfma_f32_16x16x32_bf16 v[78:81], v[142:145], v[218:221], v[78:81]
	v_mfma_f32_16x16x32_bf16 v[74:77], v[152:155], v[218:221], v[74:77]
	v_mfma_f32_16x16x32_bf16 v[126:129], v[146:149], v[198:201], v[126:129]
	v_mfma_f32_16x16x32_bf16 v[122:125], v[160:163], v[198:201], v[122:125]
	v_mfma_f32_16x16x32_bf16 v[110:113], v[146:149], v[206:209], v[110:113]
	v_mfma_f32_16x16x32_bf16 v[106:109], v[160:163], v[206:209], v[106:109]
	v_mfma_f32_16x16x32_bf16 v[94:97], v[146:149], v[214:217], v[94:97]
	v_mfma_f32_16x16x32_bf16 v[90:93], v[160:163], v[214:217], v[90:93]
	v_mfma_f32_16x16x32_bf16 v[78:81], v[146:149], v[222:225], v[78:81]
	v_mfma_f32_16x16x32_bf16 v[74:77], v[160:163], v[222:225], v[74:77]
	s_setprio 0
	s_setprio 1
	v_mfma_f32_16x16x32_bf16 v[118:121], v[164:167], v[194:197], v[118:121]
	v_mfma_f32_16x16x32_bf16 v[114:117], v[186:189], v[194:197], v[114:117]
	v_mfma_f32_16x16x32_bf16 v[102:105], v[164:167], v[202:205], v[102:105]
	v_mfma_f32_16x16x32_bf16 v[98:101], v[186:189], v[202:205], v[98:101]
	v_mfma_f32_16x16x32_bf16 v[86:89], v[164:167], v[210:213], v[86:89]
	v_mfma_f32_16x16x32_bf16 v[82:85], v[186:189], v[210:213], v[82:85]
	v_mfma_f32_16x16x32_bf16 v[70:73], v[164:167], v[218:221], v[70:73]
	v_mfma_f32_16x16x32_bf16 v[66:69], v[186:189], v[218:221], v[66:69]
	v_mfma_f32_16x16x32_bf16 v[118:121], v[182:185], v[198:201], v[118:121]
	v_mfma_f32_16x16x32_bf16 v[114:117], v[190:193], v[198:201], v[114:117]
	v_mfma_f32_16x16x32_bf16 v[102:105], v[182:185], v[206:209], v[102:105]
	v_mfma_f32_16x16x32_bf16 v[98:101], v[190:193], v[206:209], v[98:101]
	v_mfma_f32_16x16x32_bf16 v[86:89], v[182:185], v[214:217], v[86:89]
	v_mfma_f32_16x16x32_bf16 v[82:85], v[190:193], v[214:217], v[82:85]
	v_mfma_f32_16x16x32_bf16 v[70:73], v[182:185], v[222:225], v[70:73]
	v_mfma_f32_16x16x32_bf16 v[66:69], v[190:193], v[222:225], v[66:69]
	s_setprio 0
	s_barrier
; #define PG8_STAGE(bufoff, gbase, voff) do { _Pragma("unroll") for (int _i = 0; _i < 2; ++_i) \
;         __builtin_amdgcn_global_load_lds((const unsigned*)((const char*)(gbase) + (voff)[_i]), (PG8_LAS unsigned*)(lds + (bufoff) + ldsw + _i * 8192), 16, 0, 0); } while (0)
; #define PG8_LDA(dst, b, h) do { _Pragma("unroll") for (int m = 0; m < 4; ++m) _Pragma("unroll") for (int k = 0; k < 2; ++k) dst[m][k] = *(const PG8_LAS bf16x8*)(lds + PG8_SA(b, h) + aoff + m * 2048 + k * 1024); } while (0)
; #define PG8_MMA(ai, bj, At, Bt) do { __builtin_amdgcn_s_setprio(1); _Pragma("unroll") for (int m = 0; m < 4; ++m) _Pragma("unroll") for (int n = 0; n < 2; ++n) _Pragma("unroll") for (int k = 0; k < 2; ++k) \
;         acc[ai][bj][m][n] = __builtin_amdgcn_mfma_f32_16x16x32_bf16(Bt[n][k], At[m][k], acc[ai][bj][m][n], 0, 0, 0); __builtin_amdgcn_s_setprio(0); } while (0)
; #define PG8_WAIT_V(n) asm volatile("s_waitcnt vmcnt(" #n ")" ::: "memory")
; #define PG8_WAIT_L(n) asm volatile("s_waitcnt lgkmcnt(" #n ")" ::: "memory")
; #define PG8_BAR __builtin_amdgcn_s_barrier()
; #define PG8_SCHED __builtin_amdgcn_sched_barrier(0)
; template <class Epi, class Sched, bool ALIGN_EPI = false, bool SP2 = false>
; __device__ __forceinline__ void gemm_phase(PG8_LAS unsigned char* lds, const Gemm g, const Sched& S, const Epi& E, int tid_in) {
;     ...
;             PG8_LDA(At, 1, 1); PG8_STAGE(PG8_SB(1, 0), b3, voffB); PG8_STAGE(PG8_SB(1, 1), b3 + hstep, voffB); PG8_STAGE(PG8_SA(1, 0), a3, voffA);
;             PG8_WAIT_V(8); PG8_WAIT_L(0); PG8_BAR; PG8_MMA(1, 0, At, B0); PG8_MMA(1, 1, At, B1); PG8_BAR; PG8_SCHED;
	s_add_i32 s30, s63, s37
	v_lshl_add_u64 v[168:169], v[168:169], 0, s[90:91]
	s_mov_b32 m0, s30
	ds_read_b128 v[194:197], v158 offset:49152
	ds_read_b128 v[198:201], v158 offset:50176
	ds_read_b128 v[202:205], v158 offset:51200
	ds_read_b128 v[206:209], v158 offset:52224
	ds_read_b128 v[210:213], v158 offset:53248
	ds_read_b128 v[214:217], v158 offset:54272
	ds_read_b128 v[218:221], v158 offset:55296
	ds_read_b128 v[222:225], v158 offset:56320
	global_load_lds_dwordx4 v[168:169], off
	s_add_i32 m0, s30, 0x2000
	s_add_u32 s28, s28, 0x80080
	v_lshl_add_u64 v[168:169], v[226:227], 0, s[90:91]
	s_addc_u32 s29, s29, 0
	s_add_i32 s30, s55, s37
	global_load_lds_dwordx4 v[168:169], off
	v_lshl_add_u64 v[168:169], s[28:29], 0, v[0:1]
	s_mov_b32 m0, s30
	s_nop 0
	global_load_lds_dwordx4 v[168:169], off
	v_lshl_add_u64 v[168:169], s[28:29], 0, v[134:135]
	s_add_i32 m0, s30, 0x2000
	s_nop 0
	global_load_lds_dwordx4 v[168:169], off
	v_lshl_add_u64 v[228:229], v[228:229], 0, s[90:91]
	v_lshl_add_u64 v[240:241], v[240:241], 0, s[90:91]
	s_add_i32 s23, s23, 2
	s_add_u32 s14, s14, 0x100
	s_addc_u32 s15, s15, 0
	s_add_u32 s13, s13, 0x100
	s_addc_u32 s21, s21, 0
	s_cmp_gt_u32 s23, 29
	s_waitcnt vmcnt(6)
	s_waitcnt lgkmcnt(0)
	s_barrier
	s_setprio 1
	s_waitcnt lgkmcnt(0)
	v_mfma_f32_16x16x32_bf16 v[62:65], v[142:145], v[194:197], v[62:65]
	v_mfma_f32_16x16x32_bf16 v[58:61], v[152:155], v[194:197], v[58:61]
	v_mfma_f32_16x16x32_bf16 v[46:49], v[142:145], v[202:205], v[46:49]
	v_mfma_f32_16x16x32_bf16 v[42:45], v[152:155], v[202:205], v[42:45]
	v_mfma_f32_16x16x32_bf16 v[30:33], v[142:145], v[210:213], v[30:33]
	v_mfma_f32_16x16x32_bf16 v[26:29], v[152:155], v[210:213], v[26:29]
	v_mfma_f32_16x16x32_bf16 v[14:17], v[142:145], v[218:221], v[14:17]
	v_mfma_f32_16x16x32_bf16 v[10:13], v[152:155], v[218:221], v[10:13]
	v_mfma_f32_16x16x32_bf16 v[62:65], v[146:149], v[198:201], v[62:65]
	v_mfma_f32_16x16x32_bf16 v[58:61], v[160:163], v[198:201], v[58:61]
	v_mfma_f32_16x16x32_bf16 v[46:49], v[146:149], v[206:209], v[46:49]
	v_mfma_f32_16x16x32_bf16 v[42:45], v[160:163], v[206:209], v[42:45]
	v_mfma_f32_16x16x32_bf16 v[30:33], v[146:149], v[214:217], v[30:33]
	v_mfma_f32_16x16x32_bf16 v[26:29], v[160:163], v[214:217], v[26:29]
	v_mfma_f32_16x16x32_bf16 v[14:17], v[146:149], v[222:225], v[14:17]
	v_mfma_f32_16x16x32_bf16 v[10:13], v[160:163], v[222:225], v[10:13]
	s_setprio 0
	s_setprio 1
	v_mfma_f32_16x16x32_bf16 v[54:57], v[164:167], v[194:197], v[54:57]
	v_mfma_f32_16x16x32_bf16 v[50:53], v[186:189], v[194:197], v[50:53]
	v_mfma_f32_16x16x32_bf16 v[38:41], v[164:167], v[202:205], v[38:41]
	v_mfma_f32_16x16x32_bf16 v[34:37], v[186:189], v[202:205], v[34:37]
	v_mfma_f32_16x16x32_bf16 v[22:25], v[164:167], v[210:213], v[22:25]
	v_mfma_f32_16x16x32_bf16 v[18:21], v[186:189], v[210:213], v[18:21]
	v_mfma_f32_16x16x32_bf16 v[6:9], v[164:167], v[218:221], v[6:9]
	v_mfma_f32_16x16x32_bf16 v[2:5], v[186:189], v[218:221], v[2:5]
	v_mfma_f32_16x16x32_bf16 v[54:57], v[182:185], v[198:201], v[54:57]
	v_mfma_f32_16x16x32_bf16 v[50:53], v[190:193], v[198:201], v[50:53]
	v_mfma_f32_16x16x32_bf16 v[38:41], v[182:185], v[206:209], v[38:41]
	v_mfma_f32_16x16x32_bf16 v[34:37], v[190:193], v[206:209], v[34:37]
	v_mfma_f32_16x16x32_bf16 v[22:25], v[182:185], v[214:217], v[22:25]
	v_mfma_f32_16x16x32_bf16 v[18:21], v[190:193], v[214:217], v[18:21]
	v_mfma_f32_16x16x32_bf16 v[6:9], v[182:185], v[222:225], v[6:9]
	v_mfma_f32_16x16x32_bf16 v[2:5], v[190:193], v[222:225], v[2:5]
	s_setprio 0
	s_barrier
	s_cbranch_scc0 .Lbal_top_513
	s_mov_b32 m0, s45
	s_nop 0
	global_load_lds_dwordx4 v[228:229], off
	s_mov_b32 m0, s48
	s_nop 0
	global_load_lds_dwordx4 v[240:241], off
	s_and_b64 vcc, exec, s[18:19]
	s_cbranch_vccz .LBB0_516
	s_barrier

; #define PG8_STAGE(bufoff, gbase, voff) do { _Pragma("unroll") for (int _i = 0; _i < 2; ++_i) \
;         __builtin_amdgcn_global_load_lds((const unsigned*)((const char*)(gbase) + (voff)[_i]), (PG8_LAS unsigned*)(lds + (bufoff) + ldsw + _i * 8192), 16, 0, 0); } while (0)
; #define PG8_LDA(dst, b, h) do { _Pragma("unroll") for (int m = 0; m < 4; ++m) _Pragma("unroll") for (int k = 0; k < 2; ++k) dst[m][k] = *(const PG8_LAS bf16x8*)(lds + PG8_SA(b, h) + aoff + m * 2048 + k * 1024); } while (0)
; #define PG8_LDB(dst, b, h) do { _Pragma("unroll") for (int n = 0; n < 2; ++n) _Pragma("unroll") for (int k = 0; k < 2; ++k) dst[n][k] = *(const PG8_LAS bf16x8*)(lds + PG8_SB(b, h) + boff + n * 2048 + k * 1024); } while (0)
; #define PG8_MMA(ai, bj, At, Bt) do { __builtin_amdgcn_s_setprio(1); _Pragma("unroll") for (int m = 0; m < 4; ++m) _Pragma("unroll") for (int n = 0; n < 2; ++n) _Pragma("unroll") for (int k = 0; k < 2; ++k) \
;         acc[ai][bj][m][n] = __builtin_amdgcn_mfma_f32_16x16x32_bf16(Bt[n][k], At[m][k], acc[ai][bj][m][n], 0, 0, 0); __builtin_amdgcn_s_setprio(0); } while (0)
; #define PG8_WAIT_V(n) asm volatile("s_waitcnt vmcnt(" #n ")" ::: "memory")
; #define PG8_BAR __builtin_amdgcn_s_barrier()
; template <class Epi, class Sched, bool ALIGN_EPI = false, bool SP2 = false>
; __device__ __forceinline__ void gemm_phase(PG8_LAS unsigned char* lds, const Gemm g, const Sched& S, const Epi& E, int tid_in) {
;     ...
;         for (int t = 0; t < nt; t += 2) {
;             const bool last = (t == nt - 2);
;             const char* a1 = cA + (size_t)(t + 1) * kstep;
;             const char* a2 = last ? nA : cA + (size_t)(t + 2) * kstep; const char* b2 = last ? nB : cB + (size_t)(t + 2) * kstep;
;             const char* a3 = a2 + kstep; const char* b3 = b2 + kstep;
;             if (last && has_next) S.a_ready(nxt);
;             if constexpr (SP2) {
;             PG8_LDB(B0, 0, 0); PG8_LDB(B1, 0, 1); PG8_SCHED; PG8_LDA(At, 0, 0); PG8_STAGE(PG8_SA(1, 1), a1 + hstepA, voffA);
;             PG8_WAIT_V(8); PG8_WAIT_L(0); PG8_BAR; PG8_MMA(0, 0, At, B0); PG8_MMA(0, 1, At, B1); PG8_BAR; PG8_SCHED;
;     ...
;         for (int a = 0; a < 2; ++a)
; #pragma unroll
;             for (int b = 0; b < 2; ++b)
; #pragma unroll
;                 for (int m = 0; m < 4; ++m)
; #pragma unroll
;                     for (int n = 0; n < 2; ++n) acc[a][b][m][n] = (f32x4){0.f, 0.f, 0.f, 0.f};
.LBB0_626:
	s_add_u32 s0, s22, 0x100
	v_mov_b32_e32 v2, 0
	s_addc_u32 s15, s23, 0
	s_mov_b32 s48, -2
	v_mov_b32_e32 v3, v2
	v_mov_b32_e32 v4, v2
	v_mov_b32_e32 v5, v2
	v_mov_b32_e32 v6, v2
	v_mov_b32_e32 v7, v2
	v_mov_b32_e32 v8, v2
	v_mov_b32_e32 v9, v2
	v_mov_b32_e32 v14, v2
	v_mov_b32_e32 v15, v2
	v_mov_b32_e32 v16, v2
	v_mov_b32_e32 v17, v2
	v_mov_b32_e32 v22, v2
	v_mov_b32_e32 v23, v2
	v_mov_b32_e32 v24, v2
	v_mov_b32_e32 v25, v2
	v_mov_b32_e32 v30, v2
	v_mov_b32_e32 v31, v2
	v_mov_b32_e32 v32, v2
	v_mov_b32_e32 v33, v2
	v_mov_b32_e32 v38, v2
	v_mov_b32_e32 v39, v2
	v_mov_b32_e32 v40, v2
	v_mov_b32_e32 v41, v2
	v_mov_b32_e32 v46, v2
	v_mov_b32_e32 v47, v2
	v_mov_b32_e32 v48, v2
	v_mov_b32_e32 v49, v2
	v_mov_b32_e32 v54, v2
	v_mov_b32_e32 v55, v2
	v_mov_b32_e32 v56, v2
	v_mov_b32_e32 v57, v2
	v_mov_b32_e32 v10, v2
	v_mov_b32_e32 v11, v2
	v_mov_b32_e32 v12, v2
	v_mov_b32_e32 v13, v2
	v_mov_b32_e32 v18, v2
	v_mov_b32_e32 v19, v2
	v_mov_b32_e32 v20, v2
	v_mov_b32_e32 v21, v2
	v_mov_b32_e32 v26, v2
	v_mov_b32_e32 v27, v2
	v_mov_b32_e32 v28, v2
	v_mov_b32_e32 v29, v2
	v_mov_b32_e32 v34, v2
	v_mov_b32_e32 v35, v2
	v_mov_b32_e32 v36, v2
	v_mov_b32_e32 v37, v2
	v_mov_b32_e32 v42, v2
	v_mov_b32_e32 v43, v2
	v_mov_b32_e32 v44, v2
	v_mov_b32_e32 v45, v2
	v_mov_b32_e32 v50, v2
	v_mov_b32_e32 v51, v2
	v_mov_b32_e32 v52, v2
	v_mov_b32_e32 v53, v2
	v_mov_b32_e32 v58, v2
	v_mov_b32_e32 v59, v2
	v_mov_b32_e32 v60, v2
	v_mov_b32_e32 v61, v2
	v_mov_b32_e32 v62, v2
	v_mov_b32_e32 v63, v2
	v_mov_b32_e32 v64, v2
	v_mov_b32_e32 v65, v2
	v_mov_b32_e32 v66, v2
	v_mov_b32_e32 v67, v2
	v_mov_b32_e32 v68, v2
	v_mov_b32_e32 v69, v2
	v_mov_b32_e32 v70, v2
	v_mov_b32_e32 v71, v2
	v_mov_b32_e32 v72, v2
	v_mov_b32_e32 v73, v2
	v_mov_b32_e32 v78, v2
	v_mov_b32_e32 v79, v2
	v_mov_b32_e32 v80, v2
	v_mov_b32_e32 v81, v2
	v_mov_b32_e32 v86, v2
	v_mov_b32_e32 v87, v2
	v_mov_b32_e32 v88, v2
	v_mov_b32_e32 v89, v2
	v_mov_b32_e32 v94, v2
	v_mov_b32_e32 v95, v2
	v_mov_b32_e32 v96, v2
	v_mov_b32_e32 v97, v2
	v_mov_b32_e32 v102, v2
	v_mov_b32_e32 v103, v2
	v_mov_b32_e32 v104, v2
	v_mov_b32_e32 v105, v2
	v_mov_b32_e32 v110, v2
	v_mov_b32_e32 v111, v2
	v_mov_b32_e32 v112, v2
	v_mov_b32_e32 v113, v2
	v_mov_b32_e32 v118, v2
	v_mov_b32_e32 v119, v2
	v_mov_b32_e32 v120, v2
	v_mov_b32_e32 v121, v2
	v_mov_b32_e32 v74, v2
	v_mov_b32_e32 v75, v2
	v_mov_b32_e32 v76, v2
	v_mov_b32_e32 v77, v2
	v_mov_b32_e32 v82, v2
	v_mov_b32_e32 v83, v2
	v_mov_b32_e32 v84, v2
	v_mov_b32_e32 v85, v2
	v_mov_b32_e32 v90, v2
	v_mov_b32_e32 v91, v2
	v_mov_b32_e32 v92, v2
	v_mov_b32_e32 v93, v2
	v_mov_b32_e32 v98, v2
	v_mov_b32_e32 v99, v2
	v_mov_b32_e32 v100, v2
	v_mov_b32_e32 v101, v2
	v_mov_b32_e32 v106, v2
	v_mov_b32_e32 v107, v2
	v_mov_b32_e32 v108, v2
	v_mov_b32_e32 v109, v2
	v_mov_b32_e32 v114, v2
	v_mov_b32_e32 v115, v2
	v_mov_b32_e32 v116, v2
	v_mov_b32_e32 v117, v2
	v_mov_b32_e32 v122, v2
	v_mov_b32_e32 v123, v2
	v_mov_b32_e32 v124, v2
	v_mov_b32_e32 v125, v2
	v_mov_b32_e32 v126, v2
	v_mov_b32_e32 v127, v2
	v_mov_b32_e32 v128, v2
	v_mov_b32_e32 v129, v2
	s_branch .LBB0_627
.Lbal_top_627:
	s_mov_b32 m0, s42
	s_nop 0
	global_load_lds_dwordx4 v[228:229], off
	s_mov_b32 m0, s43
	s_nop 0
	global_load_lds_dwordx4 v[240:241], off
.LBB0_627:
	v_add_u32_e32 v140, s4, v145
	ds_read_b128 v[148:151], v140
	ds_read_b128 v[152:155], v140 offset:1024
	ds_read_b128 v[156:159], v140 offset:2048
	ds_read_b128 v[160:163], v140 offset:3072
	v_add_u32_e32 v140, s5, v145
	ds_read_b128 v[164:167], v140
	ds_read_b128 v[182:185], v140 offset:1024
	ds_read_b128 v[186:189], v140 offset:2048
	ds_read_b128 v[190:193], v140 offset:3072
	s_add_u32 s22, s20, 0x100
	s_addc_u32 s23, s21, 0
	s_cmp_eq_u32 s48, 4
	s_cselect_b32 s27, s17, s23
	s_cselect_b32 s26, s16, s22
	s_cselect_b32 s25, s19, s15
	s_cselect_b32 s24, s18, s0
	v_lshl_add_u64 v[168:169], s[20:21], 0, v[136:137]
	s_add_i32 m0, s34, 0xc000
	ds_read_b128 v[194:197], v147
	ds_read_b128 v[198:201], v147 offset:1024
	ds_read_b128 v[202:205], v147 offset:2048
	ds_read_b128 v[206:209], v147 offset:3072
	ds_read_b128 v[210:213], v147 offset:4096
	ds_read_b128 v[214:217], v147 offset:5120
	ds_read_b128 v[218:221], v147 offset:6144
	ds_read_b128 v[222:225], v147 offset:7168
	global_load_lds_dwordx4 v[168:169], off
	v_lshl_add_u64 v[168:169], s[20:21], 0, v[138:139]
	s_add_i32 m0, s34, 0xe000
	s_nop 0
	global_load_lds_dwordx4 v[168:169], off
	s_waitcnt vmcnt(8)
	s_waitcnt lgkmcnt(0)
	s_barrier
	s_setprio 1
	s_waitcnt lgkmcnt(0)
	v_mfma_f32_16x16x32_bf16 v[126:129], v[148:151], v[194:197], v[126:129]
	v_mfma_f32_16x16x32_bf16 v[122:125], v[156:159], v[194:197], v[122:125]
	v_mfma_f32_16x16x32_bf16 v[114:117], v[148:151], v[202:205], v[114:117]
	v_mfma_f32_16x16x32_bf16 v[106:109], v[156:159], v[202:205], v[106:109]
	v_mfma_f32_16x16x32_bf16 v[98:101], v[148:151], v[210:213], v[98:101]
	v_mfma_f32_16x16x32_bf16 v[90:93], v[156:159], v[210:213], v[90:93]
	v_mfma_f32_16x16x32_bf16 v[82:85], v[148:151], v[218:221], v[82:85]
	v_mfma_f32_16x16x32_bf16 v[74:77], v[156:159], v[218:221], v[74:77]
	v_mfma_f32_16x16x32_bf16 v[126:129], v[152:155], v[198:201], v[126:129]
	v_mfma_f32_16x16x32_bf16 v[122:125], v[160:163], v[198:201], v[122:125]
	v_mfma_f32_16x16x32_bf16 v[114:117], v[152:155], v[206:209], v[114:117]
	v_mfma_f32_16x16x32_bf16 v[106:109], v[160:163], v[206:209], v[106:109]
	v_mfma_f32_16x16x32_bf16 v[98:101], v[152:155], v[214:217], v[98:101]
	v_mfma_f32_16x16x32_bf16 v[90:93], v[160:163], v[214:217], v[90:93]
	v_mfma_f32_16x16x32_bf16 v[82:85], v[152:155], v[222:225], v[82:85]
	v_mfma_f32_16x16x32_bf16 v[74:77], v[160:163], v[222:225], v[74:77]
	s_setprio 0
	s_setprio 1
	v_mfma_f32_16x16x32_bf16 v[118:121], v[164:167], v[194:197], v[118:121]
	v_mfma_f32_16x16x32_bf16 v[110:113], v[186:189], v[194:197], v[110:113]
	v_mfma_f32_16x16x32_bf16 v[102:105], v[164:167], v[202:205], v[102:105]
	v_mfma_f32_16x16x32_bf16 v[94:97], v[186:189], v[202:205], v[94:97]
	v_mfma_f32_16x16x32_bf16 v[86:89], v[164:167], v[210:213], v[86:89]
	v_mfma_f32_16x16x32_bf16 v[78:81], v[186:189], v[210:213], v[78:81]
	v_mfma_f32_16x16x32_bf16 v[70:73], v[164:167], v[218:221], v[70:73]
	v_mfma_f32_16x16x32_bf16 v[66:69], v[186:189], v[218:221], v[66:69]
	v_mfma_f32_16x16x32_bf16 v[118:121], v[182:185], v[198:201], v[118:121]
	v_mfma_f32_16x16x32_bf16 v[110:113], v[190:193], v[198:201], v[110:113]
	v_mfma_f32_16x16x32_bf16 v[102:105], v[182:185], v[206:209], v[102:105]
	v_mfma_f32_16x16x32_bf16 v[94:97], v[190:193], v[206:209], v[94:97]
	v_mfma_f32_16x16x32_bf16 v[86:89], v[182:185], v[214:217], v[86:89]
	v_mfma_f32_16x16x32_bf16 v[78:81], v[190:193], v[214:217], v[78:81]
	v_mfma_f32_16x16x32_bf16 v[70:73], v[182:185], v[222:225], v[70:73]
	v_mfma_f32_16x16x32_bf16 v[66:69], v[190:193], v[222:225], v[66:69]
	s_setprio 0
	s_barrier
; #define PG8_STAGE(bufoff, gbase, voff) do { _Pragma("unroll") for (int _i = 0; _i < 2; ++_i) \
;         __builtin_amdgcn_global_load_lds((const unsigned*)((const char*)(gbase) + (voff)[_i]), (PG8_LAS unsigned*)(lds + (bufoff) + ldsw + _i * 8192), 16, 0, 0); } while (0)
; #define PG8_LDA(dst, b, h) do { _Pragma("unroll") for (int m = 0; m < 4; ++m) _Pragma("unroll") for (int k = 0; k < 2; ++k) dst[m][k] = *(const PG8_LAS bf16x8*)(lds + PG8_SA(b, h) + aoff + m * 2048 + k * 1024); } while (0)
; #define PG8_LDB(dst, b, h) do { _Pragma("unroll") for (int n = 0; n < 2; ++n) _Pragma("unroll") for (int k = 0; k < 2; ++k) dst[n][k] = *(const PG8_LAS bf16x8*)(lds + PG8_SB(b, h) + boff + n * 2048 + k * 1024); } while (0)
; #define PG8_MMA(ai, bj, At, Bt) do { __builtin_amdgcn_s_setprio(1); _Pragma("unroll") for (int m = 0; m < 4; ++m) _Pragma("unroll") for (int n = 0; n < 2; ++n) _Pragma("unroll") for (int k = 0; k < 2; ++k) \
;         acc[ai][bj][m][n] = __builtin_amdgcn_mfma_f32_16x16x32_bf16(Bt[n][k], At[m][k], acc[ai][bj][m][n], 0, 0, 0); __builtin_amdgcn_s_setprio(0); } while (0)
; #define PG8_WAIT_V(n) asm volatile("s_waitcnt vmcnt(" #n ")" ::: "memory")
; #define PG8_WAIT_L(n) asm volatile("s_waitcnt lgkmcnt(" #n ")" ::: "memory")
; #define PG8_BAR __builtin_amdgcn_s_barrier()
; #define PG8_SCHED __builtin_amdgcn_sched_barrier(0)
; template <class Epi, class Sched, bool ALIGN_EPI = false, bool SP2 = false>
; __device__ __forceinline__ void gemm_phase(PG8_LAS unsigned char* lds, const Gemm g, const Sched& S, const Epi& E, int tid_in) {
;     ...
;             PG8_LDA(At, 0, 1); PG8_STAGE(PG8_SB(0, 0), b2, voffB); PG8_STAGE(PG8_SB(0, 1), b2 + hstep, voffB); PG8_STAGE(PG8_SA(0, 0), a2, voffA);
;             PG8_WAIT_V(8); PG8_WAIT_L(0); PG8_BAR; PG8_MMA(1, 0, At, B0); PG8_MMA(1, 1, At, B1); PG8_BAR; PG8_SCHED;
;             PG8_LDB(B0, 1, 0); PG8_LDB(B1, 1, 1); PG8_SCHED; PG8_LDA(At, 1, 0); PG8_STAGE(PG8_SA(0, 1), a2 + hstepA, voffA);
;             PG8_WAIT_V(8); PG8_WAIT_L(0); PG8_BAR; PG8_MMA(0, 0, At, B0); PG8_MMA(0, 1, At, B1); PG8_BAR; PG8_SCHED;
	s_add_i32 s20, s4, s33
	v_lshl_add_u64 v[168:169], s[24:25], 0, v[0:1]
	s_mov_b32 m0, s20
	ds_read_b128 v[194:197], v147 offset:16384
	ds_read_b128 v[198:201], v147 offset:17408
	ds_read_b128 v[202:205], v147 offset:18432
	ds_read_b128 v[206:209], v147 offset:19456
	ds_read_b128 v[210:213], v147 offset:20480
	ds_read_b128 v[214:217], v147 offset:21504
	ds_read_b128 v[218:221], v147 offset:22528
	ds_read_b128 v[222:225], v147 offset:23552
	global_load_lds_dwordx4 v[168:169], off
	s_add_i32 m0, s20, 0x2000
	s_add_u32 s20, s24, 0x20000
	v_lshl_add_u64 v[226:227], s[24:25], 0, v[134:135]
	s_addc_u32 s21, s25, 0
	s_add_i32 s49, s5, s33
	global_load_lds_dwordx4 v[226:227], off
	v_lshl_add_u64 v[228:229], s[20:21], 0, v[0:1]
	s_mov_b32 m0, s49
	v_lshl_add_u64 v[240:241], s[26:27], 0, v[132:133]
	global_load_lds_dwordx4 v[228:229], off
	v_lshl_add_u64 v[228:229], s[20:21], 0, v[134:135]
	s_add_i32 m0, s49, 0x2000
	s_nop 0
	global_load_lds_dwordx4 v[228:229], off
	s_waitcnt vmcnt(6)
	s_waitcnt lgkmcnt(0)
	s_barrier
	s_setprio 1
	s_waitcnt lgkmcnt(0)
	v_mfma_f32_16x16x32_bf16 v[62:65], v[148:151], v[194:197], v[62:65]
	v_mfma_f32_16x16x32_bf16 v[58:61], v[156:159], v[194:197], v[58:61]
	v_mfma_f32_16x16x32_bf16 v[50:53], v[148:151], v[202:205], v[50:53]
	v_mfma_f32_16x16x32_bf16 v[42:45], v[156:159], v[202:205], v[42:45]
	v_mfma_f32_16x16x32_bf16 v[34:37], v[148:151], v[210:213], v[34:37]
	v_mfma_f32_16x16x32_bf16 v[26:29], v[156:159], v[210:213], v[26:29]
	v_mfma_f32_16x16x32_bf16 v[18:21], v[148:151], v[218:221], v[18:21]
	v_mfma_f32_16x16x32_bf16 v[10:13], v[156:159], v[218:221], v[10:13]
	v_mfma_f32_16x16x32_bf16 v[62:65], v[152:155], v[198:201], v[62:65]
	v_mfma_f32_16x16x32_bf16 v[58:61], v[160:163], v[198:201], v[58:61]
	v_mfma_f32_16x16x32_bf16 v[50:53], v[152:155], v[206:209], v[50:53]
	v_mfma_f32_16x16x32_bf16 v[42:45], v[160:163], v[206:209], v[42:45]
	v_mfma_f32_16x16x32_bf16 v[34:37], v[152:155], v[214:217], v[34:37]
	v_mfma_f32_16x16x32_bf16 v[26:29], v[160:163], v[214:217], v[26:29]
	v_mfma_f32_16x16x32_bf16 v[18:21], v[152:155], v[222:225], v[18:21]
	v_mfma_f32_16x16x32_bf16 v[10:13], v[160:163], v[222:225], v[10:13]
	s_setprio 0
	s_setprio 1
	v_mfma_f32_16x16x32_bf16 v[54:57], v[164:167], v[194:197], v[54:57]
	v_mfma_f32_16x16x32_bf16 v[46:49], v[186:189], v[194:197], v[46:49]
	v_mfma_f32_16x16x32_bf16 v[38:41], v[164:167], v[202:205], v[38:41]
	v_mfma_f32_16x16x32_bf16 v[30:33], v[186:189], v[202:205], v[30:33]
	v_mfma_f32_16x16x32_bf16 v[22:25], v[164:167], v[210:213], v[22:25]
	v_mfma_f32_16x16x32_bf16 v[14:17], v[186:189], v[210:213], v[14:17]
	v_mfma_f32_16x16x32_bf16 v[6:9], v[164:167], v[218:221], v[6:9]
	v_mfma_f32_16x16x32_bf16 v[2:5], v[186:189], v[218:221], v[2:5]
	v_mfma_f32_16x16x32_bf16 v[54:57], v[182:185], v[198:201], v[54:57]
	v_mfma_f32_16x16x32_bf16 v[46:49], v[190:193], v[198:201], v[46:49]
	v_mfma_f32_16x16x32_bf16 v[38:41], v[182:185], v[206:209], v[38:41]
	v_mfma_f32_16x16x32_bf16 v[30:33], v[190:193], v[206:209], v[30:33]
	v_mfma_f32_16x16x32_bf16 v[22:25], v[182:185], v[214:217], v[22:25]
	v_mfma_f32_16x16x32_bf16 v[14:17], v[190:193], v[214:217], v[14:17]
	v_mfma_f32_16x16x32_bf16 v[6:9], v[182:185], v[222:225], v[6:9]
	v_mfma_f32_16x16x32_bf16 v[2:5], v[190:193], v[222:225], v[2:5]
	s_setprio 0
	s_barrier
	v_lshl_add_u64 v[228:229], s[26:27], 0, v[130:131]
	s_mov_b32 m0, s34
	s_nop 0
	global_load_lds_dwordx4 v[228:229], off
	s_mov_b32 m0, s35
	s_nop 0
	global_load_lds_dwordx4 v[240:241], off
	v_add_u32_e32 v140, s63, v145
	ds_read_b128 v[148:151], v140
	ds_read_b128 v[152:155], v140 offset:1024
	ds_read_b128 v[156:159], v140 offset:2048
	ds_read_b128 v[160:163], v140 offset:3072
	v_add_u32_e32 v140, s55, v145
	ds_read_b128 v[164:167], v140
	ds_read_b128 v[182:185], v140 offset:1024
	ds_read_b128 v[186:189], v140 offset:2048
	ds_read_b128 v[190:193], v140 offset:3072
	s_add_u32 s20, s26, 0x2e0000
	s_addc_u32 s21, s27, 0
	s_mov_b32 m0, s36
	v_lshl_add_u64 v[242:243], s[20:21], 0, v[130:131]
	ds_read_b128 v[194:197], v147 offset:32768
	ds_read_b128 v[198:201], v147 offset:33792
	ds_read_b128 v[202:205], v147 offset:34816
	ds_read_b128 v[206:209], v147 offset:35840
	ds_read_b128 v[210:213], v147 offset:36864
	ds_read_b128 v[214:217], v147 offset:37888
	ds_read_b128 v[218:221], v147 offset:38912
	ds_read_b128 v[222:225], v147 offset:39936
	global_load_lds_dwordx4 v[242:243], off
	v_lshl_add_u64 v[242:243], s[20:21], 0, v[132:133]
	s_mov_b32 m0, s37
	s_nop 0
	global_load_lds_dwordx4 v[242:243], off
	s_waitcnt vmcnt(8)
	s_waitcnt lgkmcnt(0)
	s_barrier
; #define PG8_STAGE(bufoff, gbase, voff) do { _Pragma("unroll") for (int _i = 0; _i < 2; ++_i) \
;         __builtin_amdgcn_global_load_lds((const unsigned*)((const char*)(gbase) + (voff)[_i]), (PG8_LAS unsigned*)(lds + (bufoff) + ldsw + _i * 8192), 16, 0, 0); } while (0)
; #define PG8_LDA(dst, b, h) do { _Pragma("unroll") for (int m = 0; m < 4; ++m) _Pragma("unroll") for (int k = 0; k < 2; ++k) dst[m][k] = *(const PG8_LAS bf16x8*)(lds + PG8_SA(b, h) + aoff + m * 2048 + k * 1024); } while (0)
; #define PG8_MMA(ai, bj, At, Bt) do { __builtin_amdgcn_s_setprio(1); _Pragma("unroll") for (int m = 0; m < 4; ++m) _Pragma("unroll") for (int n = 0; n < 2; ++n) _Pragma("unroll") for (int k = 0; k < 2; ++k) \
;         acc[ai][bj][m][n] = __builtin_amdgcn_mfma_f32_16x16x32_bf16(Bt[n][k], At[m][k], acc[ai][bj][m][n], 0, 0, 0); __builtin_amdgcn_s_setprio(0); } while (0)
; #define PG8_WAIT_V(n) asm volatile("s_waitcnt vmcnt(" #n ")" ::: "memory")
; #define PG8_WAIT_L(n) asm volatile("s_waitcnt lgkmcnt(" #n ")" ::: "memory")
; #define PG8_BAR __builtin_amdgcn_s_barrier()
; #define PG8_SCHED __builtin_amdgcn_sched_barrier(0)
; template <class Epi, class Sched, bool ALIGN_EPI = false, bool SP2 = false>
; __device__ __forceinline__ void gemm_phase(PG8_LAS unsigned char* lds, const Gemm g, const Sched& S, const Epi& E, int tid_in) {
;     ...
;             PG8_WAIT_V(8); PG8_WAIT_L(0); PG8_BAR; PG8_MMA(0, 0, At, B0); PG8_MMA(0, 1, At, B1); PG8_BAR; PG8_SCHED;
;             PG8_LDA(At, 1, 1); PG8_STAGE(PG8_SB(1, 0), b3, voffB); PG8_STAGE(PG8_SB(1, 1), b3 + hstep, voffB); PG8_STAGE(PG8_SA(1, 0), a3, voffA);
;             PG8_WAIT_V(8); PG8_WAIT_L(0); PG8_BAR; PG8_MMA(1, 0, At, B0); PG8_MMA(1, 1, At, B1); PG8_BAR; PG8_SCHED;
	s_setprio 1
	s_waitcnt lgkmcnt(0)
	v_mfma_f32_16x16x32_bf16 v[126:129], v[148:151], v[194:197], v[126:129]
	v_mfma_f32_16x16x32_bf16 v[122:125], v[156:159], v[194:197], v[122:125]
	v_mfma_f32_16x16x32_bf16 v[114:117], v[148:151], v[202:205], v[114:117]
	v_mfma_f32_16x16x32_bf16 v[106:109], v[156:159], v[202:205], v[106:109]
	v_mfma_f32_16x16x32_bf16 v[98:101], v[148:151], v[210:213], v[98:101]
	v_mfma_f32_16x16x32_bf16 v[90:93], v[156:159], v[210:213], v[90:93]
	v_mfma_f32_16x16x32_bf16 v[82:85], v[148:151], v[218:221], v[82:85]
	v_mfma_f32_16x16x32_bf16 v[74:77], v[156:159], v[218:221], v[74:77]
	v_mfma_f32_16x16x32_bf16 v[126:129], v[152:155], v[198:201], v[126:129]
	v_mfma_f32_16x16x32_bf16 v[122:125], v[160:163], v[198:201], v[122:125]
	v_mfma_f32_16x16x32_bf16 v[114:117], v[152:155], v[206:209], v[114:117]
	v_mfma_f32_16x16x32_bf16 v[106:109], v[160:163], v[206:209], v[106:109]
	v_mfma_f32_16x16x32_bf16 v[98:101], v[152:155], v[214:217], v[98:101]
	v_mfma_f32_16x16x32_bf16 v[90:93], v[160:163], v[214:217], v[90:93]
	v_mfma_f32_16x16x32_bf16 v[82:85], v[152:155], v[222:225], v[82:85]
	v_mfma_f32_16x16x32_bf16 v[74:77], v[160:163], v[222:225], v[74:77]
	s_setprio 0
	s_setprio 1
	v_mfma_f32_16x16x32_bf16 v[118:121], v[164:167], v[194:197], v[118:121]
	v_mfma_f32_16x16x32_bf16 v[110:113], v[186:189], v[194:197], v[110:113]
	v_mfma_f32_16x16x32_bf16 v[102:105], v[164:167], v[202:205], v[102:105]
	v_mfma_f32_16x16x32_bf16 v[94:97], v[186:189], v[202:205], v[94:97]
	v_mfma_f32_16x16x32_bf16 v[86:89], v[164:167], v[210:213], v[86:89]
	v_mfma_f32_16x16x32_bf16 v[78:81], v[186:189], v[210:213], v[78:81]
	v_mfma_f32_16x16x32_bf16 v[70:73], v[164:167], v[218:221], v[70:73]
	v_mfma_f32_16x16x32_bf16 v[66:69], v[186:189], v[218:221], v[66:69]
	v_mfma_f32_16x16x32_bf16 v[118:121], v[182:185], v[198:201], v[118:121]
	v_mfma_f32_16x16x32_bf16 v[110:113], v[190:193], v[198:201], v[110:113]
	v_mfma_f32_16x16x32_bf16 v[102:105], v[182:185], v[206:209], v[102:105]
	v_mfma_f32_16x16x32_bf16 v[94:97], v[190:193], v[206:209], v[94:97]
	v_mfma_f32_16x16x32_bf16 v[86:89], v[182:185], v[214:217], v[86:89]
	v_mfma_f32_16x16x32_bf16 v[78:81], v[190:193], v[214:217], v[78:81]
	v_mfma_f32_16x16x32_bf16 v[70:73], v[182:185], v[222:225], v[70:73]
	v_mfma_f32_16x16x32_bf16 v[66:69], v[190:193], v[222:225], v[66:69]
	s_setprio 0
	s_barrier
	s_add_i32 s20, s63, s33
	v_lshl_add_u64 v[168:169], v[168:169], 0, s[90:91]
	s_mov_b32 m0, s20
	ds_read_b128 v[194:197], v147 offset:49152
	ds_read_b128 v[198:201], v147 offset:50176
	ds_read_b128 v[202:205], v147 offset:51200
	ds_read_b128 v[206:209], v147 offset:52224
	ds_read_b128 v[210:213], v147 offset:53248
	ds_read_b128 v[214:217], v147 offset:54272
	ds_read_b128 v[218:221], v147 offset:55296
	ds_read_b128 v[222:225], v147 offset:56320
	global_load_lds_dwordx4 v[168:169], off
	s_add_i32 m0, s20, 0x2000
	s_add_u32 s20, s24, 0x20080
	v_lshl_add_u64 v[168:169], v[226:227], 0, s[90:91]
	s_addc_u32 s21, s25, 0
	s_add_i32 s24, s55, s33
	global_load_lds_dwordx4 v[168:169], off
	v_lshl_add_u64 v[168:169], s[20:21], 0, v[0:1]
	s_mov_b32 m0, s24
	s_nop 0
	global_load_lds_dwordx4 v[168:169], off
	v_lshl_add_u64 v[168:169], s[20:21], 0, v[134:135]
	s_add_i32 m0, s24, 0x2000
	s_nop 0
	global_load_lds_dwordx4 v[168:169], off
	v_lshl_add_u64 v[228:229], v[228:229], 0, s[90:91]
	v_lshl_add_u64 v[240:241], v[240:241], 0, s[90:91]
	s_add_i32 s48, s48, 2
	s_add_u32 s0, s0, 0x100
	s_addc_u32 s15, s15, 0
	s_cmp_gt_u32 s48, 5
	s_mov_b64 s[20:21], s[22:23]
	s_waitcnt vmcnt(6)
	s_waitcnt lgkmcnt(0)
	s_barrier
	s_setprio 1
	s_waitcnt lgkmcnt(0)
	v_mfma_f32_16x16x32_bf16 v[62:65], v[148:151], v[194:197], v[62:65]
	v_mfma_f32_16x16x32_bf16 v[58:61], v[156:159], v[194:197], v[58:61]
	v_mfma_f32_16x16x32_bf16 v[50:53], v[148:151], v[202:205], v[50:53]
	v_mfma_f32_16x16x32_bf16 v[42:45], v[156:159], v[202:205], v[42:45]
	v_mfma_f32_16x16x32_bf16 v[34:37], v[148:151], v[210:213], v[34:37]
	v_mfma_f32_16x16x32_bf16 v[26:29], v[156:159], v[210:213], v[26:29]
	v_mfma_f32_16x16x32_bf16 v[18:21], v[148:151], v[218:221], v[18:21]
	v_mfma_f32_16x16x32_bf16 v[10:13], v[156:159], v[218:221], v[10:13]
	v_mfma_f32_16x16x32_bf16 v[62:65], v[152:155], v[198:201], v[62:65]
	v_mfma_f32_16x16x32_bf16 v[58:61], v[160:163], v[198:201], v[58:61]
	v_mfma_f32_16x16x32_bf16 v[50:53], v[152:155], v[206:209], v[50:53]
	v_mfma_f32_16x16x32_bf16 v[42:45], v[160:163], v[206:209], v[42:45]
	v_mfma_f32_16x16x32_bf16 v[34:37], v[152:155], v[214:217], v[34:37]
	v_mfma_f32_16x16x32_bf16 v[26:29], v[160:163], v[214:217], v[26:29]
	v_mfma_f32_16x16x32_bf16 v[18:21], v[152:155], v[222:225], v[18:21]
	v_mfma_f32_16x16x32_bf16 v[10:13], v[160:163], v[222:225], v[10:13]
	s_setprio 0
	s_setprio 1
	v_mfma_f32_16x16x32_bf16 v[54:57], v[164:167], v[194:197], v[54:57]
	v_mfma_f32_16x16x32_bf16 v[46:49], v[186:189], v[194:197], v[46:49]
	v_mfma_f32_16x16x32_bf16 v[38:41], v[164:167], v[202:205], v[38:41]
	v_mfma_f32_16x16x32_bf16 v[30:33], v[186:189], v[202:205], v[30:33]
	v_mfma_f32_16x16x32_bf16 v[22:25], v[164:167], v[210:213], v[22:25]
	v_mfma_f32_16x16x32_bf16 v[14:17], v[186:189], v[210:213], v[14:17]
	v_mfma_f32_16x16x32_bf16 v[6:9], v[164:167], v[218:221], v[6:9]
	v_mfma_f32_16x16x32_bf16 v[2:5], v[186:189], v[218:221], v[2:5]
	v_mfma_f32_16x16x32_bf16 v[54:57], v[182:185], v[198:201], v[54:57]
	v_mfma_f32_16x16x32_bf16 v[46:49], v[190:193], v[198:201], v[46:49]
	v_mfma_f32_16x16x32_bf16 v[38:41], v[182:185], v[206:209], v[38:41]
	v_mfma_f32_16x16x32_bf16 v[30:33], v[190:193], v[206:209], v[30:33]
	v_mfma_f32_16x16x32_bf16 v[22:25], v[182:185], v[214:217], v[22:25]
	v_mfma_f32_16x16x32_bf16 v[14:17], v[190:193], v[214:217], v[14:17]
	v_mfma_f32_16x16x32_bf16 v[6:9], v[182:185], v[222:225], v[6:9]
	v_mfma_f32_16x16x32_bf16 v[2:5], v[190:193], v[222:225], v[2:5]
	s_setprio 0
	s_barrier
	s_cbranch_scc0 .Lbal_top_627
	s_mov_b32 m0, s42
	s_nop 0
	global_load_lds_dwordx4 v[228:229], off
	s_mov_b32 m0, s43
	s_nop 0
	global_load_lds_dwordx4 v[240:241], off
	s_and_b64 vcc, exec, s[12:13]
	s_cbranch_vccz .LBB0_630
	s_barrier

; #define PG8_STAGE(bufoff, gbase, voff) do { _Pragma("unroll") for (int _i = 0; _i < 2; ++_i) \
;         __builtin_amdgcn_global_load_lds((const unsigned*)((const char*)(gbase) + (voff)[_i]), (PG8_LAS unsigned*)(lds + (bufoff) + ldsw + _i * 8192), 16, 0, 0); } while (0)
; #define PG8_LDA(dst, b, h) do { _Pragma("unroll") for (int m = 0; m < 4; ++m) _Pragma("unroll") for (int k = 0; k < 2; ++k) dst[m][k] = *(const PG8_LAS bf16x8*)(lds + PG8_SA(b, h) + aoff + m * 2048 + k * 1024); } while (0)
; #define PG8_LDB(dst, b, h) do { _Pragma("unroll") for (int n = 0; n < 2; ++n) _Pragma("unroll") for (int k = 0; k < 2; ++k) dst[n][k] = *(const PG8_LAS bf16x8*)(lds + PG8_SB(b, h) + boff + n * 2048 + k * 1024); } while (0)
; #define PG8_MMA(ai, bj, At, Bt) do { __builtin_amdgcn_s_setprio(1); _Pragma("unroll") for (int m = 0; m < 4; ++m) _Pragma("unroll") for (int n = 0; n < 2; ++n) _Pragma("unroll") for (int k = 0; k < 2; ++k) \
;         acc[ai][bj][m][n] = __builtin_amdgcn_mfma_f32_16x16x32_bf16(Bt[n][k], At[m][k], acc[ai][bj][m][n], 0, 0, 0); __builtin_amdgcn_s_setprio(0); } while (0)
; #define PG8_WAIT_V(n) asm volatile("s_waitcnt vmcnt(" #n ")" ::: "memory")
; #define PG8_BAR __builtin_amdgcn_s_barrier()
; template <class Epi, class Sched, bool ALIGN_EPI = false, bool SP2 = false>
; __device__ __forceinline__ void gemm_phase(PG8_LAS unsigned char* lds, const Gemm g, const Sched& S, const Epi& E, int tid_in) {
;     ...
;         for (int t = 0; t < nt; t += 2) {
;             const bool last = (t == nt - 2);
;             const char* a1 = cA + (size_t)(t + 1) * kstep;
;             const char* a2 = last ? nA : cA + (size_t)(t + 2) * kstep; const char* b2 = last ? nB : cB + (size_t)(t + 2) * kstep;
;             const char* a3 = a2 + kstep; const char* b3 = b2 + kstep;
;             if (last && has_next) S.a_ready(nxt);
;             if constexpr (SP2) {
;             PG8_LDB(B0, 0, 0); PG8_LDB(B1, 0, 1); PG8_SCHED; PG8_LDA(At, 0, 0); PG8_STAGE(PG8_SA(1, 1), a1 + hstepA, voffA);
;             PG8_WAIT_V(8); PG8_WAIT_L(0); PG8_BAR; PG8_MMA(0, 0, At, B0); PG8_MMA(0, 1, At, B1); PG8_BAR; PG8_SCHED;
;             PG8_LDA(At, 0, 1); PG8_STAGE(PG8_SB(0, 0), b2, voffB); PG8_STAGE(PG8_SB(0, 1), b2 + hstep, voffB); PG8_STAGE(PG8_SA(0, 0), a2, voffA);
;             PG8_WAIT_V(8); PG8_WAIT_L(0); PG8_BAR; PG8_MMA(1, 0, At, B0); PG8_MMA(1, 1, At, B1); PG8_BAR; PG8_SCHED;
.LBB0_899:
	s_and_b64 s[12:13], s[28:29], exec
	s_cselect_b32 s30, s25, s9
	s_cselect_b32 s31, s24, s8
	s_cselect_b32 s46, s27, s11
	s_cselect_b32 s47, s26, s10
	s_add_i32 s68, s14, -2
	s_add_u32 s8, s8, 0x40080
	s_addc_u32 s9, s9, 0
	s_add_u32 s76, s10, 0x100
	s_addc_u32 vcc_lo, s11, 0
	s_mov_b32 s10, 0
	s_branch .LBB0_900
.Lbal_top_900:
	s_mov_b32 m0, s49
	s_nop 0
	global_load_lds_dwordx4 v[220:221], off
	s_mov_b32 m0, s79
	s_nop 0
	global_load_lds_dwordx4 v[222:223], off
.LBB0_900:
	v_add_u32_e32 v0, s4, v242
	ds_read_b128 v[132:135], v0
	ds_read_b128 v[144:147], v0 offset:1024
	ds_read_b128 v[148:151], v0 offset:2048
	ds_read_b128 v[152:155], v0 offset:3072
	v_add_u32_e32 v0, s5, v242
	ds_read_b128 v[156:159], v0
	ds_read_b128 v[160:163], v0 offset:1024
	ds_read_b128 v[164:167], v0 offset:2048
	ds_read_b128 v[182:185], v0 offset:3072
	s_add_i32 vcc_hi, s10, 2
	s_add_u32 s11, s8, 0xfffc0080
	s_addc_u32 s12, s9, -1
	s_cmp_eq_u32 s68, s10
	s_cselect_b32 s10, s47, s76
	s_cselect_b32 s13, s30, s12
	s_cselect_b32 s12, s31, s11
	s_cselect_b32 s11, s46, vcc_lo
	v_lshl_add_u64 v[2:3], s[8:9], 0, v[140:141]
	s_add_i32 m0, s37, 0xc000
	ds_read_b128 v[186:189], v243
	ds_read_b128 v[190:193], v243 offset:1024
	ds_read_b128 v[194:197], v243 offset:2048
	ds_read_b128 v[198:201], v243 offset:3072
	ds_read_b128 v[202:205], v243 offset:4096
	ds_read_b128 v[206:209], v243 offset:5120
	ds_read_b128 v[210:213], v243 offset:6144
	ds_read_b128 v[214:217], v243 offset:7168
	global_load_lds_dwordx4 v[2:3], off
	v_lshl_add_u64 v[2:3], s[8:9], 0, v[142:143]
	s_add_i32 m0, s37, 0xe000
	s_nop 0
	global_load_lds_dwordx4 v[2:3], off
	s_waitcnt vmcnt(8)
	s_waitcnt lgkmcnt(0)
	s_barrier
	s_setprio 1
	s_waitcnt lgkmcnt(0)
	v_mfma_f32_16x16x32_bf16 v[128:131], v[132:135], v[186:189], v[128:131]
	v_mfma_f32_16x16x32_bf16 v[124:127], v[148:151], v[186:189], v[124:127]
	v_mfma_f32_16x16x32_bf16 v[120:123], v[132:135], v[194:197], v[120:123]
	v_mfma_f32_16x16x32_bf16 v[116:119], v[148:151], v[194:197], v[116:119]
	v_mfma_f32_16x16x32_bf16 v[112:115], v[132:135], v[202:205], v[112:115]
	v_mfma_f32_16x16x32_bf16 v[108:111], v[148:151], v[202:205], v[108:111]
	v_mfma_f32_16x16x32_bf16 v[104:107], v[132:135], v[210:213], v[104:107]
	v_mfma_f32_16x16x32_bf16 v[100:103], v[148:151], v[210:213], v[100:103]
	v_mfma_f32_16x16x32_bf16 v[128:131], v[144:147], v[190:193], v[128:131]
	v_mfma_f32_16x16x32_bf16 v[124:127], v[152:155], v[190:193], v[124:127]
	v_mfma_f32_16x16x32_bf16 v[120:123], v[144:147], v[198:201], v[120:123]
	v_mfma_f32_16x16x32_bf16 v[116:119], v[152:155], v[198:201], v[116:119]
	v_mfma_f32_16x16x32_bf16 v[112:115], v[144:147], v[206:209], v[112:115]
	v_mfma_f32_16x16x32_bf16 v[108:111], v[152:155], v[206:209], v[108:111]
	v_mfma_f32_16x16x32_bf16 v[104:107], v[144:147], v[214:217], v[104:107]
	v_mfma_f32_16x16x32_bf16 v[100:103], v[152:155], v[214:217], v[100:103]
	s_setprio 0
	s_setprio 1
	v_mfma_f32_16x16x32_bf16 v[96:99], v[156:159], v[186:189], v[96:99]
	v_mfma_f32_16x16x32_bf16 v[92:95], v[164:167], v[186:189], v[92:95]
	v_mfma_f32_16x16x32_bf16 v[88:91], v[156:159], v[194:197], v[88:91]
	v_mfma_f32_16x16x32_bf16 v[84:87], v[164:167], v[194:197], v[84:87]
	v_mfma_f32_16x16x32_bf16 v[80:83], v[156:159], v[202:205], v[80:83]
	v_mfma_f32_16x16x32_bf16 v[76:79], v[164:167], v[202:205], v[76:79]
	v_mfma_f32_16x16x32_bf16 v[72:75], v[156:159], v[210:213], v[72:75]
	v_mfma_f32_16x16x32_bf16 v[68:71], v[164:167], v[210:213], v[68:71]
	v_mfma_f32_16x16x32_bf16 v[96:99], v[160:163], v[190:193], v[96:99]
	v_mfma_f32_16x16x32_bf16 v[92:95], v[182:185], v[190:193], v[92:95]
	v_mfma_f32_16x16x32_bf16 v[88:91], v[160:163], v[198:201], v[88:91]
	v_mfma_f32_16x16x32_bf16 v[84:87], v[182:185], v[198:201], v[84:87]
	v_mfma_f32_16x16x32_bf16 v[80:83], v[160:163], v[206:209], v[80:83]
	v_mfma_f32_16x16x32_bf16 v[76:79], v[182:185], v[206:209], v[76:79]
	v_mfma_f32_16x16x32_bf16 v[72:75], v[160:163], v[214:217], v[72:75]
	v_mfma_f32_16x16x32_bf16 v[68:71], v[182:185], v[214:217], v[68:71]
	s_setprio 0
	s_barrier
	s_add_i32 s64, s4, s36
	v_lshl_add_u64 v[168:169], s[10:11], 0, v[136:137]
	s_mov_b32 m0, s64
	ds_read_b128 v[186:189], v243 offset:16384
	ds_read_b128 v[190:193], v243 offset:17408
	ds_read_b128 v[194:197], v243 offset:18432
	ds_read_b128 v[198:201], v243 offset:19456
	ds_read_b128 v[202:205], v243 offset:20480
	ds_read_b128 v[206:209], v243 offset:21504
	ds_read_b128 v[210:213], v243 offset:22528
	ds_read_b128 v[214:217], v243 offset:23552
	global_load_lds_dwordx4 v[168:169], off
	s_add_i32 m0, s64, 0x2000
	s_add_u32 s64, s10, 0x40000
	v_lshl_add_u64 v[218:219], s[10:11], 0, v[138:139]
	s_addc_u32 s65, s11, 0
	s_add_i32 s95, s5, s36
	global_load_lds_dwordx4 v[218:219], off
	v_lshl_add_u64 v[2:3], s[64:65], 0, v[136:137]
	s_mov_b32 m0, s95
	v_lshl_add_u64 v[220:221], s[12:13], 0, v[136:137]
	global_load_lds_dwordx4 v[2:3], off
	v_lshl_add_u64 v[2:3], s[64:65], 0, v[138:139]
	s_add_i32 m0, s95, 0x2000
	v_lshl_add_u64 v[222:223], s[12:13], 0, v[138:139]
	global_load_lds_dwordx4 v[2:3], off
	s_waitcnt vmcnt(6)
	s_waitcnt lgkmcnt(0)
	s_barrier
; #define PG8_STAGE(bufoff, gbase, voff) do { _Pragma("unroll") for (int _i = 0; _i < 2; ++_i) \
;         __builtin_amdgcn_global_load_lds((const unsigned*)((const char*)(gbase) + (voff)[_i]), (PG8_LAS unsigned*)(lds + (bufoff) + ldsw + _i * 8192), 16, 0, 0); } while (0)
; #define PG8_LDA(dst, b, h) do { _Pragma("unroll") for (int m = 0; m < 4; ++m) _Pragma("unroll") for (int k = 0; k < 2; ++k) dst[m][k] = *(const PG8_LAS bf16x8*)(lds + PG8_SA(b, h) + aoff + m * 2048 + k * 1024); } while (0)
; #define PG8_LDB(dst, b, h) do { _Pragma("unroll") for (int n = 0; n < 2; ++n) _Pragma("unroll") for (int k = 0; k < 2; ++k) dst[n][k] = *(const PG8_LAS bf16x8*)(lds + PG8_SB(b, h) + boff + n * 2048 + k * 1024); } while (0)
; #define PG8_MMA(ai, bj, At, Bt) do { __builtin_amdgcn_s_setprio(1); _Pragma("unroll") for (int m = 0; m < 4; ++m) _Pragma("unroll") for (int n = 0; n < 2; ++n) _Pragma("unroll") for (int k = 0; k < 2; ++k) \
;         acc[ai][bj][m][n] = __builtin_amdgcn_mfma_f32_16x16x32_bf16(Bt[n][k], At[m][k], acc[ai][bj][m][n], 0, 0, 0); __builtin_amdgcn_s_setprio(0); } while (0)
; #define PG8_WAIT_V(n) asm volatile("s_waitcnt vmcnt(" #n ")" ::: "memory")
; #define PG8_WAIT_L(n) asm volatile("s_waitcnt lgkmcnt(" #n ")" ::: "memory")
; #define PG8_BAR __builtin_amdgcn_s_barrier()
; #define PG8_SCHED __builtin_amdgcn_sched_barrier(0)
; template <class Epi, class Sched, bool ALIGN_EPI = false, bool SP2 = false>
; __device__ __forceinline__ void gemm_phase(PG8_LAS unsigned char* lds, const Gemm g, const Sched& S, const Epi& E, int tid_in) {
;     ...
;             PG8_WAIT_V(8); PG8_WAIT_L(0); PG8_BAR; PG8_MMA(1, 0, At, B0); PG8_MMA(1, 1, At, B1); PG8_BAR; PG8_SCHED;
;             PG8_LDB(B0, 1, 0); PG8_LDB(B1, 1, 1); PG8_SCHED; PG8_LDA(At, 1, 0); PG8_STAGE(PG8_SA(0, 1), a2 + hstepA, voffA);
;             PG8_WAIT_V(8); PG8_WAIT_L(0); PG8_BAR; PG8_MMA(0, 0, At, B0); PG8_MMA(0, 1, At, B1); PG8_BAR; PG8_SCHED;
	s_setprio 1
	s_waitcnt lgkmcnt(0)
	v_mfma_f32_16x16x32_bf16 v[64:67], v[132:135], v[186:189], v[64:67]
	v_mfma_f32_16x16x32_bf16 v[60:63], v[148:151], v[186:189], v[60:63]
	v_mfma_f32_16x16x32_bf16 v[56:59], v[132:135], v[194:197], v[56:59]
	v_mfma_f32_16x16x32_bf16 v[52:55], v[148:151], v[194:197], v[52:55]
	v_mfma_f32_16x16x32_bf16 v[48:51], v[132:135], v[202:205], v[48:51]
	v_mfma_f32_16x16x32_bf16 v[44:47], v[148:151], v[202:205], v[44:47]
	v_mfma_f32_16x16x32_bf16 v[40:43], v[132:135], v[210:213], v[40:43]
	v_mfma_f32_16x16x32_bf16 v[36:39], v[148:151], v[210:213], v[36:39]
	v_mfma_f32_16x16x32_bf16 v[64:67], v[144:147], v[190:193], v[64:67]
	v_mfma_f32_16x16x32_bf16 v[60:63], v[152:155], v[190:193], v[60:63]
	v_mfma_f32_16x16x32_bf16 v[56:59], v[144:147], v[198:201], v[56:59]
	v_mfma_f32_16x16x32_bf16 v[52:55], v[152:155], v[198:201], v[52:55]
	v_mfma_f32_16x16x32_bf16 v[48:51], v[144:147], v[206:209], v[48:51]
	v_mfma_f32_16x16x32_bf16 v[44:47], v[152:155], v[206:209], v[44:47]
	v_mfma_f32_16x16x32_bf16 v[40:43], v[144:147], v[214:217], v[40:43]
	v_mfma_f32_16x16x32_bf16 v[36:39], v[152:155], v[214:217], v[36:39]
	s_setprio 0
	s_setprio 1
	v_mfma_f32_16x16x32_bf16 v[32:35], v[156:159], v[186:189], v[32:35]
	v_mfma_f32_16x16x32_bf16 v[28:31], v[164:167], v[186:189], v[28:31]
	v_mfma_f32_16x16x32_bf16 v[24:27], v[156:159], v[194:197], v[24:27]
	v_mfma_f32_16x16x32_bf16 v[20:23], v[164:167], v[194:197], v[20:23]
	v_mfma_f32_16x16x32_bf16 v[16:19], v[156:159], v[202:205], v[16:19]
	v_mfma_f32_16x16x32_bf16 v[12:15], v[164:167], v[202:205], v[12:15]
	v_mfma_f32_16x16x32_bf16 v[8:11], v[156:159], v[210:213], v[8:11]
	v_mfma_f32_16x16x32_bf16 v[2:5], v[164:167], v[210:213], v[4:7]
	v_mfma_f32_16x16x32_bf16 v[32:35], v[160:163], v[190:193], v[32:35]
	v_mfma_f32_16x16x32_bf16 v[28:31], v[182:185], v[190:193], v[28:31]
	v_mfma_f32_16x16x32_bf16 v[24:27], v[160:163], v[198:201], v[24:27]
	v_mfma_f32_16x16x32_bf16 v[20:23], v[182:185], v[198:201], v[20:23]
	v_mfma_f32_16x16x32_bf16 v[16:19], v[160:163], v[206:209], v[16:19]
	v_mfma_f32_16x16x32_bf16 v[12:15], v[182:185], v[206:209], v[12:15]
	v_mfma_f32_16x16x32_bf16 v[8:11], v[160:163], v[214:217], v[8:11]
	v_mfma_f32_16x16x32_bf16 v[2:5], v[182:185], v[214:217], v[2:5]
	s_setprio 0
	s_barrier
	s_mov_b32 m0, s37
	s_nop 0
	global_load_lds_dwordx4 v[220:221], off
	s_mov_b32 m0, s38
	s_nop 0
	global_load_lds_dwordx4 v[222:223], off
	v_add_u32_e32 v0, s63, v242
	ds_read_b128 v[132:135], v0
	ds_read_b128 v[144:147], v0 offset:1024
	ds_read_b128 v[148:151], v0 offset:2048
	ds_read_b128 v[152:155], v0 offset:3072
	v_add_u32_e32 v0, s55, v242
	ds_read_b128 v[156:159], v0
	ds_read_b128 v[160:163], v0 offset:1024
	ds_read_b128 v[164:167], v0 offset:2048
	ds_read_b128 v[182:185], v0 offset:3072
	s_add_u32 s12, s12, 0x40000
	s_addc_u32 s13, s13, 0
	s_mov_b32 m0, s39
	v_lshl_add_u64 v[6:7], s[12:13], 0, v[136:137]
	ds_read_b128 v[186:189], v243 offset:32768
	ds_read_b128 v[190:193], v243 offset:33792
	ds_read_b128 v[194:197], v243 offset:34816
	ds_read_b128 v[198:201], v243 offset:35840
	ds_read_b128 v[202:205], v243 offset:36864
	ds_read_b128 v[206:209], v243 offset:37888
	ds_read_b128 v[210:213], v243 offset:38912
	ds_read_b128 v[214:217], v243 offset:39936
	global_load_lds_dwordx4 v[6:7], off
	v_lshl_add_u64 v[6:7], s[12:13], 0, v[138:139]
	s_mov_b32 m0, s40
	s_nop 0
	global_load_lds_dwordx4 v[6:7], off
	s_waitcnt vmcnt(8)
	s_waitcnt lgkmcnt(0)
	s_barrier
	s_setprio 1
	s_waitcnt lgkmcnt(0)
	v_mfma_f32_16x16x32_bf16 v[128:131], v[132:135], v[186:189], v[128:131]
	v_mfma_f32_16x16x32_bf16 v[124:127], v[148:151], v[186:189], v[124:127]
	v_mfma_f32_16x16x32_bf16 v[120:123], v[132:135], v[194:197], v[120:123]
	v_mfma_f32_16x16x32_bf16 v[116:119], v[148:151], v[194:197], v[116:119]
	v_mfma_f32_16x16x32_bf16 v[112:115], v[132:135], v[202:205], v[112:115]
	v_mfma_f32_16x16x32_bf16 v[108:111], v[148:151], v[202:205], v[108:111]
	v_mfma_f32_16x16x32_bf16 v[104:107], v[132:135], v[210:213], v[104:107]
	v_mfma_f32_16x16x32_bf16 v[100:103], v[148:151], v[210:213], v[100:103]
	v_mfma_f32_16x16x32_bf16 v[128:131], v[144:147], v[190:193], v[128:131]
	v_mfma_f32_16x16x32_bf16 v[124:127], v[152:155], v[190:193], v[124:127]
	v_mfma_f32_16x16x32_bf16 v[120:123], v[144:147], v[198:201], v[120:123]
	v_mfma_f32_16x16x32_bf16 v[116:119], v[152:155], v[198:201], v[116:119]
	v_mfma_f32_16x16x32_bf16 v[112:115], v[144:147], v[206:209], v[112:115]
	v_mfma_f32_16x16x32_bf16 v[108:111], v[152:155], v[206:209], v[108:111]
	v_mfma_f32_16x16x32_bf16 v[104:107], v[144:147], v[214:217], v[104:107]
	v_mfma_f32_16x16x32_bf16 v[100:103], v[152:155], v[214:217], v[100:103]
	s_setprio 0
	s_setprio 1
	v_mfma_f32_16x16x32_bf16 v[96:99], v[156:159], v[186:189], v[96:99]
	v_mfma_f32_16x16x32_bf16 v[92:95], v[164:167], v[186:189], v[92:95]
	v_mfma_f32_16x16x32_bf16 v[88:91], v[156:159], v[194:197], v[88:91]
	v_mfma_f32_16x16x32_bf16 v[84:87], v[164:167], v[194:197], v[84:87]
	v_mfma_f32_16x16x32_bf16 v[80:83], v[156:159], v[202:205], v[80:83]
	v_mfma_f32_16x16x32_bf16 v[76:79], v[164:167], v[202:205], v[76:79]
	v_mfma_f32_16x16x32_bf16 v[72:75], v[156:159], v[210:213], v[72:75]
	v_mfma_f32_16x16x32_bf16 v[68:71], v[164:167], v[210:213], v[68:71]
	v_mfma_f32_16x16x32_bf16 v[96:99], v[160:163], v[190:193], v[96:99]
	v_mfma_f32_16x16x32_bf16 v[92:95], v[182:185], v[190:193], v[92:95]
	v_mfma_f32_16x16x32_bf16 v[88:91], v[160:163], v[198:201], v[88:91]
	v_mfma_f32_16x16x32_bf16 v[84:87], v[182:185], v[198:201], v[84:87]
	v_mfma_f32_16x16x32_bf16 v[80:83], v[160:163], v[206:209], v[80:83]
	v_mfma_f32_16x16x32_bf16 v[76:79], v[182:185], v[206:209], v[76:79]
	v_mfma_f32_16x16x32_bf16 v[72:75], v[160:163], v[214:217], v[72:75]
	v_mfma_f32_16x16x32_bf16 v[68:71], v[182:185], v[214:217], v[68:71]
	s_setprio 0
	s_barrier
; #define PG8_STAGE(bufoff, gbase, voff) do { _Pragma("unroll") for (int _i = 0; _i < 2; ++_i) \
;         __builtin_amdgcn_global_load_lds((const unsigned*)((const char*)(gbase) + (voff)[_i]), (PG8_LAS unsigned*)(lds + (bufoff) + ldsw + _i * 8192), 16, 0, 0); } while (0)
; #define PG8_LDA(dst, b, h) do { _Pragma("unroll") for (int m = 0; m < 4; ++m) _Pragma("unroll") for (int k = 0; k < 2; ++k) dst[m][k] = *(const PG8_LAS bf16x8*)(lds + PG8_SA(b, h) + aoff + m * 2048 + k * 1024); } while (0)
; #define PG8_MMA(ai, bj, At, Bt) do { __builtin_amdgcn_s_setprio(1); _Pragma("unroll") for (int m = 0; m < 4; ++m) _Pragma("unroll") for (int n = 0; n < 2; ++n) _Pragma("unroll") for (int k = 0; k < 2; ++k) \
;         acc[ai][bj][m][n] = __builtin_amdgcn_mfma_f32_16x16x32_bf16(Bt[n][k], At[m][k], acc[ai][bj][m][n], 0, 0, 0); __builtin_amdgcn_s_setprio(0); } while (0)
; #define PG8_WAIT_V(n) asm volatile("s_waitcnt vmcnt(" #n ")" ::: "memory")
; #define PG8_WAIT_L(n) asm volatile("s_waitcnt lgkmcnt(" #n ")" ::: "memory")
; #define PG8_BAR __builtin_amdgcn_s_barrier()
; #define PG8_SCHED __builtin_amdgcn_sched_barrier(0)
; template <class Epi, class Sched, bool ALIGN_EPI = false, bool SP2 = false>
; __device__ __forceinline__ void gemm_phase(PG8_LAS unsigned char* lds, const Gemm g, const Sched& S, const Epi& E, int tid_in) {
;     ...
;             PG8_LDA(At, 1, 1); PG8_STAGE(PG8_SB(1, 0), b3, voffB); PG8_STAGE(PG8_SB(1, 1), b3 + hstep, voffB); PG8_STAGE(PG8_SA(1, 0), a3, voffA);
;             PG8_WAIT_V(8); PG8_WAIT_L(0); PG8_BAR; PG8_MMA(1, 0, At, B0); PG8_MMA(1, 1, At, B1); PG8_BAR; PG8_SCHED;
	s_add_i32 s12, s63, s36
	v_lshl_add_u64 v[6:7], v[168:169], 0, s[90:91]
	s_mov_b32 m0, s12
	ds_read_b128 v[186:189], v243 offset:49152
	ds_read_b128 v[190:193], v243 offset:50176
	ds_read_b128 v[194:197], v243 offset:51200
	ds_read_b128 v[198:201], v243 offset:52224
	ds_read_b128 v[202:205], v243 offset:53248
	ds_read_b128 v[206:209], v243 offset:54272
	ds_read_b128 v[210:213], v243 offset:55296
	ds_read_b128 v[214:217], v243 offset:56320
	global_load_lds_dwordx4 v[6:7], off
	s_add_i32 m0, s12, 0x2000
	s_add_u32 s10, s10, 0x40080
	v_lshl_add_u64 v[6:7], v[218:219], 0, s[90:91]
	s_addc_u32 s11, s11, 0
	s_add_i32 s12, s55, s36
	global_load_lds_dwordx4 v[6:7], off
	v_lshl_add_u64 v[6:7], s[10:11], 0, v[136:137]
	s_mov_b32 m0, s12
	s_nop 0
	global_load_lds_dwordx4 v[6:7], off
	v_lshl_add_u64 v[6:7], s[10:11], 0, v[138:139]
	s_add_i32 m0, s12, 0x2000
	s_nop 0
	global_load_lds_dwordx4 v[6:7], off
	v_lshl_add_u64 v[220:221], v[220:221], 0, s[90:91]
	v_lshl_add_u64 v[222:223], v[222:223], 0, s[90:91]
	s_add_u32 s8, s8, 0x100
	s_addc_u32 s9, s9, 0
	s_add_u32 s76, s76, 0x100
	s_addc_u32 vcc_lo, vcc_lo, 0
	s_cmp_ge_i32 vcc_hi, s14
	s_mov_b32 s10, vcc_hi
	s_waitcnt vmcnt(6)
	s_waitcnt lgkmcnt(0)
	s_barrier
	s_setprio 1
	s_waitcnt lgkmcnt(0)
	v_mfma_f32_16x16x32_bf16 v[64:67], v[132:135], v[186:189], v[64:67]
	v_mfma_f32_16x16x32_bf16 v[60:63], v[148:151], v[186:189], v[60:63]
	v_mfma_f32_16x16x32_bf16 v[56:59], v[132:135], v[194:197], v[56:59]
	v_mfma_f32_16x16x32_bf16 v[52:55], v[148:151], v[194:197], v[52:55]
	v_mfma_f32_16x16x32_bf16 v[48:51], v[132:135], v[202:205], v[48:51]
	v_mfma_f32_16x16x32_bf16 v[44:47], v[148:151], v[202:205], v[44:47]
	v_mfma_f32_16x16x32_bf16 v[40:43], v[132:135], v[210:213], v[40:43]
	v_mfma_f32_16x16x32_bf16 v[36:39], v[148:151], v[210:213], v[36:39]
	v_mfma_f32_16x16x32_bf16 v[64:67], v[144:147], v[190:193], v[64:67]
	v_mfma_f32_16x16x32_bf16 v[60:63], v[152:155], v[190:193], v[60:63]
	v_mfma_f32_16x16x32_bf16 v[56:59], v[144:147], v[198:201], v[56:59]
	v_mfma_f32_16x16x32_bf16 v[52:55], v[152:155], v[198:201], v[52:55]
	v_mfma_f32_16x16x32_bf16 v[48:51], v[144:147], v[206:209], v[48:51]
	v_mfma_f32_16x16x32_bf16 v[44:47], v[152:155], v[206:209], v[44:47]
	v_mfma_f32_16x16x32_bf16 v[40:43], v[144:147], v[214:217], v[40:43]
	v_mfma_f32_16x16x32_bf16 v[36:39], v[152:155], v[214:217], v[36:39]
	s_setprio 0
	s_setprio 1
	v_mfma_f32_16x16x32_bf16 v[32:35], v[156:159], v[186:189], v[32:35]
	v_mfma_f32_16x16x32_bf16 v[28:31], v[164:167], v[186:189], v[28:31]
	v_mfma_f32_16x16x32_bf16 v[24:27], v[156:159], v[194:197], v[24:27]
	v_mfma_f32_16x16x32_bf16 v[20:23], v[164:167], v[194:197], v[20:23]
	v_mfma_f32_16x16x32_bf16 v[16:19], v[156:159], v[202:205], v[16:19]
	v_mfma_f32_16x16x32_bf16 v[12:15], v[164:167], v[202:205], v[12:15]
	v_mfma_f32_16x16x32_bf16 v[6:9], v[156:159], v[210:213], v[8:11]
	v_mfma_f32_16x16x32_bf16 v[2:5], v[164:167], v[210:213], v[2:5]
	v_mfma_f32_16x16x32_bf16 v[32:35], v[160:163], v[190:193], v[32:35]
	v_mfma_f32_16x16x32_bf16 v[28:31], v[182:185], v[190:193], v[28:31]
	v_mfma_f32_16x16x32_bf16 v[24:27], v[160:163], v[198:201], v[24:27]
	v_mfma_f32_16x16x32_bf16 v[20:23], v[182:185], v[198:201], v[20:23]
	v_mfma_f32_16x16x32_bf16 v[16:19], v[160:163], v[206:209], v[16:19]
	v_mfma_f32_16x16x32_bf16 v[12:15], v[182:185], v[206:209], v[12:15]
	v_mfma_f32_16x16x32_bf16 v[8:11], v[160:163], v[214:217], v[6:9]
	v_mfma_f32_16x16x32_bf16 v[4:7], v[182:185], v[214:217], v[2:5]
	s_setprio 0
	s_barrier
	s_cbranch_scc0 .Lbal_top_900
	s_mov_b32 m0, s49
	s_nop 0
	global_load_lds_dwordx4 v[220:221], off
	s_mov_b32 m0, s79
	s_nop 0
	global_load_lds_dwordx4 v[222:223], off
	s_and_b64 vcc, exec, s[18:19]
	s_cbranch_vccz .LBB0_903
	s_barrier

; #define PG8_STAGE(bufoff, gbase, voff) do { _Pragma("unroll") for (int _i = 0; _i < 2; ++_i) \
;         __builtin_amdgcn_global_load_lds((const unsigned*)((const char*)(gbase) + (voff)[_i]), (PG8_LAS unsigned*)(lds + (bufoff) + ldsw + _i * 8192), 16, 0, 0); } while (0)
; #define PG8_LDA(dst, b, h) do { _Pragma("unroll") for (int m = 0; m < 4; ++m) _Pragma("unroll") for (int k = 0; k < 2; ++k) dst[m][k] = *(const PG8_LAS bf16x8*)(lds + PG8_SA(b, h) + aoff + m * 2048 + k * 1024); } while (0)
; #define PG8_LDB(dst, b, h) do { _Pragma("unroll") for (int n = 0; n < 2; ++n) _Pragma("unroll") for (int k = 0; k < 2; ++k) dst[n][k] = *(const PG8_LAS bf16x8*)(lds + PG8_SB(b, h) + boff + n * 2048 + k * 1024); } while (0)
; #define PG8_MMA(ai, bj, At, Bt) do { __builtin_amdgcn_s_setprio(1); _Pragma("unroll") for (int m = 0; m < 4; ++m) _Pragma("unroll") for (int n = 0; n < 2; ++n) _Pragma("unroll") for (int k = 0; k < 2; ++k) \
;         acc[ai][bj][m][n] = __builtin_amdgcn_mfma_f32_16x16x32_bf16(Bt[n][k], At[m][k], acc[ai][bj][m][n], 0, 0, 0); __builtin_amdgcn_s_setprio(0); } while (0)
; #define PG8_WAIT_V(n) asm volatile("s_waitcnt vmcnt(" #n ")" ::: "memory")
; #define PG8_BAR __builtin_amdgcn_s_barrier()
; template <class Epi, class Sched, bool ALIGN_EPI = false, bool SP2 = false>
; __device__ __forceinline__ void gemm_phase(PG8_LAS unsigned char* lds, const Gemm g, const Sched& S, const Epi& E, int tid_in) {
;     ...
;         for (int t = 0; t < nt; t += 2) {
;             const bool last = (t == nt - 2);
;             const char* a1 = cA + (size_t)(t + 1) * kstep;
;             const char* a2 = last ? nA : cA + (size_t)(t + 2) * kstep; const char* b2 = last ? nB : cB + (size_t)(t + 2) * kstep;
;             const char* a3 = a2 + kstep; const char* b3 = b2 + kstep;
;             if (last && has_next) S.a_ready(nxt);
;             if constexpr (SP2) {
;             PG8_LDB(B0, 0, 0); PG8_LDB(B1, 0, 1); PG8_SCHED; PG8_LDA(At, 0, 0); PG8_STAGE(PG8_SA(1, 1), a1 + hstepA, voffA);
;             PG8_WAIT_V(8); PG8_WAIT_L(0); PG8_BAR; PG8_MMA(0, 0, At, B0); PG8_MMA(0, 1, At, B1); PG8_BAR; PG8_SCHED;
;             PG8_LDA(At, 0, 1); PG8_STAGE(PG8_SB(0, 0), b2, voffB); PG8_STAGE(PG8_SB(0, 1), b2 + hstep, voffB); PG8_STAGE(PG8_SA(0, 0), a2, voffA);
;             PG8_WAIT_V(8); PG8_WAIT_L(0); PG8_BAR; PG8_MMA(1, 0, At, B0); PG8_MMA(1, 1, At, B1); PG8_BAR; PG8_SCHED;
.LBB0_1347:
	s_and_b64 s[28:29], s[22:23], exec
	s_cselect_b32 s46, s19, s25
	s_cselect_b32 s47, s18, s24
	s_cselect_b32 s49, s21, s27
	s_cselect_b32 s66, s20, s26
	s_add_i32 s67, s45, -2
	s_add_u32 s24, s24, 0x80080
	s_addc_u32 s25, s25, 0
	s_add_u32 s68, s26, 0x100
	s_addc_u32 s70, s27, 0
	s_mov_b32 s26, 0
	s_branch .LBB0_1348
.Lbal_top_1348:
	s_mov_b32 m0, s41
	s_nop 0
	global_load_lds_dwordx4 v[220:221], off
	s_mov_b32 m0, s42
	s_nop 0
	global_load_lds_dwordx4 v[222:223], off
.LBB0_1348:
	v_add_u32_e32 v152, s4, v146
	v_add_u32_e32 v168, s5, v146
	ds_read_b128 v[136:139], v152
	ds_read_b128 v[140:143], v152 offset:1024
	ds_read_b128 v[148:151], v152 offset:2048
	ds_read_b128 v[152:155], v152 offset:3072
	ds_read_b128 v[156:159], v168
	ds_read_b128 v[160:163], v168 offset:1024
	ds_read_b128 v[164:167], v168 offset:2048
	ds_read_b128 v[182:185], v168 offset:3072
	s_add_i32 s76, s26, 2
	s_add_u32 s27, s24, 0xfff80080
	s_addc_u32 s28, s25, -1
	s_cmp_eq_u32 s67, s26
	s_cselect_b32 s26, s66, s68
	s_cselect_b32 s29, s46, s28
	s_cselect_b32 s28, s47, s27
	s_cselect_b32 s27, s49, s70
	v_lshl_add_u64 v[168:169], s[24:25], 0, v[132:133]
	s_add_i32 m0, s31, 0xc000
	ds_read_b128 v[186:189], v147
	ds_read_b128 v[190:193], v147 offset:1024
	ds_read_b128 v[194:197], v147 offset:2048
	ds_read_b128 v[198:201], v147 offset:3072
	ds_read_b128 v[202:205], v147 offset:4096
	ds_read_b128 v[206:209], v147 offset:5120
	ds_read_b128 v[210:213], v147 offset:6144
	ds_read_b128 v[214:217], v147 offset:7168
	global_load_lds_dwordx4 v[168:169], off
	v_lshl_add_u64 v[168:169], s[24:25], 0, v[134:135]
	s_add_i32 m0, s31, 0xe000
	s_nop 0
	global_load_lds_dwordx4 v[168:169], off
	s_waitcnt vmcnt(8)
	s_waitcnt lgkmcnt(0)
	s_barrier
	s_setprio 1
	s_waitcnt lgkmcnt(0)
	v_mfma_f32_16x16x32_bf16 v[126:129], v[136:139], v[186:189], v[126:129]
	v_mfma_f32_16x16x32_bf16 v[122:125], v[148:151], v[186:189], v[122:125]
	v_mfma_f32_16x16x32_bf16 v[118:121], v[136:139], v[194:197], v[118:121]
	v_mfma_f32_16x16x32_bf16 v[114:117], v[148:151], v[194:197], v[114:117]
	v_mfma_f32_16x16x32_bf16 v[110:113], v[136:139], v[202:205], v[110:113]
	v_mfma_f32_16x16x32_bf16 v[106:109], v[148:151], v[202:205], v[106:109]
	v_mfma_f32_16x16x32_bf16 v[102:105], v[136:139], v[210:213], v[102:105]
	v_mfma_f32_16x16x32_bf16 v[98:101], v[148:151], v[210:213], v[98:101]
	v_mfma_f32_16x16x32_bf16 v[126:129], v[140:143], v[190:193], v[126:129]
	v_mfma_f32_16x16x32_bf16 v[122:125], v[152:155], v[190:193], v[122:125]
	v_mfma_f32_16x16x32_bf16 v[118:121], v[140:143], v[198:201], v[118:121]
	v_mfma_f32_16x16x32_bf16 v[114:117], v[152:155], v[198:201], v[114:117]
	v_mfma_f32_16x16x32_bf16 v[110:113], v[140:143], v[206:209], v[110:113]
	v_mfma_f32_16x16x32_bf16 v[106:109], v[152:155], v[206:209], v[106:109]
	v_mfma_f32_16x16x32_bf16 v[102:105], v[140:143], v[214:217], v[102:105]
	v_mfma_f32_16x16x32_bf16 v[98:101], v[152:155], v[214:217], v[98:101]
	s_setprio 0
	s_setprio 1
	v_mfma_f32_16x16x32_bf16 v[94:97], v[156:159], v[186:189], v[94:97]
	v_mfma_f32_16x16x32_bf16 v[90:93], v[164:167], v[186:189], v[90:93]
	v_mfma_f32_16x16x32_bf16 v[86:89], v[156:159], v[194:197], v[86:89]
	v_mfma_f32_16x16x32_bf16 v[82:85], v[164:167], v[194:197], v[82:85]
	v_mfma_f32_16x16x32_bf16 v[78:81], v[156:159], v[202:205], v[78:81]
	v_mfma_f32_16x16x32_bf16 v[74:77], v[164:167], v[202:205], v[74:77]
	v_mfma_f32_16x16x32_bf16 v[70:73], v[156:159], v[210:213], v[70:73]
	v_mfma_f32_16x16x32_bf16 v[66:69], v[164:167], v[210:213], v[66:69]
	v_mfma_f32_16x16x32_bf16 v[94:97], v[160:163], v[190:193], v[94:97]
	v_mfma_f32_16x16x32_bf16 v[90:93], v[182:185], v[190:193], v[90:93]
	v_mfma_f32_16x16x32_bf16 v[86:89], v[160:163], v[198:201], v[86:89]
	v_mfma_f32_16x16x32_bf16 v[82:85], v[182:185], v[198:201], v[82:85]
	v_mfma_f32_16x16x32_bf16 v[78:81], v[160:163], v[206:209], v[78:81]
	v_mfma_f32_16x16x32_bf16 v[74:77], v[182:185], v[206:209], v[74:77]
	v_mfma_f32_16x16x32_bf16 v[70:73], v[160:163], v[214:217], v[70:73]
	v_mfma_f32_16x16x32_bf16 v[66:69], v[182:185], v[214:217], v[66:69]
	s_setprio 0
	s_barrier
	s_add_i32 s64, s4, s30
	v_lshl_add_u64 v[168:169], s[26:27], 0, v[0:1]
	s_mov_b32 m0, s64
	ds_read_b128 v[186:189], v147 offset:16384
	ds_read_b128 v[190:193], v147 offset:17408
	ds_read_b128 v[194:197], v147 offset:18432
	ds_read_b128 v[198:201], v147 offset:19456
	ds_read_b128 v[202:205], v147 offset:20480
	ds_read_b128 v[206:209], v147 offset:21504
	ds_read_b128 v[210:213], v147 offset:22528
	ds_read_b128 v[214:217], v147 offset:23552
	global_load_lds_dwordx4 v[168:169], off
	s_add_i32 m0, s64, 0x2000
	s_add_u32 s64, s26, 0x80000
	v_lshl_add_u64 v[218:219], s[26:27], 0, v[130:131]
	s_addc_u32 s65, s27, 0
	s_add_i32 s79, s5, s30
	global_load_lds_dwordx4 v[218:219], off
	v_lshl_add_u64 v[220:221], s[64:65], 0, v[0:1]
	s_mov_b32 m0, s79
	v_lshl_add_u64 v[222:223], s[28:29], 0, v[130:131]
	global_load_lds_dwordx4 v[220:221], off
	v_lshl_add_u64 v[220:221], s[64:65], 0, v[130:131]
	s_add_i32 m0, s79, 0x2000
	s_nop 0
	global_load_lds_dwordx4 v[220:221], off
	s_waitcnt vmcnt(6)
	s_waitcnt lgkmcnt(0)
	s_barrier
; #define PG8_STAGE(bufoff, gbase, voff) do { _Pragma("unroll") for (int _i = 0; _i < 2; ++_i) \
;         __builtin_amdgcn_global_load_lds((const unsigned*)((const char*)(gbase) + (voff)[_i]), (PG8_LAS unsigned*)(lds + (bufoff) + ldsw + _i * 8192), 16, 0, 0); } while (0)
; #define PG8_LDA(dst, b, h) do { _Pragma("unroll") for (int m = 0; m < 4; ++m) _Pragma("unroll") for (int k = 0; k < 2; ++k) dst[m][k] = *(const PG8_LAS bf16x8*)(lds + PG8_SA(b, h) + aoff + m * 2048 + k * 1024); } while (0)
; #define PG8_LDB(dst, b, h) do { _Pragma("unroll") for (int n = 0; n < 2; ++n) _Pragma("unroll") for (int k = 0; k < 2; ++k) dst[n][k] = *(const PG8_LAS bf16x8*)(lds + PG8_SB(b, h) + boff + n * 2048 + k * 1024); } while (0)
; #define PG8_MMA(ai, bj, At, Bt) do { __builtin_amdgcn_s_setprio(1); _Pragma("unroll") for (int m = 0; m < 4; ++m) _Pragma("unroll") for (int n = 0; n < 2; ++n) _Pragma("unroll") for (int k = 0; k < 2; ++k) \
;         acc[ai][bj][m][n] = __builtin_amdgcn_mfma_f32_16x16x32_bf16(Bt[n][k], At[m][k], acc[ai][bj][m][n], 0, 0, 0); __builtin_amdgcn_s_setprio(0); } while (0)
; #define PG8_WAIT_V(n) asm volatile("s_waitcnt vmcnt(" #n ")" ::: "memory")
; #define PG8_WAIT_L(n) asm volatile("s_waitcnt lgkmcnt(" #n ")" ::: "memory")
; #define PG8_BAR __builtin_amdgcn_s_barrier()
; #define PG8_SCHED __builtin_amdgcn_sched_barrier(0)
; template <class Epi, class Sched, bool ALIGN_EPI = false, bool SP2 = false>
; __device__ __forceinline__ void gemm_phase(PG8_LAS unsigned char* lds, const Gemm g, const Sched& S, const Epi& E, int tid_in) {
;     ...
;             PG8_WAIT_V(8); PG8_WAIT_L(0); PG8_BAR; PG8_MMA(1, 0, At, B0); PG8_MMA(1, 1, At, B1); PG8_BAR; PG8_SCHED;
;             PG8_LDB(B0, 1, 0); PG8_LDB(B1, 1, 1); PG8_SCHED; PG8_LDA(At, 1, 0); PG8_STAGE(PG8_SA(0, 1), a2 + hstepA, voffA);
;             PG8_WAIT_V(8); PG8_WAIT_L(0); PG8_BAR; PG8_MMA(0, 0, At, B0); PG8_MMA(0, 1, At, B1); PG8_BAR; PG8_SCHED;
	s_setprio 1
	s_waitcnt lgkmcnt(0)
	v_mfma_f32_16x16x32_bf16 v[62:65], v[136:139], v[186:189], v[62:65]
	v_mfma_f32_16x16x32_bf16 v[58:61], v[148:151], v[186:189], v[58:61]
	v_mfma_f32_16x16x32_bf16 v[54:57], v[136:139], v[194:197], v[54:57]
	v_mfma_f32_16x16x32_bf16 v[50:53], v[148:151], v[194:197], v[50:53]
	v_mfma_f32_16x16x32_bf16 v[46:49], v[136:139], v[202:205], v[46:49]
	v_mfma_f32_16x16x32_bf16 v[42:45], v[148:151], v[202:205], v[42:45]
	v_mfma_f32_16x16x32_bf16 v[38:41], v[136:139], v[210:213], v[38:41]
	v_mfma_f32_16x16x32_bf16 v[34:37], v[148:151], v[210:213], v[34:37]
	v_mfma_f32_16x16x32_bf16 v[62:65], v[140:143], v[190:193], v[62:65]
	v_mfma_f32_16x16x32_bf16 v[58:61], v[152:155], v[190:193], v[58:61]
	v_mfma_f32_16x16x32_bf16 v[54:57], v[140:143], v[198:201], v[54:57]
	v_mfma_f32_16x16x32_bf16 v[50:53], v[152:155], v[198:201], v[50:53]
	v_mfma_f32_16x16x32_bf16 v[46:49], v[140:143], v[206:209], v[46:49]
	v_mfma_f32_16x16x32_bf16 v[42:45], v[152:155], v[206:209], v[42:45]
	v_mfma_f32_16x16x32_bf16 v[38:41], v[140:143], v[214:217], v[38:41]
	v_mfma_f32_16x16x32_bf16 v[34:37], v[152:155], v[214:217], v[34:37]
	s_setprio 0
	s_setprio 1
	v_mfma_f32_16x16x32_bf16 v[30:33], v[156:159], v[186:189], v[30:33]
	v_mfma_f32_16x16x32_bf16 v[26:29], v[164:167], v[186:189], v[26:29]
	v_mfma_f32_16x16x32_bf16 v[22:25], v[156:159], v[194:197], v[22:25]
	v_mfma_f32_16x16x32_bf16 v[18:21], v[164:167], v[194:197], v[18:21]
	v_mfma_f32_16x16x32_bf16 v[14:17], v[156:159], v[202:205], v[14:17]
	v_mfma_f32_16x16x32_bf16 v[10:13], v[164:167], v[202:205], v[10:13]
	v_mfma_f32_16x16x32_bf16 v[6:9], v[156:159], v[210:213], v[6:9]
	v_mfma_f32_16x16x32_bf16 v[2:5], v[164:167], v[210:213], v[2:5]
	v_mfma_f32_16x16x32_bf16 v[30:33], v[160:163], v[190:193], v[30:33]
	v_mfma_f32_16x16x32_bf16 v[26:29], v[182:185], v[190:193], v[26:29]
	v_mfma_f32_16x16x32_bf16 v[22:25], v[160:163], v[198:201], v[22:25]
	v_mfma_f32_16x16x32_bf16 v[18:21], v[182:185], v[198:201], v[18:21]
	v_mfma_f32_16x16x32_bf16 v[14:17], v[160:163], v[206:209], v[14:17]
	v_mfma_f32_16x16x32_bf16 v[10:13], v[182:185], v[206:209], v[10:13]
	v_mfma_f32_16x16x32_bf16 v[6:9], v[160:163], v[214:217], v[6:9]
	v_mfma_f32_16x16x32_bf16 v[2:5], v[182:185], v[214:217], v[2:5]
	s_setprio 0
	s_barrier
	v_lshl_add_u64 v[220:221], s[28:29], 0, v[0:1]
	s_mov_b32 m0, s31
	s_nop 0
	global_load_lds_dwordx4 v[220:221], off
	s_mov_b32 m0, s33
	s_nop 0
	global_load_lds_dwordx4 v[222:223], off
	v_add_u32_e32 v152, s63, v146
	v_add_u32_e32 v182, s55, v146
	ds_read_b128 v[136:139], v152
	ds_read_b128 v[140:143], v152 offset:1024
	ds_read_b128 v[148:151], v152 offset:2048
	ds_read_b128 v[152:155], v152 offset:3072
	ds_read_b128 v[156:159], v182
	ds_read_b128 v[160:163], v182 offset:1024
	ds_read_b128 v[164:167], v182 offset:2048
	ds_read_b128 v[182:185], v182 offset:3072
	s_add_u32 s28, s28, 0x80000
	s_addc_u32 s29, s29, 0
	s_mov_b32 m0, s34
	v_lshl_add_u64 v[224:225], s[28:29], 0, v[0:1]
	ds_read_b128 v[186:189], v147 offset:32768
	ds_read_b128 v[190:193], v147 offset:33792
	ds_read_b128 v[194:197], v147 offset:34816
	ds_read_b128 v[198:201], v147 offset:35840
	ds_read_b128 v[202:205], v147 offset:36864
	ds_read_b128 v[206:209], v147 offset:37888
	ds_read_b128 v[210:213], v147 offset:38912
	ds_read_b128 v[214:217], v147 offset:39936
	global_load_lds_dwordx4 v[224:225], off
	v_lshl_add_u64 v[224:225], s[28:29], 0, v[130:131]
	s_mov_b32 m0, s35
	s_nop 0
	global_load_lds_dwordx4 v[224:225], off
	s_waitcnt vmcnt(8)
	s_waitcnt lgkmcnt(0)
	s_barrier
	s_setprio 1
	s_waitcnt lgkmcnt(0)
	v_mfma_f32_16x16x32_bf16 v[126:129], v[136:139], v[186:189], v[126:129]
	v_mfma_f32_16x16x32_bf16 v[122:125], v[148:151], v[186:189], v[122:125]
	v_mfma_f32_16x16x32_bf16 v[118:121], v[136:139], v[194:197], v[118:121]
	v_mfma_f32_16x16x32_bf16 v[114:117], v[148:151], v[194:197], v[114:117]
	v_mfma_f32_16x16x32_bf16 v[110:113], v[136:139], v[202:205], v[110:113]
	v_mfma_f32_16x16x32_bf16 v[106:109], v[148:151], v[202:205], v[106:109]
	v_mfma_f32_16x16x32_bf16 v[102:105], v[136:139], v[210:213], v[102:105]
	v_mfma_f32_16x16x32_bf16 v[98:101], v[148:151], v[210:213], v[98:101]
	v_mfma_f32_16x16x32_bf16 v[126:129], v[140:143], v[190:193], v[126:129]
	v_mfma_f32_16x16x32_bf16 v[122:125], v[152:155], v[190:193], v[122:125]
	v_mfma_f32_16x16x32_bf16 v[118:121], v[140:143], v[198:201], v[118:121]
	v_mfma_f32_16x16x32_bf16 v[114:117], v[152:155], v[198:201], v[114:117]
	v_mfma_f32_16x16x32_bf16 v[110:113], v[140:143], v[206:209], v[110:113]
	v_mfma_f32_16x16x32_bf16 v[106:109], v[152:155], v[206:209], v[106:109]
	v_mfma_f32_16x16x32_bf16 v[102:105], v[140:143], v[214:217], v[102:105]
	v_mfma_f32_16x16x32_bf16 v[98:101], v[152:155], v[214:217], v[98:101]
	s_setprio 0
	s_setprio 1
	v_mfma_f32_16x16x32_bf16 v[94:97], v[156:159], v[186:189], v[94:97]
	v_mfma_f32_16x16x32_bf16 v[90:93], v[164:167], v[186:189], v[90:93]
	v_mfma_f32_16x16x32_bf16 v[86:89], v[156:159], v[194:197], v[86:89]
	v_mfma_f32_16x16x32_bf16 v[82:85], v[164:167], v[194:197], v[82:85]
	v_mfma_f32_16x16x32_bf16 v[78:81], v[156:159], v[202:205], v[78:81]
	v_mfma_f32_16x16x32_bf16 v[74:77], v[164:167], v[202:205], v[74:77]
	v_mfma_f32_16x16x32_bf16 v[70:73], v[156:159], v[210:213], v[70:73]
	v_mfma_f32_16x16x32_bf16 v[66:69], v[164:167], v[210:213], v[66:69]
	v_mfma_f32_16x16x32_bf16 v[94:97], v[160:163], v[190:193], v[94:97]
	v_mfma_f32_16x16x32_bf16 v[90:93], v[182:185], v[190:193], v[90:93]
	v_mfma_f32_16x16x32_bf16 v[86:89], v[160:163], v[198:201], v[86:89]
	v_mfma_f32_16x16x32_bf16 v[82:85], v[182:185], v[198:201], v[82:85]
	v_mfma_f32_16x16x32_bf16 v[78:81], v[160:163], v[206:209], v[78:81]
	v_mfma_f32_16x16x32_bf16 v[74:77], v[182:185], v[206:209], v[74:77]
	v_mfma_f32_16x16x32_bf16 v[70:73], v[160:163], v[214:217], v[70:73]
	v_mfma_f32_16x16x32_bf16 v[66:69], v[182:185], v[214:217], v[66:69]
	s_setprio 0
	s_barrier
; #define PG8_STAGE(bufoff, gbase, voff) do { _Pragma("unroll") for (int _i = 0; _i < 2; ++_i) \
;         __builtin_amdgcn_global_load_lds((const unsigned*)((const char*)(gbase) + (voff)[_i]), (PG8_LAS unsigned*)(lds + (bufoff) + ldsw + _i * 8192), 16, 0, 0); } while (0)
; #define PG8_LDA(dst, b, h) do { _Pragma("unroll") for (int m = 0; m < 4; ++m) _Pragma("unroll") for (int k = 0; k < 2; ++k) dst[m][k] = *(const PG8_LAS bf16x8*)(lds + PG8_SA(b, h) + aoff + m * 2048 + k * 1024); } while (0)
; #define PG8_MMA(ai, bj, At, Bt) do { __builtin_amdgcn_s_setprio(1); _Pragma("unroll") for (int m = 0; m < 4; ++m) _Pragma("unroll") for (int n = 0; n < 2; ++n) _Pragma("unroll") for (int k = 0; k < 2; ++k) \
;         acc[ai][bj][m][n] = __builtin_amdgcn_mfma_f32_16x16x32_bf16(Bt[n][k], At[m][k], acc[ai][bj][m][n], 0, 0, 0); __builtin_amdgcn_s_setprio(0); } while (0)
; #define PG8_WAIT_V(n) asm volatile("s_waitcnt vmcnt(" #n ")" ::: "memory")
; #define PG8_WAIT_L(n) asm volatile("s_waitcnt lgkmcnt(" #n ")" ::: "memory")
; #define PG8_BAR __builtin_amdgcn_s_barrier()
; #define PG8_SCHED __builtin_amdgcn_sched_barrier(0)
; template <class Epi, class Sched, bool ALIGN_EPI = false, bool SP2 = false>
; __device__ __forceinline__ void gemm_phase(PG8_LAS unsigned char* lds, const Gemm g, const Sched& S, const Epi& E, int tid_in) {
;     ...
;             PG8_LDA(At, 1, 1); PG8_STAGE(PG8_SB(1, 0), b3, voffB); PG8_STAGE(PG8_SB(1, 1), b3 + hstep, voffB); PG8_STAGE(PG8_SA(1, 0), a3, voffA);
;             PG8_WAIT_V(8); PG8_WAIT_L(0); PG8_BAR; PG8_MMA(1, 0, At, B0); PG8_MMA(1, 1, At, B1); PG8_BAR; PG8_SCHED;
	s_add_i32 s28, s63, s30
	v_lshl_add_u64 v[168:169], v[168:169], 0, s[90:91]
	s_mov_b32 m0, s28
	ds_read_b128 v[186:189], v147 offset:49152
	ds_read_b128 v[190:193], v147 offset:50176
	ds_read_b128 v[194:197], v147 offset:51200
	ds_read_b128 v[198:201], v147 offset:52224
	ds_read_b128 v[202:205], v147 offset:53248
	ds_read_b128 v[206:209], v147 offset:54272
	ds_read_b128 v[210:213], v147 offset:55296
	ds_read_b128 v[214:217], v147 offset:56320
	global_load_lds_dwordx4 v[168:169], off
	s_add_i32 m0, s28, 0x2000
	s_add_u32 s26, s26, 0x80080
	v_lshl_add_u64 v[168:169], v[218:219], 0, s[90:91]
	s_addc_u32 s27, s27, 0
	s_add_i32 s28, s55, s30
	global_load_lds_dwordx4 v[168:169], off
	v_lshl_add_u64 v[168:169], s[26:27], 0, v[0:1]
	s_mov_b32 m0, s28
	s_nop 0
	global_load_lds_dwordx4 v[168:169], off
	v_lshl_add_u64 v[168:169], s[26:27], 0, v[130:131]
	s_add_i32 m0, s28, 0x2000
	s_nop 0
	global_load_lds_dwordx4 v[168:169], off
	v_lshl_add_u64 v[220:221], v[220:221], 0, s[90:91]
	v_lshl_add_u64 v[222:223], v[222:223], 0, s[90:91]
	s_add_u32 s24, s24, 0x100
	s_addc_u32 s25, s25, 0
	s_add_u32 s68, s68, 0x100
	s_addc_u32 s70, s70, 0
	s_cmp_ge_u32 s76, s45
	s_mov_b32 s26, s76
	s_waitcnt vmcnt(6)
	s_waitcnt lgkmcnt(0)
	s_barrier
	s_setprio 1
	s_waitcnt lgkmcnt(0)
	v_mfma_f32_16x16x32_bf16 v[62:65], v[136:139], v[186:189], v[62:65]
	v_mfma_f32_16x16x32_bf16 v[58:61], v[148:151], v[186:189], v[58:61]
	v_mfma_f32_16x16x32_bf16 v[54:57], v[136:139], v[194:197], v[54:57]
	v_mfma_f32_16x16x32_bf16 v[50:53], v[148:151], v[194:197], v[50:53]
	v_mfma_f32_16x16x32_bf16 v[46:49], v[136:139], v[202:205], v[46:49]
	v_mfma_f32_16x16x32_bf16 v[42:45], v[148:151], v[202:205], v[42:45]
	v_mfma_f32_16x16x32_bf16 v[38:41], v[136:139], v[210:213], v[38:41]
	v_mfma_f32_16x16x32_bf16 v[34:37], v[148:151], v[210:213], v[34:37]
	v_mfma_f32_16x16x32_bf16 v[62:65], v[140:143], v[190:193], v[62:65]
	v_mfma_f32_16x16x32_bf16 v[58:61], v[152:155], v[190:193], v[58:61]
	v_mfma_f32_16x16x32_bf16 v[54:57], v[140:143], v[198:201], v[54:57]
	v_mfma_f32_16x16x32_bf16 v[50:53], v[152:155], v[198:201], v[50:53]
	v_mfma_f32_16x16x32_bf16 v[46:49], v[140:143], v[206:209], v[46:49]
	v_mfma_f32_16x16x32_bf16 v[42:45], v[152:155], v[206:209], v[42:45]
	v_mfma_f32_16x16x32_bf16 v[38:41], v[140:143], v[214:217], v[38:41]
	v_mfma_f32_16x16x32_bf16 v[34:37], v[152:155], v[214:217], v[34:37]
	s_setprio 0
	s_setprio 1
	v_mfma_f32_16x16x32_bf16 v[30:33], v[156:159], v[186:189], v[30:33]
	v_mfma_f32_16x16x32_bf16 v[26:29], v[164:167], v[186:189], v[26:29]
	v_mfma_f32_16x16x32_bf16 v[22:25], v[156:159], v[194:197], v[22:25]
	v_mfma_f32_16x16x32_bf16 v[18:21], v[164:167], v[194:197], v[18:21]
	v_mfma_f32_16x16x32_bf16 v[14:17], v[156:159], v[202:205], v[14:17]
	v_mfma_f32_16x16x32_bf16 v[10:13], v[164:167], v[202:205], v[10:13]
	v_mfma_f32_16x16x32_bf16 v[6:9], v[156:159], v[210:213], v[6:9]
	v_mfma_f32_16x16x32_bf16 v[2:5], v[164:167], v[210:213], v[2:5]
	v_mfma_f32_16x16x32_bf16 v[30:33], v[160:163], v[190:193], v[30:33]
	v_mfma_f32_16x16x32_bf16 v[26:29], v[182:185], v[190:193], v[26:29]
	v_mfma_f32_16x16x32_bf16 v[22:25], v[160:163], v[198:201], v[22:25]
	v_mfma_f32_16x16x32_bf16 v[18:21], v[182:185], v[198:201], v[18:21]
	v_mfma_f32_16x16x32_bf16 v[14:17], v[160:163], v[206:209], v[14:17]
	v_mfma_f32_16x16x32_bf16 v[10:13], v[182:185], v[206:209], v[10:13]
	v_mfma_f32_16x16x32_bf16 v[6:9], v[160:163], v[214:217], v[6:9]
	v_mfma_f32_16x16x32_bf16 v[2:5], v[182:185], v[214:217], v[2:5]
	s_setprio 0
	s_barrier
	s_cbranch_scc0 .Lbal_top_1348
	s_mov_b32 m0, s41
	s_nop 0
	global_load_lds_dwordx4 v[220:221], off
	s_mov_b32 m0, s42
	s_nop 0
	global_load_lds_dwordx4 v[222:223], off
	s_and_b64 vcc, exec, s[16:17]
	s_cbranch_vccz .LBB0_1351
	s_barrier

; #define PG8_LAS __attribute__((address_space(3)))
; #define PG8_STAGE(bufoff, gbase, voff) do { _Pragma("unroll") for (int _i = 0; _i < 2; ++_i) \
;         __builtin_amdgcn_global_load_lds((const unsigned*)((const char*)(gbase) + (voff)[_i]), (PG8_LAS unsigned*)(lds + (bufoff) + ldsw + _i * 8192), 16, 0, 0); } while (0)
; #define PG8_LDA(dst, b, h) do { _Pragma("unroll") for (int m = 0; m < 4; ++m) _Pragma("unroll") for (int k = 0; k < 2; ++k) dst[m][k] = *(const PG8_LAS bf16x8*)(lds + PG8_SA(b, h) + aoff + m * 2048 + k * 1024); } while (0)
; #define PG8_LDB(dst, b, h) do { _Pragma("unroll") for (int n = 0; n < 2; ++n) _Pragma("unroll") for (int k = 0; k < 2; ++k) dst[n][k] = *(const PG8_LAS bf16x8*)(lds + PG8_SB(b, h) + boff + n * 2048 + k * 1024); } while (0)
; #define PG8_WAIT_V(n) asm volatile("s_waitcnt vmcnt(" #n ")" ::: "memory")
; #define PG8_WAIT_L(n) asm volatile("s_waitcnt lgkmcnt(" #n ")" ::: "memory")
; #define PG8_BAR __builtin_amdgcn_s_barrier()
; #define PG8_SCHED __builtin_amdgcn_sched_barrier(0)
; template <class Epi, class Sched, bool ALIGN_EPI = false, bool SP2 = false>
; __device__ __forceinline__ void gemm_phase(PG8_LAS unsigned char* lds, const Gemm g, const Sched& S, const Epi& E, int tid_in) {
;     ...
;         if constexpr (rowsc_of<Epi>::v) __builtin_amdgcn_global_load_lds((const unsigned*)(E.SSQ + cur.pm * BM + lane * 4), (PG8_LAS unsigned*)(lds + RS_LDS_OFF + wid * 1024), 16, 0, 0);
;         for (int t = 0; t < nt; t += 2) {
;             const bool last = (t == nt - 2);
;             const char* a1 = cA + (size_t)(t + 1) * kstep;
;             const char* a2 = last ? nA : cA + (size_t)(t + 2) * kstep; const char* b2 = last ? nB : cB + (size_t)(t + 2) * kstep;
;             const char* a3 = a2 + kstep; const char* b3 = b2 + kstep;
;             if (last && has_next) S.a_ready(nxt);
;             if constexpr (SP2) {
;             PG8_LDB(B0, 0, 0); PG8_LDB(B1, 0, 1); PG8_SCHED; PG8_LDA(At, 0, 0); PG8_STAGE(PG8_SA(1, 1), a1 + hstepA, voffA);
;             PG8_WAIT_V(8); PG8_WAIT_L(0); PG8_BAR; PG8_MMA(0, 0, At, B0); PG8_MMA(0, 1, At, B1); PG8_BAR; PG8_SCHED;
;     ...
;         for (int a = 0; a < 2; ++a)
; #pragma unroll
;             for (int b = 0; b < 2; ++b)
; #pragma unroll
;                 for (int m = 0; m < 4; ++m)
; #pragma unroll
;                     for (int n = 0; n < 2; ++n) acc[a][b][m][n] = (f32x4){0.f, 0.f, 0.f, 0.f};
.LBB0_1506:
	s_lshl_b32 s22, s28, 8
	s_ashr_i32 s23, s22, 31
	s_mov_b32 m0, s43
	v_lshl_add_u64 v[2:3], s[22:23], 2, v[136:137]
	global_load_lds_dwordx4 v[2:3], off
	s_add_u32 s24, s24, 0x80080
	s_addc_u32 s25, s25, 0
	s_add_u32 s15, s26, 0x100
	v_mov_b32_e32 v2, 0
	s_addc_u32 s17, s27, 0
	s_mov_b32 s23, -2
	v_mov_b32_e32 v3, v2
	v_mov_b32_e32 v4, v2
	v_mov_b32_e32 v5, v2
	v_mov_b32_e32 v10, v2
	v_mov_b32_e32 v11, v2
	v_mov_b32_e32 v12, v2
	v_mov_b32_e32 v13, v2
	v_mov_b32_e32 v18, v2
	v_mov_b32_e32 v19, v2
	v_mov_b32_e32 v20, v2
	v_mov_b32_e32 v21, v2
	v_mov_b32_e32 v26, v2
	v_mov_b32_e32 v27, v2
	v_mov_b32_e32 v28, v2
	v_mov_b32_e32 v29, v2
	v_mov_b32_e32 v34, v2
	v_mov_b32_e32 v35, v2
	v_mov_b32_e32 v36, v2
	v_mov_b32_e32 v37, v2
	v_mov_b32_e32 v42, v2
	v_mov_b32_e32 v43, v2
	v_mov_b32_e32 v44, v2
	v_mov_b32_e32 v45, v2
	v_mov_b32_e32 v50, v2
	v_mov_b32_e32 v51, v2
	v_mov_b32_e32 v52, v2
	v_mov_b32_e32 v53, v2
	v_mov_b32_e32 v58, v2
	v_mov_b32_e32 v59, v2
	v_mov_b32_e32 v60, v2
	v_mov_b32_e32 v61, v2
	v_mov_b32_e32 v6, v2
	v_mov_b32_e32 v7, v2
	v_mov_b32_e32 v8, v2
	v_mov_b32_e32 v9, v2
	v_mov_b32_e32 v14, v2
	v_mov_b32_e32 v15, v2
	v_mov_b32_e32 v16, v2
	v_mov_b32_e32 v17, v2
	v_mov_b32_e32 v22, v2
	v_mov_b32_e32 v23, v2
	v_mov_b32_e32 v24, v2
	v_mov_b32_e32 v25, v2
	v_mov_b32_e32 v30, v2
	v_mov_b32_e32 v31, v2
	v_mov_b32_e32 v32, v2
	v_mov_b32_e32 v33, v2
	v_mov_b32_e32 v38, v2
	v_mov_b32_e32 v39, v2
	v_mov_b32_e32 v40, v2
	v_mov_b32_e32 v41, v2
	v_mov_b32_e32 v46, v2
	v_mov_b32_e32 v47, v2
	v_mov_b32_e32 v48, v2
	v_mov_b32_e32 v49, v2
	v_mov_b32_e32 v54, v2
	v_mov_b32_e32 v55, v2
	v_mov_b32_e32 v56, v2
	v_mov_b32_e32 v57, v2
	v_mov_b32_e32 v62, v2
	v_mov_b32_e32 v63, v2
	v_mov_b32_e32 v64, v2
	v_mov_b32_e32 v65, v2
	v_mov_b32_e32 v66, v2
	v_mov_b32_e32 v67, v2
	v_mov_b32_e32 v68, v2
	v_mov_b32_e32 v69, v2
	v_mov_b32_e32 v74, v2
	v_mov_b32_e32 v75, v2
	v_mov_b32_e32 v76, v2
	v_mov_b32_e32 v77, v2
	v_mov_b32_e32 v82, v2
	v_mov_b32_e32 v83, v2
	v_mov_b32_e32 v84, v2
	v_mov_b32_e32 v85, v2
	v_mov_b32_e32 v90, v2
	v_mov_b32_e32 v91, v2
	v_mov_b32_e32 v92, v2
	v_mov_b32_e32 v93, v2
	v_mov_b32_e32 v98, v2
	v_mov_b32_e32 v99, v2
	v_mov_b32_e32 v100, v2
	v_mov_b32_e32 v101, v2
	v_mov_b32_e32 v106, v2
	v_mov_b32_e32 v107, v2
	v_mov_b32_e32 v108, v2
	v_mov_b32_e32 v109, v2
	v_mov_b32_e32 v114, v2
	v_mov_b32_e32 v115, v2
	v_mov_b32_e32 v116, v2
	v_mov_b32_e32 v117, v2
	v_mov_b32_e32 v122, v2
	v_mov_b32_e32 v123, v2
	v_mov_b32_e32 v124, v2
	v_mov_b32_e32 v125, v2
	v_mov_b32_e32 v70, v2
	v_mov_b32_e32 v71, v2
	v_mov_b32_e32 v72, v2
	v_mov_b32_e32 v73, v2
	v_mov_b32_e32 v78, v2
	v_mov_b32_e32 v79, v2
	v_mov_b32_e32 v80, v2
	v_mov_b32_e32 v81, v2
	v_mov_b32_e32 v86, v2
	v_mov_b32_e32 v87, v2
	v_mov_b32_e32 v88, v2
	v_mov_b32_e32 v89, v2
	v_mov_b32_e32 v94, v2
	v_mov_b32_e32 v95, v2
	v_mov_b32_e32 v96, v2
	v_mov_b32_e32 v97, v2
	v_mov_b32_e32 v102, v2
	v_mov_b32_e32 v103, v2
	v_mov_b32_e32 v104, v2
	v_mov_b32_e32 v105, v2
	v_mov_b32_e32 v110, v2
	v_mov_b32_e32 v111, v2
	v_mov_b32_e32 v112, v2
	v_mov_b32_e32 v113, v2
	v_mov_b32_e32 v118, v2
	v_mov_b32_e32 v119, v2
	v_mov_b32_e32 v120, v2
	v_mov_b32_e32 v121, v2
	v_mov_b32_e32 v126, v2
	v_mov_b32_e32 v127, v2
	v_mov_b32_e32 v128, v2
	v_mov_b32_e32 v129, v2
	s_branch .LBB0_1507
.Lbal_top_1507:
	s_mov_b32 m0, s41
	s_nop 0
	global_load_lds_dwordx4 v[226:227], off
	s_mov_b32 m0, s42
	s_nop 0
	global_load_lds_dwordx4 v[228:229], off
.LBB0_1507:
	v_add_u32_e32 v158, s4, v152
	v_add_u32_e32 v186, s5, v152
	ds_read_b128 v[142:145], v158
	ds_read_b128 v[146:149], v158 offset:1024
	ds_read_b128 v[154:157], v158 offset:2048
	ds_read_b128 v[158:161], v158 offset:3072
	ds_read_b128 v[162:165], v186
	ds_read_b128 v[166:169], v186 offset:1024
	ds_read_b128 v[182:185], v186 offset:2048
	ds_read_b128 v[186:189], v186 offset:3072
	s_add_u32 s26, s24, 0xfff80080
	s_addc_u32 s27, s25, -1
	s_cmp_eq_u32 s23, 28
	s_cselect_b32 s29, s19, s27
	s_cselect_b32 s28, s18, s26
	s_cselect_b32 s27, s21, s17
	s_cselect_b32 s26, s20, s15
	v_lshl_add_u64 v[222:223], s[24:25], 0, v[138:139]
	s_add_i32 m0, s35, 0xc000
	ds_read_b128 v[190:193], v153
	ds_read_b128 v[194:197], v153 offset:1024
	ds_read_b128 v[198:201], v153 offset:2048
	ds_read_b128 v[202:205], v153 offset:3072
	ds_read_b128 v[206:209], v153 offset:4096
	ds_read_b128 v[210:213], v153 offset:5120
	ds_read_b128 v[214:217], v153 offset:6144
	ds_read_b128 v[218:221], v153 offset:7168
	global_load_lds_dwordx4 v[222:223], off
	v_lshl_add_u64 v[222:223], s[24:25], 0, v[140:141]
	s_add_i32 m0, s35, 0xe000
	s_nop 0
	global_load_lds_dwordx4 v[222:223], off
	s_waitcnt vmcnt(8)
	s_waitcnt lgkmcnt(0)
	s_barrier
; #define PG8_STAGE(bufoff, gbase, voff) do { _Pragma("unroll") for (int _i = 0; _i < 2; ++_i) \
;         __builtin_amdgcn_global_load_lds((const unsigned*)((const char*)(gbase) + (voff)[_i]), (PG8_LAS unsigned*)(lds + (bufoff) + ldsw + _i * 8192), 16, 0, 0); } while (0)
; #define PG8_LDA(dst, b, h) do { _Pragma("unroll") for (int m = 0; m < 4; ++m) _Pragma("unroll") for (int k = 0; k < 2; ++k) dst[m][k] = *(const PG8_LAS bf16x8*)(lds + PG8_SA(b, h) + aoff + m * 2048 + k * 1024); } while (0)
; #define PG8_MMA(ai, bj, At, Bt) do { __builtin_amdgcn_s_setprio(1); _Pragma("unroll") for (int m = 0; m < 4; ++m) _Pragma("unroll") for (int n = 0; n < 2; ++n) _Pragma("unroll") for (int k = 0; k < 2; ++k) \
;         acc[ai][bj][m][n] = __builtin_amdgcn_mfma_f32_16x16x32_bf16(Bt[n][k], At[m][k], acc[ai][bj][m][n], 0, 0, 0); __builtin_amdgcn_s_setprio(0); } while (0)
; #define PG8_WAIT_V(n) asm volatile("s_waitcnt vmcnt(" #n ")" ::: "memory")
; #define PG8_WAIT_L(n) asm volatile("s_waitcnt lgkmcnt(" #n ")" ::: "memory")
; #define PG8_BAR __builtin_amdgcn_s_barrier()
; #define PG8_SCHED __builtin_amdgcn_sched_barrier(0)
; template <class Epi, class Sched, bool ALIGN_EPI = false, bool SP2 = false>
; __device__ __forceinline__ void gemm_phase(PG8_LAS unsigned char* lds, const Gemm g, const Sched& S, const Epi& E, int tid_in) {
;     ...
;             PG8_WAIT_V(8); PG8_WAIT_L(0); PG8_BAR; PG8_MMA(0, 0, At, B0); PG8_MMA(0, 1, At, B1); PG8_BAR; PG8_SCHED;
;             PG8_LDA(At, 0, 1); PG8_STAGE(PG8_SB(0, 0), b2, voffB); PG8_STAGE(PG8_SB(0, 1), b2 + hstep, voffB); PG8_STAGE(PG8_SA(0, 0), a2, voffA);
;             PG8_WAIT_V(8); PG8_WAIT_L(0); PG8_BAR; PG8_MMA(1, 0, At, B0); PG8_MMA(1, 1, At, B1); PG8_BAR; PG8_SCHED;
	s_setprio 1
	s_waitcnt lgkmcnt(0)
	v_mfma_f32_16x16x32_bf16 v[126:129], v[142:145], v[190:193], v[126:129]
	v_mfma_f32_16x16x32_bf16 v[118:121], v[154:157], v[190:193], v[118:121]
	v_mfma_f32_16x16x32_bf16 v[110:113], v[142:145], v[198:201], v[110:113]
	v_mfma_f32_16x16x32_bf16 v[102:105], v[154:157], v[198:201], v[102:105]
	v_mfma_f32_16x16x32_bf16 v[94:97], v[142:145], v[206:209], v[94:97]
	v_mfma_f32_16x16x32_bf16 v[86:89], v[154:157], v[206:209], v[86:89]
	v_mfma_f32_16x16x32_bf16 v[78:81], v[142:145], v[214:217], v[78:81]
	v_mfma_f32_16x16x32_bf16 v[70:73], v[154:157], v[214:217], v[70:73]
	v_mfma_f32_16x16x32_bf16 v[126:129], v[146:149], v[194:197], v[126:129]
	v_mfma_f32_16x16x32_bf16 v[118:121], v[158:161], v[194:197], v[118:121]
	v_mfma_f32_16x16x32_bf16 v[110:113], v[146:149], v[202:205], v[110:113]
	v_mfma_f32_16x16x32_bf16 v[102:105], v[158:161], v[202:205], v[102:105]
	v_mfma_f32_16x16x32_bf16 v[94:97], v[146:149], v[210:213], v[94:97]
	v_mfma_f32_16x16x32_bf16 v[86:89], v[158:161], v[210:213], v[86:89]
	v_mfma_f32_16x16x32_bf16 v[78:81], v[146:149], v[218:221], v[78:81]
	v_mfma_f32_16x16x32_bf16 v[70:73], v[158:161], v[218:221], v[70:73]
	s_setprio 0
	s_setprio 1
	v_mfma_f32_16x16x32_bf16 v[122:125], v[162:165], v[190:193], v[122:125]
	v_mfma_f32_16x16x32_bf16 v[114:117], v[182:185], v[190:193], v[114:117]
	v_mfma_f32_16x16x32_bf16 v[106:109], v[162:165], v[198:201], v[106:109]
	v_mfma_f32_16x16x32_bf16 v[98:101], v[182:185], v[198:201], v[98:101]
	v_mfma_f32_16x16x32_bf16 v[90:93], v[162:165], v[206:209], v[90:93]
	v_mfma_f32_16x16x32_bf16 v[82:85], v[182:185], v[206:209], v[82:85]
	v_mfma_f32_16x16x32_bf16 v[74:77], v[162:165], v[214:217], v[74:77]
	v_mfma_f32_16x16x32_bf16 v[66:69], v[182:185], v[214:217], v[66:69]
	v_mfma_f32_16x16x32_bf16 v[122:125], v[166:169], v[194:197], v[122:125]
	v_mfma_f32_16x16x32_bf16 v[114:117], v[186:189], v[194:197], v[114:117]
	v_mfma_f32_16x16x32_bf16 v[106:109], v[166:169], v[202:205], v[106:109]
	v_mfma_f32_16x16x32_bf16 v[98:101], v[186:189], v[202:205], v[98:101]
	v_mfma_f32_16x16x32_bf16 v[90:93], v[166:169], v[210:213], v[90:93]
	v_mfma_f32_16x16x32_bf16 v[82:85], v[186:189], v[210:213], v[82:85]
	v_mfma_f32_16x16x32_bf16 v[74:77], v[166:169], v[218:221], v[74:77]
	v_mfma_f32_16x16x32_bf16 v[66:69], v[186:189], v[218:221], v[66:69]
	s_setprio 0
	s_barrier
	s_add_i32 s47, s4, s34
	v_lshl_add_u64 v[222:223], s[26:27], 0, v[0:1]
	s_mov_b32 m0, s47
	ds_read_b128 v[190:193], v153 offset:16384
	ds_read_b128 v[194:197], v153 offset:17408
	ds_read_b128 v[198:201], v153 offset:18432
	ds_read_b128 v[202:205], v153 offset:19456
	ds_read_b128 v[206:209], v153 offset:20480
	ds_read_b128 v[210:213], v153 offset:21504
	ds_read_b128 v[214:217], v153 offset:22528
	ds_read_b128 v[218:221], v153 offset:23552
	global_load_lds_dwordx4 v[222:223], off
	s_add_i32 m0, s47, 0x2000
	s_add_u32 s48, s26, 0x80000
	v_lshl_add_u64 v[224:225], s[26:27], 0, v[130:131]
	s_addc_u32 s49, s27, 0
	s_add_i32 s47, s5, s34
	global_load_lds_dwordx4 v[224:225], off
	v_lshl_add_u64 v[226:227], s[48:49], 0, v[0:1]
	s_mov_b32 m0, s47
	v_lshl_add_u64 v[228:229], s[28:29], 0, v[132:133]
	global_load_lds_dwordx4 v[226:227], off
	v_lshl_add_u64 v[226:227], s[48:49], 0, v[130:131]
	s_add_i32 m0, s47, 0x2000
	s_nop 0
	global_load_lds_dwordx4 v[226:227], off
	s_waitcnt vmcnt(6)
	s_waitcnt lgkmcnt(0)
	s_barrier
	s_setprio 1
	s_waitcnt lgkmcnt(0)
	v_mfma_f32_16x16x32_bf16 v[62:65], v[142:145], v[190:193], v[62:65]
	v_mfma_f32_16x16x32_bf16 v[54:57], v[154:157], v[190:193], v[54:57]
	v_mfma_f32_16x16x32_bf16 v[46:49], v[142:145], v[198:201], v[46:49]
	v_mfma_f32_16x16x32_bf16 v[38:41], v[154:157], v[198:201], v[38:41]
	v_mfma_f32_16x16x32_bf16 v[30:33], v[142:145], v[206:209], v[30:33]
	v_mfma_f32_16x16x32_bf16 v[22:25], v[154:157], v[206:209], v[22:25]
	v_mfma_f32_16x16x32_bf16 v[14:17], v[142:145], v[214:217], v[14:17]
	v_mfma_f32_16x16x32_bf16 v[6:9], v[154:157], v[214:217], v[6:9]
	v_mfma_f32_16x16x32_bf16 v[62:65], v[146:149], v[194:197], v[62:65]
	v_mfma_f32_16x16x32_bf16 v[54:57], v[158:161], v[194:197], v[54:57]
	v_mfma_f32_16x16x32_bf16 v[46:49], v[146:149], v[202:205], v[46:49]
	v_mfma_f32_16x16x32_bf16 v[38:41], v[158:161], v[202:205], v[38:41]
	v_mfma_f32_16x16x32_bf16 v[30:33], v[146:149], v[210:213], v[30:33]
	v_mfma_f32_16x16x32_bf16 v[22:25], v[158:161], v[210:213], v[22:25]
	v_mfma_f32_16x16x32_bf16 v[14:17], v[146:149], v[218:221], v[14:17]
	v_mfma_f32_16x16x32_bf16 v[6:9], v[158:161], v[218:221], v[6:9]
	s_setprio 0
	s_setprio 1
	v_mfma_f32_16x16x32_bf16 v[58:61], v[162:165], v[190:193], v[58:61]
	v_mfma_f32_16x16x32_bf16 v[50:53], v[182:185], v[190:193], v[50:53]
	v_mfma_f32_16x16x32_bf16 v[42:45], v[162:165], v[198:201], v[42:45]
	v_mfma_f32_16x16x32_bf16 v[34:37], v[182:185], v[198:201], v[34:37]
	v_mfma_f32_16x16x32_bf16 v[26:29], v[162:165], v[206:209], v[26:29]
	v_mfma_f32_16x16x32_bf16 v[18:21], v[182:185], v[206:209], v[18:21]
	v_mfma_f32_16x16x32_bf16 v[10:13], v[162:165], v[214:217], v[10:13]
	v_mfma_f32_16x16x32_bf16 v[2:5], v[182:185], v[214:217], v[2:5]
	v_mfma_f32_16x16x32_bf16 v[58:61], v[166:169], v[194:197], v[58:61]
	v_mfma_f32_16x16x32_bf16 v[50:53], v[186:189], v[194:197], v[50:53]
	v_mfma_f32_16x16x32_bf16 v[42:45], v[166:169], v[202:205], v[42:45]
	v_mfma_f32_16x16x32_bf16 v[34:37], v[186:189], v[202:205], v[34:37]
	v_mfma_f32_16x16x32_bf16 v[26:29], v[166:169], v[210:213], v[26:29]
	v_mfma_f32_16x16x32_bf16 v[18:21], v[186:189], v[210:213], v[18:21]
	v_mfma_f32_16x16x32_bf16 v[10:13], v[166:169], v[218:221], v[10:13]
	v_mfma_f32_16x16x32_bf16 v[2:5], v[186:189], v[218:221], v[2:5]
	s_setprio 0
	s_barrier
; #define PG8_STAGE(bufoff, gbase, voff) do { _Pragma("unroll") for (int _i = 0; _i < 2; ++_i) \
;         __builtin_amdgcn_global_load_lds((const unsigned*)((const char*)(gbase) + (voff)[_i]), (PG8_LAS unsigned*)(lds + (bufoff) + ldsw + _i * 8192), 16, 0, 0); } while (0)
; #define PG8_LDA(dst, b, h) do { _Pragma("unroll") for (int m = 0; m < 4; ++m) _Pragma("unroll") for (int k = 0; k < 2; ++k) dst[m][k] = *(const PG8_LAS bf16x8*)(lds + PG8_SA(b, h) + aoff + m * 2048 + k * 1024); } while (0)
; #define PG8_LDB(dst, b, h) do { _Pragma("unroll") for (int n = 0; n < 2; ++n) _Pragma("unroll") for (int k = 0; k < 2; ++k) dst[n][k] = *(const PG8_LAS bf16x8*)(lds + PG8_SB(b, h) + boff + n * 2048 + k * 1024); } while (0)
; #define PG8_MMA(ai, bj, At, Bt) do { __builtin_amdgcn_s_setprio(1); _Pragma("unroll") for (int m = 0; m < 4; ++m) _Pragma("unroll") for (int n = 0; n < 2; ++n) _Pragma("unroll") for (int k = 0; k < 2; ++k) \
;         acc[ai][bj][m][n] = __builtin_amdgcn_mfma_f32_16x16x32_bf16(Bt[n][k], At[m][k], acc[ai][bj][m][n], 0, 0, 0); __builtin_amdgcn_s_setprio(0); } while (0)
; #define PG8_WAIT_V(n) asm volatile("s_waitcnt vmcnt(" #n ")" ::: "memory")
; #define PG8_WAIT_L(n) asm volatile("s_waitcnt lgkmcnt(" #n ")" ::: "memory")
; #define PG8_BAR __builtin_amdgcn_s_barrier()
; #define PG8_SCHED __builtin_amdgcn_sched_barrier(0)
; template <class Epi, class Sched, bool ALIGN_EPI = false, bool SP2 = false>
; __device__ __forceinline__ void gemm_phase(PG8_LAS unsigned char* lds, const Gemm g, const Sched& S, const Epi& E, int tid_in) {
;     ...
;             PG8_LDB(B0, 1, 0); PG8_LDB(B1, 1, 1); PG8_SCHED; PG8_LDA(At, 1, 0); PG8_STAGE(PG8_SA(0, 1), a2 + hstepA, voffA);
;             PG8_WAIT_V(8); PG8_WAIT_L(0); PG8_BAR; PG8_MMA(0, 0, At, B0); PG8_MMA(0, 1, At, B1); PG8_BAR; PG8_SCHED;
	v_lshl_add_u64 v[226:227], s[28:29], 0, v[134:135]
	s_mov_b32 m0, s35
	s_nop 0
	global_load_lds_dwordx4 v[226:227], off
	s_mov_b32 m0, s36
	s_nop 0
	global_load_lds_dwordx4 v[228:229], off
	v_add_u32_e32 v158, s63, v152
	v_add_u32_e32 v186, s55, v152
	ds_read_b128 v[142:145], v158
	ds_read_b128 v[146:149], v158 offset:1024
	ds_read_b128 v[154:157], v158 offset:2048
	ds_read_b128 v[158:161], v158 offset:3072
	ds_read_b128 v[162:165], v186
	ds_read_b128 v[166:169], v186 offset:1024
	ds_read_b128 v[182:185], v186 offset:2048
	ds_read_b128 v[186:189], v186 offset:3072
	s_add_u32 s28, s28, 0x80000
	s_addc_u32 s29, s29, 0
	s_mov_b32 m0, s37
	v_lshl_add_u64 v[240:241], s[28:29], 0, v[134:135]
	ds_read_b128 v[190:193], v153 offset:32768
	ds_read_b128 v[194:197], v153 offset:33792
	ds_read_b128 v[198:201], v153 offset:34816
	ds_read_b128 v[202:205], v153 offset:35840
	ds_read_b128 v[206:209], v153 offset:36864
	ds_read_b128 v[210:213], v153 offset:37888
	ds_read_b128 v[214:217], v153 offset:38912
	ds_read_b128 v[218:221], v153 offset:39936
	global_load_lds_dwordx4 v[240:241], off
	v_lshl_add_u64 v[240:241], s[28:29], 0, v[132:133]
	s_mov_b32 m0, s38
	s_nop 0
	global_load_lds_dwordx4 v[240:241], off
	s_waitcnt vmcnt(8)
	s_waitcnt lgkmcnt(0)
	s_barrier
	s_setprio 1
	s_waitcnt lgkmcnt(0)
	v_mfma_f32_16x16x32_bf16 v[126:129], v[142:145], v[190:193], v[126:129]
	v_mfma_f32_16x16x32_bf16 v[118:121], v[154:157], v[190:193], v[118:121]
	v_mfma_f32_16x16x32_bf16 v[110:113], v[142:145], v[198:201], v[110:113]
	v_mfma_f32_16x16x32_bf16 v[102:105], v[154:157], v[198:201], v[102:105]
	v_mfma_f32_16x16x32_bf16 v[94:97], v[142:145], v[206:209], v[94:97]
	v_mfma_f32_16x16x32_bf16 v[86:89], v[154:157], v[206:209], v[86:89]
	v_mfma_f32_16x16x32_bf16 v[78:81], v[142:145], v[214:217], v[78:81]
	v_mfma_f32_16x16x32_bf16 v[70:73], v[154:157], v[214:217], v[70:73]
	v_mfma_f32_16x16x32_bf16 v[126:129], v[146:149], v[194:197], v[126:129]
	v_mfma_f32_16x16x32_bf16 v[118:121], v[158:161], v[194:197], v[118:121]
	v_mfma_f32_16x16x32_bf16 v[110:113], v[146:149], v[202:205], v[110:113]
	v_mfma_f32_16x16x32_bf16 v[102:105], v[158:161], v[202:205], v[102:105]
	v_mfma_f32_16x16x32_bf16 v[94:97], v[146:149], v[210:213], v[94:97]
	v_mfma_f32_16x16x32_bf16 v[86:89], v[158:161], v[210:213], v[86:89]
	v_mfma_f32_16x16x32_bf16 v[78:81], v[146:149], v[218:221], v[78:81]
	v_mfma_f32_16x16x32_bf16 v[70:73], v[158:161], v[218:221], v[70:73]
	s_setprio 0
	s_setprio 1
	v_mfma_f32_16x16x32_bf16 v[122:125], v[162:165], v[190:193], v[122:125]
	v_mfma_f32_16x16x32_bf16 v[114:117], v[182:185], v[190:193], v[114:117]
	v_mfma_f32_16x16x32_bf16 v[106:109], v[162:165], v[198:201], v[106:109]
	v_mfma_f32_16x16x32_bf16 v[98:101], v[182:185], v[198:201], v[98:101]
	v_mfma_f32_16x16x32_bf16 v[90:93], v[162:165], v[206:209], v[90:93]
	v_mfma_f32_16x16x32_bf16 v[82:85], v[182:185], v[206:209], v[82:85]
	v_mfma_f32_16x16x32_bf16 v[74:77], v[162:165], v[214:217], v[74:77]
	v_mfma_f32_16x16x32_bf16 v[66:69], v[182:185], v[214:217], v[66:69]
	v_mfma_f32_16x16x32_bf16 v[122:125], v[166:169], v[194:197], v[122:125]
	v_mfma_f32_16x16x32_bf16 v[114:117], v[186:189], v[194:197], v[114:117]
	v_mfma_f32_16x16x32_bf16 v[106:109], v[166:169], v[202:205], v[106:109]
	v_mfma_f32_16x16x32_bf16 v[98:101], v[186:189], v[202:205], v[98:101]
	v_mfma_f32_16x16x32_bf16 v[90:93], v[166:169], v[210:213], v[90:93]
	v_mfma_f32_16x16x32_bf16 v[82:85], v[186:189], v[210:213], v[82:85]
	v_mfma_f32_16x16x32_bf16 v[74:77], v[166:169], v[218:221], v[74:77]
	v_mfma_f32_16x16x32_bf16 v[66:69], v[186:189], v[218:221], v[66:69]
	s_setprio 0
	s_barrier
; #define PG8_STAGE(bufoff, gbase, voff) do { _Pragma("unroll") for (int _i = 0; _i < 2; ++_i) \
;         __builtin_amdgcn_global_load_lds((const unsigned*)((const char*)(gbase) + (voff)[_i]), (PG8_LAS unsigned*)(lds + (bufoff) + ldsw + _i * 8192), 16, 0, 0); } while (0)
; #define PG8_LDA(dst, b, h) do { _Pragma("unroll") for (int m = 0; m < 4; ++m) _Pragma("unroll") for (int k = 0; k < 2; ++k) dst[m][k] = *(const PG8_LAS bf16x8*)(lds + PG8_SA(b, h) + aoff + m * 2048 + k * 1024); } while (0)
; #define PG8_MMA(ai, bj, At, Bt) do { __builtin_amdgcn_s_setprio(1); _Pragma("unroll") for (int m = 0; m < 4; ++m) _Pragma("unroll") for (int n = 0; n < 2; ++n) _Pragma("unroll") for (int k = 0; k < 2; ++k) \
;         acc[ai][bj][m][n] = __builtin_amdgcn_mfma_f32_16x16x32_bf16(Bt[n][k], At[m][k], acc[ai][bj][m][n], 0, 0, 0); __builtin_amdgcn_s_setprio(0); } while (0)
; #define PG8_WAIT_V(n) asm volatile("s_waitcnt vmcnt(" #n ")" ::: "memory")
; #define PG8_WAIT_L(n) asm volatile("s_waitcnt lgkmcnt(" #n ")" ::: "memory")
; #define PG8_BAR __builtin_amdgcn_s_barrier()
; #define PG8_SCHED __builtin_amdgcn_sched_barrier(0)
; template <class Epi, class Sched, bool ALIGN_EPI = false, bool SP2 = false>
; __device__ __forceinline__ void gemm_phase(PG8_LAS unsigned char* lds, const Gemm g, const Sched& S, const Epi& E, int tid_in) {
;     ...
;             PG8_LDA(At, 1, 1); PG8_STAGE(PG8_SB(1, 0), b3, voffB); PG8_STAGE(PG8_SB(1, 1), b3 + hstep, voffB); PG8_STAGE(PG8_SA(1, 0), a3, voffA);
;             PG8_WAIT_V(8); PG8_WAIT_L(0); PG8_BAR; PG8_MMA(1, 0, At, B0); PG8_MMA(1, 1, At, B1); PG8_BAR; PG8_SCHED;
	s_add_i32 s28, s63, s34
	v_lshl_add_u64 v[222:223], v[222:223], 0, s[90:91]
	s_mov_b32 m0, s28
	ds_read_b128 v[190:193], v153 offset:49152
	ds_read_b128 v[194:197], v153 offset:50176
	ds_read_b128 v[198:201], v153 offset:51200
	ds_read_b128 v[202:205], v153 offset:52224
	ds_read_b128 v[206:209], v153 offset:53248
	ds_read_b128 v[210:213], v153 offset:54272
	ds_read_b128 v[214:217], v153 offset:55296
	ds_read_b128 v[218:221], v153 offset:56320
	global_load_lds_dwordx4 v[222:223], off
	s_add_i32 m0, s28, 0x2000
	s_add_u32 s26, s26, 0x80080
	v_lshl_add_u64 v[222:223], v[224:225], 0, s[90:91]
	s_addc_u32 s27, s27, 0
	s_add_i32 s28, s55, s34
	global_load_lds_dwordx4 v[222:223], off
	v_lshl_add_u64 v[222:223], s[26:27], 0, v[0:1]
	s_mov_b32 m0, s28
	s_nop 0
	global_load_lds_dwordx4 v[222:223], off
	v_lshl_add_u64 v[222:223], s[26:27], 0, v[130:131]
	s_add_i32 m0, s28, 0x2000
	s_nop 0
	global_load_lds_dwordx4 v[222:223], off
	v_lshl_add_u64 v[226:227], v[226:227], 0, s[90:91]
	v_lshl_add_u64 v[228:229], v[228:229], 0, s[90:91]
	s_add_i32 s23, s23, 2
	s_add_u32 s24, s24, 0x100
	s_addc_u32 s25, s25, 0
	s_add_u32 s15, s15, 0x100
	s_addc_u32 s17, s17, 0
	s_cmp_gt_u32 s23, 29
	s_waitcnt vmcnt(6)
	s_waitcnt lgkmcnt(0)
	s_barrier
	s_setprio 1
	s_waitcnt lgkmcnt(0)
	v_mfma_f32_16x16x32_bf16 v[62:65], v[142:145], v[190:193], v[62:65]
	v_mfma_f32_16x16x32_bf16 v[54:57], v[154:157], v[190:193], v[54:57]
	v_mfma_f32_16x16x32_bf16 v[46:49], v[142:145], v[198:201], v[46:49]
	v_mfma_f32_16x16x32_bf16 v[38:41], v[154:157], v[198:201], v[38:41]
	v_mfma_f32_16x16x32_bf16 v[30:33], v[142:145], v[206:209], v[30:33]
	v_mfma_f32_16x16x32_bf16 v[22:25], v[154:157], v[206:209], v[22:25]
	v_mfma_f32_16x16x32_bf16 v[14:17], v[142:145], v[214:217], v[14:17]
	v_mfma_f32_16x16x32_bf16 v[6:9], v[154:157], v[214:217], v[6:9]
	v_mfma_f32_16x16x32_bf16 v[62:65], v[146:149], v[194:197], v[62:65]
	v_mfma_f32_16x16x32_bf16 v[54:57], v[158:161], v[194:197], v[54:57]
	v_mfma_f32_16x16x32_bf16 v[46:49], v[146:149], v[202:205], v[46:49]
	v_mfma_f32_16x16x32_bf16 v[38:41], v[158:161], v[202:205], v[38:41]
	v_mfma_f32_16x16x32_bf16 v[30:33], v[146:149], v[210:213], v[30:33]
	v_mfma_f32_16x16x32_bf16 v[22:25], v[158:161], v[210:213], v[22:25]
	v_mfma_f32_16x16x32_bf16 v[14:17], v[146:149], v[218:221], v[14:17]
	v_mfma_f32_16x16x32_bf16 v[6:9], v[158:161], v[218:221], v[6:9]
	s_setprio 0
	s_setprio 1
	v_mfma_f32_16x16x32_bf16 v[58:61], v[162:165], v[190:193], v[58:61]
	v_mfma_f32_16x16x32_bf16 v[50:53], v[182:185], v[190:193], v[50:53]
	v_mfma_f32_16x16x32_bf16 v[42:45], v[162:165], v[198:201], v[42:45]
	v_mfma_f32_16x16x32_bf16 v[34:37], v[182:185], v[198:201], v[34:37]
	v_mfma_f32_16x16x32_bf16 v[26:29], v[162:165], v[206:209], v[26:29]
	v_mfma_f32_16x16x32_bf16 v[18:21], v[182:185], v[206:209], v[18:21]
	v_mfma_f32_16x16x32_bf16 v[10:13], v[162:165], v[214:217], v[10:13]
	v_mfma_f32_16x16x32_bf16 v[2:5], v[182:185], v[214:217], v[2:5]
	v_mfma_f32_16x16x32_bf16 v[58:61], v[166:169], v[194:197], v[58:61]
	v_mfma_f32_16x16x32_bf16 v[50:53], v[186:189], v[194:197], v[50:53]
	v_mfma_f32_16x16x32_bf16 v[42:45], v[166:169], v[202:205], v[42:45]
	v_mfma_f32_16x16x32_bf16 v[34:37], v[186:189], v[202:205], v[34:37]
	v_mfma_f32_16x16x32_bf16 v[26:29], v[166:169], v[210:213], v[26:29]
	v_mfma_f32_16x16x32_bf16 v[18:21], v[186:189], v[210:213], v[18:21]
	v_mfma_f32_16x16x32_bf16 v[10:13], v[166:169], v[218:221], v[10:13]
	v_mfma_f32_16x16x32_bf16 v[2:5], v[186:189], v[218:221], v[2:5]
	s_setprio 0
	s_barrier
	s_cbranch_scc0 .Lbal_top_1507
	s_mov_b32 m0, s41
	s_nop 0
	global_load_lds_dwordx4 v[226:227], off
	s_mov_b32 m0, s42
	s_nop 0
	global_load_lds_dwordx4 v[228:229], off
	s_and_b64 vcc, exec, s[12:13]
	s_cbranch_vccz .LBB0_1510
	s_barrier

; #define PG8_STAGE(bufoff, gbase, voff) do { _Pragma("unroll") for (int _i = 0; _i < 2; ++_i) \
;         __builtin_amdgcn_global_load_lds((const unsigned*)((const char*)(gbase) + (voff)[_i]), (PG8_LAS unsigned*)(lds + (bufoff) + ldsw + _i * 8192), 16, 0, 0); } while (0)
; #define PG8_LDA(dst, b, h) do { _Pragma("unroll") for (int m = 0; m < 4; ++m) _Pragma("unroll") for (int k = 0; k < 2; ++k) dst[m][k] = *(const PG8_LAS bf16x8*)(lds + PG8_SA(b, h) + aoff + m * 2048 + k * 1024); } while (0)
; #define PG8_LDB(dst, b, h) do { _Pragma("unroll") for (int n = 0; n < 2; ++n) _Pragma("unroll") for (int k = 0; k < 2; ++k) dst[n][k] = *(const PG8_LAS bf16x8*)(lds + PG8_SB(b, h) + boff + n * 2048 + k * 1024); } while (0)
; #define PG8_MMA(ai, bj, At, Bt) do { __builtin_amdgcn_s_setprio(1); _Pragma("unroll") for (int m = 0; m < 4; ++m) _Pragma("unroll") for (int n = 0; n < 2; ++n) _Pragma("unroll") for (int k = 0; k < 2; ++k) \
;         acc[ai][bj][m][n] = __builtin_amdgcn_mfma_f32_16x16x32_bf16(Bt[n][k], At[m][k], acc[ai][bj][m][n], 0, 0, 0); __builtin_amdgcn_s_setprio(0); } while (0)
; #define PG8_WAIT_V(n) asm volatile("s_waitcnt vmcnt(" #n ")" ::: "memory")
; #define PG8_BAR __builtin_amdgcn_s_barrier()
; template <class Epi, class Sched, bool ALIGN_EPI = false, bool SP2 = false>
; __device__ __forceinline__ void gemm_phase(PG8_LAS unsigned char* lds, const Gemm g, const Sched& S, const Epi& E, int tid_in) {
;     ...
;         for (int t = 0; t < nt; t += 2) {
;             const bool last = (t == nt - 2);
;             const char* a1 = cA + (size_t)(t + 1) * kstep;
;             const char* a2 = last ? nA : cA + (size_t)(t + 2) * kstep; const char* b2 = last ? nB : cB + (size_t)(t + 2) * kstep;
;             const char* a3 = a2 + kstep; const char* b3 = b2 + kstep;
;             if (last && has_next) S.a_ready(nxt);
;             if constexpr (SP2) {
;             PG8_LDB(B0, 0, 0); PG8_LDB(B1, 0, 1); PG8_SCHED; PG8_LDA(At, 0, 0); PG8_STAGE(PG8_SA(1, 1), a1 + hstepA, voffA);
;             PG8_WAIT_V(8); PG8_WAIT_L(0); PG8_BAR; PG8_MMA(0, 0, At, B0); PG8_MMA(0, 1, At, B1); PG8_BAR; PG8_SCHED;
;             PG8_LDA(At, 0, 1); PG8_STAGE(PG8_SB(0, 0), b2, voffB); PG8_STAGE(PG8_SB(0, 1), b2 + hstep, voffB); PG8_STAGE(PG8_SA(0, 0), a2, voffA);
;             PG8_WAIT_V(8); PG8_WAIT_L(0); PG8_BAR; PG8_MMA(1, 0, At, B0); PG8_MMA(1, 1, At, B1); PG8_BAR; PG8_SCHED;
.LBB0_1576:
	s_and_b64 s[10:11], s[34:35], exec
	s_cselect_b32 s46, s27, s7
	s_cselect_b32 s47, s26, s6
	s_cselect_b32 s76, s29, s9
	s_cselect_b32 s82, s28, s8
	s_add_i32 s83, s79, -2
	s_add_u32 s84, s8, 0x100
	s_addc_u32 s85, s9, 0
	s_mov_b32 s10, 0
	s_branch .LBB0_1577
.Lbal_top_1577:
	s_mov_b32 m0, s49
	s_nop 0
	global_load_lds_dwordx4 v[222:223], off
	s_mov_b32 m0, s66
	s_nop 0
	global_load_lds_dwordx4 v[224:225], off
.LBB0_1577:
	v_add_u32_e32 v0, s4, v164
	ds_read_b128 v[130:133], v0
	ds_read_b128 v[142:145], v0 offset:1024
	ds_read_b128 v[146:149], v0 offset:2048
	ds_read_b128 v[150:153], v0 offset:3072
	v_add_u32_e32 v0, s5, v164
	ds_read_b128 v[154:157], v0
	ds_read_b128 v[158:161], v0 offset:1024
	ds_read_b128 v[166:169], v0 offset:2048
	ds_read_b128 v[182:185], v0 offset:3072
	s_add_i32 vcc_lo, s10, 2
	s_add_u32 s8, s6, 0x100
	s_addc_u32 s9, s7, 0
	s_cmp_eq_u32 s83, s10
	s_cselect_b32 s10, s82, s84
	s_cselect_b32 s37, s46, s9
	s_cselect_b32 s36, s47, s8
	s_cselect_b32 s11, s76, s85
	v_lshl_add_u64 v[218:219], s[6:7], 0, v[138:139]
	s_add_i32 m0, s38, 0xc000
	ds_read_b128 v[186:189], v165
	ds_read_b128 v[190:193], v165 offset:1024
	ds_read_b128 v[194:197], v165 offset:2048
	ds_read_b128 v[198:201], v165 offset:3072
	ds_read_b128 v[202:205], v165 offset:4096
	ds_read_b128 v[206:209], v165 offset:5120
	ds_read_b128 v[210:213], v165 offset:6144
	ds_read_b128 v[214:217], v165 offset:7168
	global_load_lds_dwordx4 v[218:219], off
	v_lshl_add_u64 v[218:219], s[6:7], 0, v[140:141]
	s_add_i32 m0, s38, 0xe000
	s_nop 0
	global_load_lds_dwordx4 v[218:219], off
	s_waitcnt vmcnt(8)
	s_waitcnt lgkmcnt(0)
	s_barrier
	s_setprio 1
	s_waitcnt lgkmcnt(0)
	v_mfma_f32_16x16x32_bf16 v[126:129], v[130:133], v[186:189], v[126:129]
	v_mfma_f32_16x16x32_bf16 v[122:125], v[146:149], v[186:189], v[122:125]
	v_mfma_f32_16x16x32_bf16 v[118:121], v[130:133], v[194:197], v[118:121]
	v_mfma_f32_16x16x32_bf16 v[114:117], v[146:149], v[194:197], v[114:117]
	v_mfma_f32_16x16x32_bf16 v[110:113], v[130:133], v[202:205], v[110:113]
	v_mfma_f32_16x16x32_bf16 v[106:109], v[146:149], v[202:205], v[106:109]
	v_mfma_f32_16x16x32_bf16 v[102:105], v[130:133], v[210:213], v[102:105]
	v_mfma_f32_16x16x32_bf16 v[98:101], v[146:149], v[210:213], v[98:101]
	v_mfma_f32_16x16x32_bf16 v[126:129], v[142:145], v[190:193], v[126:129]
	v_mfma_f32_16x16x32_bf16 v[122:125], v[150:153], v[190:193], v[122:125]
	v_mfma_f32_16x16x32_bf16 v[118:121], v[142:145], v[198:201], v[118:121]
	v_mfma_f32_16x16x32_bf16 v[114:117], v[150:153], v[198:201], v[114:117]
	v_mfma_f32_16x16x32_bf16 v[110:113], v[142:145], v[206:209], v[110:113]
	v_mfma_f32_16x16x32_bf16 v[106:109], v[150:153], v[206:209], v[106:109]
	v_mfma_f32_16x16x32_bf16 v[102:105], v[142:145], v[214:217], v[102:105]
	v_mfma_f32_16x16x32_bf16 v[98:101], v[150:153], v[214:217], v[98:101]
	s_setprio 0
	s_setprio 1
	v_mfma_f32_16x16x32_bf16 v[94:97], v[154:157], v[186:189], v[94:97]
	v_mfma_f32_16x16x32_bf16 v[90:93], v[166:169], v[186:189], v[90:93]
	v_mfma_f32_16x16x32_bf16 v[86:89], v[154:157], v[194:197], v[86:89]
	v_mfma_f32_16x16x32_bf16 v[82:85], v[166:169], v[194:197], v[82:85]
	v_mfma_f32_16x16x32_bf16 v[78:81], v[154:157], v[202:205], v[78:81]
	v_mfma_f32_16x16x32_bf16 v[74:77], v[166:169], v[202:205], v[74:77]
	v_mfma_f32_16x16x32_bf16 v[70:73], v[154:157], v[210:213], v[70:73]
	v_mfma_f32_16x16x32_bf16 v[66:69], v[166:169], v[210:213], v[66:69]
	v_mfma_f32_16x16x32_bf16 v[94:97], v[158:161], v[190:193], v[94:97]
	v_mfma_f32_16x16x32_bf16 v[90:93], v[182:185], v[190:193], v[90:93]
	v_mfma_f32_16x16x32_bf16 v[86:89], v[158:161], v[198:201], v[86:89]
	v_mfma_f32_16x16x32_bf16 v[82:85], v[182:185], v[198:201], v[82:85]
	v_mfma_f32_16x16x32_bf16 v[78:81], v[158:161], v[206:209], v[78:81]
	v_mfma_f32_16x16x32_bf16 v[74:77], v[182:185], v[206:209], v[74:77]
	v_mfma_f32_16x16x32_bf16 v[70:73], v[158:161], v[214:217], v[70:73]
	v_mfma_f32_16x16x32_bf16 v[66:69], v[182:185], v[214:217], v[66:69]
	s_setprio 0
	s_barrier
	s_add_i32 s6, s4, s33
	v_lshl_add_u64 v[218:219], s[10:11], 0, v[134:135]
	s_mov_b32 m0, s6
	ds_read_b128 v[186:189], v165 offset:16384
	ds_read_b128 v[190:193], v165 offset:17408
	ds_read_b128 v[194:197], v165 offset:18432
	ds_read_b128 v[198:201], v165 offset:19456
	ds_read_b128 v[202:205], v165 offset:20480
	ds_read_b128 v[206:209], v165 offset:21504
	ds_read_b128 v[210:213], v165 offset:22528
	ds_read_b128 v[214:217], v165 offset:23552
	global_load_lds_dwordx4 v[218:219], off
	s_add_i32 m0, s6, 0x2000
	s_add_u32 s6, s10, 0x160000
	v_lshl_add_u64 v[220:221], s[10:11], 0, v[136:137]
	s_addc_u32 s7, s11, 0
	s_add_i32 s64, s5, s33
	global_load_lds_dwordx4 v[220:221], off
	v_lshl_add_u64 v[222:223], s[6:7], 0, v[134:135]
	s_mov_b32 m0, s64
	v_lshl_add_u64 v[224:225], s[36:37], 0, v[136:137]
	global_load_lds_dwordx4 v[222:223], off
	v_lshl_add_u64 v[222:223], s[6:7], 0, v[136:137]
	s_add_i32 m0, s64, 0x2000
	s_nop 0
	global_load_lds_dwordx4 v[222:223], off
	s_waitcnt vmcnt(6)
	s_waitcnt lgkmcnt(0)
	s_barrier
; #define PG8_STAGE(bufoff, gbase, voff) do { _Pragma("unroll") for (int _i = 0; _i < 2; ++_i) \
;         __builtin_amdgcn_global_load_lds((const unsigned*)((const char*)(gbase) + (voff)[_i]), (PG8_LAS unsigned*)(lds + (bufoff) + ldsw + _i * 8192), 16, 0, 0); } while (0)
; #define PG8_LDA(dst, b, h) do { _Pragma("unroll") for (int m = 0; m < 4; ++m) _Pragma("unroll") for (int k = 0; k < 2; ++k) dst[m][k] = *(const PG8_LAS bf16x8*)(lds + PG8_SA(b, h) + aoff + m * 2048 + k * 1024); } while (0)
; #define PG8_LDB(dst, b, h) do { _Pragma("unroll") for (int n = 0; n < 2; ++n) _Pragma("unroll") for (int k = 0; k < 2; ++k) dst[n][k] = *(const PG8_LAS bf16x8*)(lds + PG8_SB(b, h) + boff + n * 2048 + k * 1024); } while (0)
; #define PG8_MMA(ai, bj, At, Bt) do { __builtin_amdgcn_s_setprio(1); _Pragma("unroll") for (int m = 0; m < 4; ++m) _Pragma("unroll") for (int n = 0; n < 2; ++n) _Pragma("unroll") for (int k = 0; k < 2; ++k) \
;         acc[ai][bj][m][n] = __builtin_amdgcn_mfma_f32_16x16x32_bf16(Bt[n][k], At[m][k], acc[ai][bj][m][n], 0, 0, 0); __builtin_amdgcn_s_setprio(0); } while (0)
; #define PG8_WAIT_V(n) asm volatile("s_waitcnt vmcnt(" #n ")" ::: "memory")
; #define PG8_WAIT_L(n) asm volatile("s_waitcnt lgkmcnt(" #n ")" ::: "memory")
; #define PG8_BAR __builtin_amdgcn_s_barrier()
; #define PG8_SCHED __builtin_amdgcn_sched_barrier(0)
; template <class Epi, class Sched, bool ALIGN_EPI = false, bool SP2 = false>
; __device__ __forceinline__ void gemm_phase(PG8_LAS unsigned char* lds, const Gemm g, const Sched& S, const Epi& E, int tid_in) {
;     ...
;             PG8_WAIT_V(8); PG8_WAIT_L(0); PG8_BAR; PG8_MMA(1, 0, At, B0); PG8_MMA(1, 1, At, B1); PG8_BAR; PG8_SCHED;
;             PG8_LDB(B0, 1, 0); PG8_LDB(B1, 1, 1); PG8_SCHED; PG8_LDA(At, 1, 0); PG8_STAGE(PG8_SA(0, 1), a2 + hstepA, voffA);
;             PG8_WAIT_V(8); PG8_WAIT_L(0); PG8_BAR; PG8_MMA(0, 0, At, B0); PG8_MMA(0, 1, At, B1); PG8_BAR; PG8_SCHED;
	s_setprio 1
	s_waitcnt lgkmcnt(0)
	v_mfma_f32_16x16x32_bf16 v[62:65], v[130:133], v[186:189], v[62:65]
	v_mfma_f32_16x16x32_bf16 v[58:61], v[146:149], v[186:189], v[58:61]
	v_mfma_f32_16x16x32_bf16 v[54:57], v[130:133], v[194:197], v[54:57]
	v_mfma_f32_16x16x32_bf16 v[50:53], v[146:149], v[194:197], v[50:53]
	v_mfma_f32_16x16x32_bf16 v[46:49], v[130:133], v[202:205], v[46:49]
	v_mfma_f32_16x16x32_bf16 v[42:45], v[146:149], v[202:205], v[42:45]
	v_mfma_f32_16x16x32_bf16 v[38:41], v[130:133], v[210:213], v[38:41]
	v_mfma_f32_16x16x32_bf16 v[34:37], v[146:149], v[210:213], v[34:37]
	v_mfma_f32_16x16x32_bf16 v[62:65], v[142:145], v[190:193], v[62:65]
	v_mfma_f32_16x16x32_bf16 v[58:61], v[150:153], v[190:193], v[58:61]
	v_mfma_f32_16x16x32_bf16 v[54:57], v[142:145], v[198:201], v[54:57]
	v_mfma_f32_16x16x32_bf16 v[50:53], v[150:153], v[198:201], v[50:53]
	v_mfma_f32_16x16x32_bf16 v[46:49], v[142:145], v[206:209], v[46:49]
	v_mfma_f32_16x16x32_bf16 v[42:45], v[150:153], v[206:209], v[42:45]
	v_mfma_f32_16x16x32_bf16 v[38:41], v[142:145], v[214:217], v[38:41]
	v_mfma_f32_16x16x32_bf16 v[34:37], v[150:153], v[214:217], v[34:37]
	s_setprio 0
	s_setprio 1
	v_mfma_f32_16x16x32_bf16 v[30:33], v[154:157], v[186:189], v[30:33]
	v_mfma_f32_16x16x32_bf16 v[26:29], v[166:169], v[186:189], v[26:29]
	v_mfma_f32_16x16x32_bf16 v[22:25], v[154:157], v[194:197], v[22:25]
	v_mfma_f32_16x16x32_bf16 v[18:21], v[166:169], v[194:197], v[18:21]
	v_mfma_f32_16x16x32_bf16 v[14:17], v[154:157], v[202:205], v[14:17]
	v_mfma_f32_16x16x32_bf16 v[10:13], v[166:169], v[202:205], v[10:13]
	v_mfma_f32_16x16x32_bf16 v[6:9], v[154:157], v[210:213], v[6:9]
	v_mfma_f32_16x16x32_bf16 v[2:5], v[166:169], v[210:213], v[2:5]
	v_mfma_f32_16x16x32_bf16 v[30:33], v[158:161], v[190:193], v[30:33]
	v_mfma_f32_16x16x32_bf16 v[26:29], v[182:185], v[190:193], v[26:29]
	v_mfma_f32_16x16x32_bf16 v[22:25], v[158:161], v[198:201], v[22:25]
	v_mfma_f32_16x16x32_bf16 v[18:21], v[182:185], v[198:201], v[18:21]
	v_mfma_f32_16x16x32_bf16 v[14:17], v[158:161], v[206:209], v[14:17]
	v_mfma_f32_16x16x32_bf16 v[10:13], v[182:185], v[206:209], v[10:13]
	v_mfma_f32_16x16x32_bf16 v[6:9], v[158:161], v[214:217], v[6:9]
	v_mfma_f32_16x16x32_bf16 v[2:5], v[182:185], v[214:217], v[2:5]
	s_setprio 0
	s_barrier
	v_lshl_add_u64 v[222:223], s[36:37], 0, v[134:135]
	s_mov_b32 m0, s38
	s_nop 0
	global_load_lds_dwordx4 v[222:223], off
	s_mov_b32 m0, s39
	s_nop 0
	global_load_lds_dwordx4 v[224:225], off
	v_add_u32_e32 v0, s63, v164
	ds_read_b128 v[130:133], v0
	ds_read_b128 v[142:145], v0 offset:1024
	ds_read_b128 v[146:149], v0 offset:2048
	ds_read_b128 v[150:153], v0 offset:3072
	v_add_u32_e32 v0, s55, v164
	ds_read_b128 v[154:157], v0
	ds_read_b128 v[158:161], v0 offset:1024
	ds_read_b128 v[166:169], v0 offset:2048
	ds_read_b128 v[182:185], v0 offset:3072
	s_add_u32 s6, s36, 0x160000
	s_addc_u32 s7, s37, 0
	s_mov_b32 m0, s40
	v_lshl_add_u64 v[226:227], s[6:7], 0, v[134:135]
	ds_read_b128 v[186:189], v165 offset:32768
	ds_read_b128 v[190:193], v165 offset:33792
	ds_read_b128 v[194:197], v165 offset:34816
	ds_read_b128 v[198:201], v165 offset:35840
	ds_read_b128 v[202:205], v165 offset:36864
	ds_read_b128 v[206:209], v165 offset:37888
	ds_read_b128 v[210:213], v165 offset:38912
	ds_read_b128 v[214:217], v165 offset:39936
	global_load_lds_dwordx4 v[226:227], off
	v_lshl_add_u64 v[226:227], s[6:7], 0, v[136:137]
	s_mov_b32 m0, s41
	s_nop 0
	global_load_lds_dwordx4 v[226:227], off
	s_waitcnt vmcnt(8)
	s_waitcnt lgkmcnt(0)
	s_barrier
	s_setprio 1
	s_waitcnt lgkmcnt(0)
	v_mfma_f32_16x16x32_bf16 v[126:129], v[130:133], v[186:189], v[126:129]
	v_mfma_f32_16x16x32_bf16 v[122:125], v[146:149], v[186:189], v[122:125]
	v_mfma_f32_16x16x32_bf16 v[118:121], v[130:133], v[194:197], v[118:121]
	v_mfma_f32_16x16x32_bf16 v[114:117], v[146:149], v[194:197], v[114:117]
	v_mfma_f32_16x16x32_bf16 v[110:113], v[130:133], v[202:205], v[110:113]
	v_mfma_f32_16x16x32_bf16 v[106:109], v[146:149], v[202:205], v[106:109]
	v_mfma_f32_16x16x32_bf16 v[102:105], v[130:133], v[210:213], v[102:105]
	v_mfma_f32_16x16x32_bf16 v[98:101], v[146:149], v[210:213], v[98:101]
	v_mfma_f32_16x16x32_bf16 v[126:129], v[142:145], v[190:193], v[126:129]
	v_mfma_f32_16x16x32_bf16 v[122:125], v[150:153], v[190:193], v[122:125]
	v_mfma_f32_16x16x32_bf16 v[118:121], v[142:145], v[198:201], v[118:121]
	v_mfma_f32_16x16x32_bf16 v[114:117], v[150:153], v[198:201], v[114:117]
	v_mfma_f32_16x16x32_bf16 v[110:113], v[142:145], v[206:209], v[110:113]
	v_mfma_f32_16x16x32_bf16 v[106:109], v[150:153], v[206:209], v[106:109]
	v_mfma_f32_16x16x32_bf16 v[102:105], v[142:145], v[214:217], v[102:105]
	v_mfma_f32_16x16x32_bf16 v[98:101], v[150:153], v[214:217], v[98:101]
	s_setprio 0
	s_setprio 1
	v_mfma_f32_16x16x32_bf16 v[94:97], v[154:157], v[186:189], v[94:97]
	v_mfma_f32_16x16x32_bf16 v[90:93], v[166:169], v[186:189], v[90:93]
	v_mfma_f32_16x16x32_bf16 v[86:89], v[154:157], v[194:197], v[86:89]
	v_mfma_f32_16x16x32_bf16 v[82:85], v[166:169], v[194:197], v[82:85]
	v_mfma_f32_16x16x32_bf16 v[78:81], v[154:157], v[202:205], v[78:81]
	v_mfma_f32_16x16x32_bf16 v[74:77], v[166:169], v[202:205], v[74:77]
	v_mfma_f32_16x16x32_bf16 v[70:73], v[154:157], v[210:213], v[70:73]
	v_mfma_f32_16x16x32_bf16 v[66:69], v[166:169], v[210:213], v[66:69]
	v_mfma_f32_16x16x32_bf16 v[94:97], v[158:161], v[190:193], v[94:97]
	v_mfma_f32_16x16x32_bf16 v[90:93], v[182:185], v[190:193], v[90:93]
	v_mfma_f32_16x16x32_bf16 v[86:89], v[158:161], v[198:201], v[86:89]
	v_mfma_f32_16x16x32_bf16 v[82:85], v[182:185], v[198:201], v[82:85]
	v_mfma_f32_16x16x32_bf16 v[78:81], v[158:161], v[206:209], v[78:81]
	v_mfma_f32_16x16x32_bf16 v[74:77], v[182:185], v[206:209], v[74:77]
	v_mfma_f32_16x16x32_bf16 v[70:73], v[158:161], v[214:217], v[70:73]
	v_mfma_f32_16x16x32_bf16 v[66:69], v[182:185], v[214:217], v[66:69]
	s_setprio 0
	s_barrier
; #define PG8_STAGE(bufoff, gbase, voff) do { _Pragma("unroll") for (int _i = 0; _i < 2; ++_i) \
;         __builtin_amdgcn_global_load_lds((const unsigned*)((const char*)(gbase) + (voff)[_i]), (PG8_LAS unsigned*)(lds + (bufoff) + ldsw + _i * 8192), 16, 0, 0); } while (0)
; #define PG8_LDA(dst, b, h) do { _Pragma("unroll") for (int m = 0; m < 4; ++m) _Pragma("unroll") for (int k = 0; k < 2; ++k) dst[m][k] = *(const PG8_LAS bf16x8*)(lds + PG8_SA(b, h) + aoff + m * 2048 + k * 1024); } while (0)
; #define PG8_MMA(ai, bj, At, Bt) do { __builtin_amdgcn_s_setprio(1); _Pragma("unroll") for (int m = 0; m < 4; ++m) _Pragma("unroll") for (int n = 0; n < 2; ++n) _Pragma("unroll") for (int k = 0; k < 2; ++k) \
;         acc[ai][bj][m][n] = __builtin_amdgcn_mfma_f32_16x16x32_bf16(Bt[n][k], At[m][k], acc[ai][bj][m][n], 0, 0, 0); __builtin_amdgcn_s_setprio(0); } while (0)
; #define PG8_WAIT_V(n) asm volatile("s_waitcnt vmcnt(" #n ")" ::: "memory")
; #define PG8_WAIT_L(n) asm volatile("s_waitcnt lgkmcnt(" #n ")" ::: "memory")
; #define PG8_BAR __builtin_amdgcn_s_barrier()
; #define PG8_SCHED __builtin_amdgcn_sched_barrier(0)
; template <class Epi, class Sched, bool ALIGN_EPI = false, bool SP2 = false>
; __device__ __forceinline__ void gemm_phase(PG8_LAS unsigned char* lds, const Gemm g, const Sched& S, const Epi& E, int tid_in) {
;     ...
;             PG8_LDA(At, 1, 1); PG8_STAGE(PG8_SB(1, 0), b3, voffB); PG8_STAGE(PG8_SB(1, 1), b3 + hstep, voffB); PG8_STAGE(PG8_SA(1, 0), a3, voffA);
;             PG8_WAIT_V(8); PG8_WAIT_L(0); PG8_BAR; PG8_MMA(1, 0, At, B0); PG8_MMA(1, 1, At, B1); PG8_BAR; PG8_SCHED;
	s_add_i32 s6, s63, s33
	v_lshl_add_u64 v[218:219], v[218:219], 0, s[90:91]
	s_mov_b32 m0, s6
	ds_read_b128 v[186:189], v165 offset:49152
	ds_read_b128 v[190:193], v165 offset:50176
	ds_read_b128 v[194:197], v165 offset:51200
	ds_read_b128 v[198:201], v165 offset:52224
	ds_read_b128 v[202:205], v165 offset:53248
	ds_read_b128 v[206:209], v165 offset:54272
	ds_read_b128 v[210:213], v165 offset:55296
	ds_read_b128 v[214:217], v165 offset:56320
	global_load_lds_dwordx4 v[218:219], off
	s_add_i32 m0, s6, 0x2000
	s_add_u32 s6, s10, 0x160080
	v_lshl_add_u64 v[218:219], v[220:221], 0, s[90:91]
	s_addc_u32 s7, s11, 0
	s_add_i32 s10, s55, s33
	global_load_lds_dwordx4 v[218:219], off
	v_lshl_add_u64 v[218:219], s[6:7], 0, v[134:135]
	s_mov_b32 m0, s10
	s_nop 0
	global_load_lds_dwordx4 v[218:219], off
	v_lshl_add_u64 v[218:219], s[6:7], 0, v[136:137]
	s_add_i32 m0, s10, 0x2000
	s_nop 0
	global_load_lds_dwordx4 v[218:219], off
	v_lshl_add_u64 v[222:223], v[222:223], 0, s[90:91]
	v_lshl_add_u64 v[224:225], v[224:225], 0, s[90:91]
	s_add_u32 s84, s84, 0x100
	s_addc_u32 s85, s85, 0
	s_cmp_ge_u32 vcc_lo, s79
	s_mov_b64 s[6:7], s[8:9]
	s_mov_b32 s10, vcc_lo
	s_waitcnt vmcnt(6)
	s_waitcnt lgkmcnt(0)
	s_barrier
	s_setprio 1
	s_waitcnt lgkmcnt(0)
	v_mfma_f32_16x16x32_bf16 v[62:65], v[130:133], v[186:189], v[62:65]
	v_mfma_f32_16x16x32_bf16 v[58:61], v[146:149], v[186:189], v[58:61]
	v_mfma_f32_16x16x32_bf16 v[54:57], v[130:133], v[194:197], v[54:57]
	v_mfma_f32_16x16x32_bf16 v[50:53], v[146:149], v[194:197], v[50:53]
	v_mfma_f32_16x16x32_bf16 v[46:49], v[130:133], v[202:205], v[46:49]
	v_mfma_f32_16x16x32_bf16 v[42:45], v[146:149], v[202:205], v[42:45]
	v_mfma_f32_16x16x32_bf16 v[38:41], v[130:133], v[210:213], v[38:41]
	v_mfma_f32_16x16x32_bf16 v[34:37], v[146:149], v[210:213], v[34:37]
	v_mfma_f32_16x16x32_bf16 v[62:65], v[142:145], v[190:193], v[62:65]
	v_mfma_f32_16x16x32_bf16 v[58:61], v[150:153], v[190:193], v[58:61]
	v_mfma_f32_16x16x32_bf16 v[54:57], v[142:145], v[198:201], v[54:57]
	v_mfma_f32_16x16x32_bf16 v[50:53], v[150:153], v[198:201], v[50:53]
	v_mfma_f32_16x16x32_bf16 v[46:49], v[142:145], v[206:209], v[46:49]
	v_mfma_f32_16x16x32_bf16 v[42:45], v[150:153], v[206:209], v[42:45]
	v_mfma_f32_16x16x32_bf16 v[38:41], v[142:145], v[214:217], v[38:41]
	v_mfma_f32_16x16x32_bf16 v[34:37], v[150:153], v[214:217], v[34:37]
	s_setprio 0
	s_setprio 1
	v_mfma_f32_16x16x32_bf16 v[30:33], v[154:157], v[186:189], v[30:33]
	v_mfma_f32_16x16x32_bf16 v[26:29], v[166:169], v[186:189], v[26:29]
	v_mfma_f32_16x16x32_bf16 v[22:25], v[154:157], v[194:197], v[22:25]
	v_mfma_f32_16x16x32_bf16 v[18:21], v[166:169], v[194:197], v[18:21]
	v_mfma_f32_16x16x32_bf16 v[14:17], v[154:157], v[202:205], v[14:17]
	v_mfma_f32_16x16x32_bf16 v[10:13], v[166:169], v[202:205], v[10:13]
	v_mfma_f32_16x16x32_bf16 v[6:9], v[154:157], v[210:213], v[6:9]
	v_mfma_f32_16x16x32_bf16 v[2:5], v[166:169], v[210:213], v[2:5]
	v_mfma_f32_16x16x32_bf16 v[30:33], v[158:161], v[190:193], v[30:33]
	v_mfma_f32_16x16x32_bf16 v[26:29], v[182:185], v[190:193], v[26:29]
	v_mfma_f32_16x16x32_bf16 v[22:25], v[158:161], v[198:201], v[22:25]
	v_mfma_f32_16x16x32_bf16 v[18:21], v[182:185], v[198:201], v[18:21]
	v_mfma_f32_16x16x32_bf16 v[14:17], v[158:161], v[206:209], v[14:17]
	v_mfma_f32_16x16x32_bf16 v[10:13], v[182:185], v[206:209], v[10:13]
	v_mfma_f32_16x16x32_bf16 v[6:9], v[158:161], v[214:217], v[6:9]
	v_mfma_f32_16x16x32_bf16 v[2:5], v[182:185], v[214:217], v[2:5]
	s_setprio 0
	s_barrier
	s_cbranch_scc0 .Lbal_top_1577
	s_mov_b32 m0, s49
	s_nop 0
	global_load_lds_dwordx4 v[222:223], off
	s_mov_b32 m0, s66
	s_nop 0
	global_load_lds_dwordx4 v[224:225], off
	s_and_b64 vcc, exec, s[24:25]
	s_cbranch_vccz .LBB0_1580
	s_barrier
